# GEMM K-loops: first trip peeled, its first-touch MFMAs take C=0, so the per-unit accumulator clearing is gone
# baseline (speedup 1.0000x reference)
; #define PG8_STAGE(bufoff, gbase, voff) do { _Pragma("unroll") for (int _i = 0; _i < 2; ++_i) \
;         __builtin_amdgcn_global_load_lds((const unsigned*)((const char*)(gbase) + (voff)[_i]), (PG8_LAS unsigned*)(lds + (bufoff) + ldsw + _i * 8192), 16, 0, 0); } while (0)
; #define PG8_LDA(dst, b, h) do { _Pragma("unroll") for (int m = 0; m < 4; ++m) _Pragma("unroll") for (int k = 0; k < 2; ++k) dst[m][k] = *(const PG8_LAS bf16x8*)(lds + PG8_SA(b, h) + aoff + m * 2048 + k * 1024); } while (0)
; #define PG8_LDB(dst, b, h) do { _Pragma("unroll") for (int n = 0; n < 2; ++n) _Pragma("unroll") for (int k = 0; k < 2; ++k) dst[n][k] = *(const PG8_LAS bf16x8*)(lds + PG8_SB(b, h) + boff + n * 2048 + k * 1024); } while (0)
; #define PG8_MMA(ai, bj, At, Bt) do { __builtin_amdgcn_s_setprio(1); _Pragma("unroll") for (int m = 0; m < 4; ++m) _Pragma("unroll") for (int n = 0; n < 2; ++n) _Pragma("unroll") for (int k = 0; k < 2; ++k) \
;         acc[ai][bj][m][n] = __builtin_amdgcn_mfma_f32_16x16x32_bf16(Bt[n][k], At[m][k], acc[ai][bj][m][n], 0, 0, 0); __builtin_amdgcn_s_setprio(0); } while (0)
; #define PG8_WAIT_V(n) asm volatile("s_waitcnt vmcnt(" #n ")" ::: "memory")
; #define PG8_WAIT_L(n) asm volatile("s_waitcnt lgkmcnt(" #n ")" ::: "memory")
; template <class Epi, class Sched, bool ALIGN_EPI = false, bool SP2 = false>
; __device__ __forceinline__ void gemm_phase(PG8_LAS unsigned char* lds, const Gemm g, const Sched& S, const Epi& E) {
;     ...
;             const bool last = (t == nt - 2);
;             const char* a1 = cA + (size_t)(t + 1) * kstep;
;             const char* a2 = last ? nA : cA + (size_t)(t + 2) * kstep; const char* b2 = last ? nB : cB + (size_t)(t + 2) * kstep;
;             const char* a3 = a2 + kstep; const char* b3 = b2 + kstep;
;             if (last && has_next) S.a_ready(nxt);
;             if constexpr (SP2) {
;             PG8_LDB(B0, 0, 0); PG8_LDB(B1, 0, 1); PG8_SCHED; PG8_LDA(At, 0, 0); PG8_STAGE(PG8_SA(1, 1), a1 + hstepA, voffA);
;             PG8_WAIT_V(8); PG8_WAIT_L(0); PG8_BAR; PG8_MMA(0, 0, At, B0); PG8_MMA(0, 1, At, B1); PG8_BAR; PG8_SCHED;
;             PG8_LDA(At, 0, 1); PG8_STAGE(PG8_SB(0, 0), b2, voffB); PG8_STAGE(PG8_SB(0, 1), b2 + hstepB, voffB); PG8_STAGE(PG8_SA(0, 0), a2, voffA);
;             PG8_WAIT_V(8); PG8_WAIT_L(0); PG8_BAR; PG8_MMA(1, 0, At, B0); PG8_MMA(1, 1, At, B1); PG8_BAR; PG8_SCHED;
.LBB0_196:
	s_ashr_i32 s41, s40, 31
	s_lshl_b64 s[6:7], s[40:41], 19
	s_add_u32 s42, s31, s6
	s_addc_u32 s43, s52, s7
	s_and_b64 s[6:7], s[4:5], exec
	s_cselect_b32 s11, s43, s49
	s_cselect_b32 s13, s42, s48
	s_ashr_i32 s37, s36, 31
	s_lshl_b64 s[6:7], s[36:37], 19
	s_add_u32 s44, s53, s6
	s_addc_u32 s45, s54, s7
	s_and_b64 s[6:7], s[4:5], exec
	s_cselect_b32 s33, s45, s47
	s_cselect_b32 s37, s44, s46
	s_add_u32 s6, s48, 0x40080
	s_addc_u32 s7, s49, 0
	s_add_u32 s38, s46, 0x100
	s_addc_u32 s39, s47, 0
	s_mov_b32 s41, -2
	s_waitcnt vmcnt(0)
	ds_read_b128 v[130:133], v180
	ds_read_b128 v[134:137], v180 offset:1024
	ds_read_b128 v[138:141], v180 offset:2048
	ds_read_b128 v[142:145], v180 offset:3072
	ds_read_b128 v[168:171], v181
	ds_read_b128 v[188:191], v181 offset:1024
	ds_read_b128 v[192:195], v181 offset:2048
	ds_read_b128 v[196:199], v181 offset:3072
	s_add_u32 s8, s6, 0xfffc0080
	s_addc_u32 s9, s7, -1
	s_cmp_eq_u32 s41, 12
	s_cselect_b32 s47, s11, s9
	s_cselect_b32 s46, s13, s8
	s_cselect_b32 s9, s33, s39
	s_cselect_b32 s8, s37, s38
	v_lshl_add_u64 v[172:173], s[6:7], 0, v[158:159]
	s_add_i32 m0, s59, 0xc000
	ds_read_b128 v[200:203], v182
	ds_read_b128 v[204:207], v182 offset:1024
	ds_read_b128 v[208:211], v182 offset:2048
	ds_read_b128 v[212:215], v182 offset:3072
	ds_read_b128 v[220:223], v182 offset:4096
	ds_read_b128 v[224:227], v182 offset:5120
	ds_read_b128 v[228:231], v182 offset:6144
	ds_read_b128 v[232:235], v182 offset:7168
	global_load_lds_dwordx4 v[172:173], off
	v_lshl_add_u64 v[172:173], s[6:7], 0, v[160:161]
	s_add_i32 m0, s59, 0xe000
	s_nop 0
	global_load_lds_dwordx4 v[172:173], off
	s_waitcnt vmcnt(8)
	s_waitcnt lgkmcnt(0)
	s_barrier
	s_setprio 1
	s_waitcnt lgkmcnt(0)
	v_mfma_f32_16x16x32_bf16 v[126:129], v[130:133], v[200:203], 0
	v_mfma_f32_16x16x32_bf16 v[122:125], v[138:141], v[200:203], 0
	v_mfma_f32_16x16x32_bf16 v[110:113], v[130:133], v[208:211], 0
	v_mfma_f32_16x16x32_bf16 v[106:109], v[138:141], v[208:211], 0
	v_mfma_f32_16x16x32_bf16 v[94:97], v[130:133], v[220:223], 0
	v_mfma_f32_16x16x32_bf16 v[90:93], v[138:141], v[220:223], 0
	v_mfma_f32_16x16x32_bf16 v[78:81], v[130:133], v[228:231], 0
	v_mfma_f32_16x16x32_bf16 v[74:77], v[138:141], v[228:231], 0
	v_mfma_f32_16x16x32_bf16 v[126:129], v[134:137], v[204:207], v[126:129]
	v_mfma_f32_16x16x32_bf16 v[122:125], v[142:145], v[204:207], v[122:125]
	v_mfma_f32_16x16x32_bf16 v[110:113], v[134:137], v[212:215], v[110:113]
	v_mfma_f32_16x16x32_bf16 v[106:109], v[142:145], v[212:215], v[106:109]
	v_mfma_f32_16x16x32_bf16 v[94:97], v[134:137], v[224:227], v[94:97]
	v_mfma_f32_16x16x32_bf16 v[90:93], v[142:145], v[224:227], v[90:93]
	v_mfma_f32_16x16x32_bf16 v[78:81], v[134:137], v[232:235], v[78:81]
	v_mfma_f32_16x16x32_bf16 v[74:77], v[142:145], v[232:235], v[74:77]
	s_setprio 0
	s_setprio 1
	v_mfma_f32_16x16x32_bf16 v[118:121], v[168:171], v[200:203], 0
	v_mfma_f32_16x16x32_bf16 v[114:117], v[192:195], v[200:203], 0
	v_mfma_f32_16x16x32_bf16 v[102:105], v[168:171], v[208:211], 0
	v_mfma_f32_16x16x32_bf16 v[98:101], v[192:195], v[208:211], 0
	v_mfma_f32_16x16x32_bf16 v[86:89], v[168:171], v[220:223], 0
	v_mfma_f32_16x16x32_bf16 v[82:85], v[192:195], v[220:223], 0
	v_mfma_f32_16x16x32_bf16 v[70:73], v[168:171], v[228:231], 0
	v_mfma_f32_16x16x32_bf16 v[66:69], v[192:195], v[228:231], 0
	v_mfma_f32_16x16x32_bf16 v[118:121], v[188:191], v[204:207], v[118:121]
	v_mfma_f32_16x16x32_bf16 v[114:117], v[196:199], v[204:207], v[114:117]
	v_mfma_f32_16x16x32_bf16 v[102:105], v[188:191], v[212:215], v[102:105]
	v_mfma_f32_16x16x32_bf16 v[98:101], v[196:199], v[212:215], v[98:101]
	v_mfma_f32_16x16x32_bf16 v[86:89], v[188:191], v[224:227], v[86:89]
	v_mfma_f32_16x16x32_bf16 v[82:85], v[196:199], v[224:227], v[82:85]
	v_mfma_f32_16x16x32_bf16 v[70:73], v[188:191], v[232:235], v[70:73]
	v_mfma_f32_16x16x32_bf16 v[66:69], v[196:199], v[232:235], v[66:69]
	s_setprio 0
	s_barrier
	s_add_i32 s48, s78, s55
	v_lshl_add_u64 v[172:173], s[8:9], 0, v[148:149]
	s_mov_b32 m0, s48
	ds_read_b128 v[200:203], v182 offset:16384
	ds_read_b128 v[204:207], v182 offset:17408
	ds_read_b128 v[208:211], v182 offset:18432
	ds_read_b128 v[212:215], v182 offset:19456
	ds_read_b128 v[220:223], v182 offset:20480
	ds_read_b128 v[224:227], v182 offset:21504
	ds_read_b128 v[228:231], v182 offset:22528
	ds_read_b128 v[232:235], v182 offset:23552
	global_load_lds_dwordx4 v[172:173], off
	s_add_i32 m0, s48, 0x2000
	s_add_u32 s48, s8, 0x40000
	v_lshl_add_u64 v[178:179], s[8:9], 0, v[152:153]
	s_addc_u32 s49, s9, 0
	s_add_i32 s50, s79, s55
	global_load_lds_dwordx4 v[178:179], off
	v_lshl_add_u64 v[216:217], s[48:49], 0, v[148:149]
	s_mov_b32 m0, s50
	v_lshl_add_u64 v[236:237], s[46:47], 0, v[150:151]
	global_load_lds_dwordx4 v[216:217], off
	v_lshl_add_u64 v[216:217], s[48:49], 0, v[152:153]
	s_add_i32 m0, s50, 0x2000
	s_nop 0
	global_load_lds_dwordx4 v[216:217], off
	v_lshl_add_u64 v[216:217], s[46:47], 0, v[146:147]
	s_mov_b32 m0, s59
	s_nop 0
	global_load_lds_dwordx4 v[216:217], off
	s_mov_b32 m0, s60
	s_nop 0
	global_load_lds_dwordx4 v[236:237], off
	s_waitcnt vmcnt(8)
	s_waitcnt lgkmcnt(0)
	s_barrier
; #define PG8_STAGE(bufoff, gbase, voff) do { _Pragma("unroll") for (int _i = 0; _i < 2; ++_i) \
;         __builtin_amdgcn_global_load_lds((const unsigned*)((const char*)(gbase) + (voff)[_i]), (PG8_LAS unsigned*)(lds + (bufoff) + ldsw + _i * 8192), 16, 0, 0); } while (0)
; #define PG8_LDA(dst, b, h) do { _Pragma("unroll") for (int m = 0; m < 4; ++m) _Pragma("unroll") for (int k = 0; k < 2; ++k) dst[m][k] = *(const PG8_LAS bf16x8*)(lds + PG8_SA(b, h) + aoff + m * 2048 + k * 1024); } while (0)
; #define PG8_LDB(dst, b, h) do { _Pragma("unroll") for (int n = 0; n < 2; ++n) _Pragma("unroll") for (int k = 0; k < 2; ++k) dst[n][k] = *(const PG8_LAS bf16x8*)(lds + PG8_SB(b, h) + boff + n * 2048 + k * 1024); } while (0)
; #define PG8_MMA(ai, bj, At, Bt) do { __builtin_amdgcn_s_setprio(1); _Pragma("unroll") for (int m = 0; m < 4; ++m) _Pragma("unroll") for (int n = 0; n < 2; ++n) _Pragma("unroll") for (int k = 0; k < 2; ++k) \
;         acc[ai][bj][m][n] = __builtin_amdgcn_mfma_f32_16x16x32_bf16(Bt[n][k], At[m][k], acc[ai][bj][m][n], 0, 0, 0); __builtin_amdgcn_s_setprio(0); } while (0)
; #define PG8_WAIT_V(n) asm volatile("s_waitcnt vmcnt(" #n ")" ::: "memory")
; #define PG8_WAIT_L(n) asm volatile("s_waitcnt lgkmcnt(" #n ")" ::: "memory")
; #define PG8_BAR __builtin_amdgcn_s_barrier()
; #define PG8_SCHED __builtin_amdgcn_sched_barrier(0)
; template <class Epi, class Sched, bool ALIGN_EPI = false, bool SP2 = false>
; __device__ __forceinline__ void gemm_phase(PG8_LAS unsigned char* lds, const Gemm g, const Sched& S, const Epi& E) {
;     ...
;             PG8_WAIT_V(8); PG8_WAIT_L(0); PG8_BAR; PG8_MMA(1, 0, At, B0); PG8_MMA(1, 1, At, B1); PG8_BAR; PG8_SCHED;
;             PG8_LDB(B0, 1, 0); PG8_LDB(B1, 1, 1); PG8_SCHED; PG8_LDA(At, 1, 0); PG8_STAGE(PG8_SA(0, 1), a2 + hstepA, voffA);
;             PG8_WAIT_V(8); PG8_WAIT_L(0); PG8_BAR; PG8_MMA(0, 0, At, B0); PG8_MMA(0, 1, At, B1); PG8_BAR; PG8_SCHED;
	s_setprio 1
	s_waitcnt lgkmcnt(0)
	v_mfma_f32_16x16x32_bf16 v[62:65], v[130:133], v[200:203], 0
	v_mfma_f32_16x16x32_bf16 v[58:61], v[138:141], v[200:203], 0
	v_mfma_f32_16x16x32_bf16 v[46:49], v[130:133], v[208:211], 0
	v_mfma_f32_16x16x32_bf16 v[42:45], v[138:141], v[208:211], 0
	v_mfma_f32_16x16x32_bf16 v[30:33], v[130:133], v[220:223], 0
	v_mfma_f32_16x16x32_bf16 v[26:29], v[138:141], v[220:223], 0
	v_mfma_f32_16x16x32_bf16 v[14:17], v[130:133], v[228:231], 0
	v_mfma_f32_16x16x32_bf16 v[10:13], v[138:141], v[228:231], 0
	v_mfma_f32_16x16x32_bf16 v[62:65], v[134:137], v[204:207], v[62:65]
	v_mfma_f32_16x16x32_bf16 v[58:61], v[142:145], v[204:207], v[58:61]
	v_mfma_f32_16x16x32_bf16 v[46:49], v[134:137], v[212:215], v[46:49]
	v_mfma_f32_16x16x32_bf16 v[42:45], v[142:145], v[212:215], v[42:45]
	v_mfma_f32_16x16x32_bf16 v[30:33], v[134:137], v[224:227], v[30:33]
	v_mfma_f32_16x16x32_bf16 v[26:29], v[142:145], v[224:227], v[26:29]
	v_mfma_f32_16x16x32_bf16 v[14:17], v[134:137], v[232:235], v[14:17]
	v_mfma_f32_16x16x32_bf16 v[10:13], v[142:145], v[232:235], v[10:13]
	s_setprio 0
	s_setprio 1
	v_mfma_f32_16x16x32_bf16 v[54:57], v[168:171], v[200:203], 0
	v_mfma_f32_16x16x32_bf16 v[50:53], v[192:195], v[200:203], 0
	v_mfma_f32_16x16x32_bf16 v[38:41], v[168:171], v[208:211], 0
	v_mfma_f32_16x16x32_bf16 v[34:37], v[192:195], v[208:211], 0
	v_mfma_f32_16x16x32_bf16 v[22:25], v[168:171], v[220:223], 0
	v_mfma_f32_16x16x32_bf16 v[18:21], v[192:195], v[220:223], 0
	v_mfma_f32_16x16x32_bf16 v[6:9], v[168:171], v[228:231], 0
	v_mfma_f32_16x16x32_bf16 v[2:5], v[192:195], v[228:231], 0
	v_mfma_f32_16x16x32_bf16 v[54:57], v[188:191], v[204:207], v[54:57]
	v_mfma_f32_16x16x32_bf16 v[50:53], v[196:199], v[204:207], v[50:53]
	v_mfma_f32_16x16x32_bf16 v[38:41], v[188:191], v[212:215], v[38:41]
	v_mfma_f32_16x16x32_bf16 v[34:37], v[196:199], v[212:215], v[34:37]
	v_mfma_f32_16x16x32_bf16 v[22:25], v[188:191], v[224:227], v[22:25]
	v_mfma_f32_16x16x32_bf16 v[18:21], v[196:199], v[224:227], v[18:21]
	v_mfma_f32_16x16x32_bf16 v[6:9], v[188:191], v[232:235], v[6:9]
	v_mfma_f32_16x16x32_bf16 v[2:5], v[196:199], v[232:235], v[2:5]
	s_setprio 0
	s_barrier
	s_add_i32 s48, 0, 0x18000
	s_add_i32 s49, 0, 0x1c000
	v_add_u32_e32 v142, s48, v177
	v_add_u32_e32 v154, s49, v177
	ds_read_b128 v[130:133], v142
	ds_read_b128 v[134:137], v142 offset:1024
	ds_read_b128 v[138:141], v142 offset:2048
	ds_read_b128 v[142:145], v142 offset:3072
	ds_read_b128 v[168:171], v154
	ds_read_b128 v[188:191], v154 offset:1024
	ds_read_b128 v[192:195], v154 offset:2048
	ds_read_b128 v[196:199], v154 offset:3072
	s_add_u32 s46, s46, 0x40000
	s_addc_u32 s47, s47, 0
	s_mov_b32 m0, s61
	v_lshl_add_u64 v[238:239], s[46:47], 0, v[146:147]
	ds_read_b128 v[200:203], v182 offset:32768
	ds_read_b128 v[204:207], v182 offset:33792
	ds_read_b128 v[208:211], v182 offset:34816
	ds_read_b128 v[212:215], v182 offset:35840
	ds_read_b128 v[220:223], v182 offset:36864
	ds_read_b128 v[224:227], v182 offset:37888
	ds_read_b128 v[228:231], v182 offset:38912
	ds_read_b128 v[232:235], v182 offset:39936
	global_load_lds_dwordx4 v[238:239], off
	v_lshl_add_u64 v[238:239], s[46:47], 0, v[150:151]
	s_mov_b32 m0, s62
	s_nop 0
	global_load_lds_dwordx4 v[238:239], off
	s_waitcnt vmcnt(8)
	s_waitcnt lgkmcnt(0)
	s_barrier
	s_setprio 1
	s_waitcnt lgkmcnt(0)
	v_mfma_f32_16x16x32_bf16 v[126:129], v[130:133], v[200:203], v[126:129]
	v_mfma_f32_16x16x32_bf16 v[122:125], v[138:141], v[200:203], v[122:125]
	v_mfma_f32_16x16x32_bf16 v[110:113], v[130:133], v[208:211], v[110:113]
	v_mfma_f32_16x16x32_bf16 v[106:109], v[138:141], v[208:211], v[106:109]
	v_mfma_f32_16x16x32_bf16 v[94:97], v[130:133], v[220:223], v[94:97]
	v_mfma_f32_16x16x32_bf16 v[90:93], v[138:141], v[220:223], v[90:93]
	v_mfma_f32_16x16x32_bf16 v[78:81], v[130:133], v[228:231], v[78:81]
	v_mfma_f32_16x16x32_bf16 v[74:77], v[138:141], v[228:231], v[74:77]
	v_mfma_f32_16x16x32_bf16 v[126:129], v[134:137], v[204:207], v[126:129]
	v_mfma_f32_16x16x32_bf16 v[122:125], v[142:145], v[204:207], v[122:125]
	v_mfma_f32_16x16x32_bf16 v[110:113], v[134:137], v[212:215], v[110:113]
	v_mfma_f32_16x16x32_bf16 v[106:109], v[142:145], v[212:215], v[106:109]
	v_mfma_f32_16x16x32_bf16 v[94:97], v[134:137], v[224:227], v[94:97]
	v_mfma_f32_16x16x32_bf16 v[90:93], v[142:145], v[224:227], v[90:93]
	v_mfma_f32_16x16x32_bf16 v[78:81], v[134:137], v[232:235], v[78:81]
	v_mfma_f32_16x16x32_bf16 v[74:77], v[142:145], v[232:235], v[74:77]
	s_setprio 0
	s_setprio 1
	v_mfma_f32_16x16x32_bf16 v[118:121], v[168:171], v[200:203], v[118:121]
	v_mfma_f32_16x16x32_bf16 v[114:117], v[192:195], v[200:203], v[114:117]
	v_mfma_f32_16x16x32_bf16 v[102:105], v[168:171], v[208:211], v[102:105]
	v_mfma_f32_16x16x32_bf16 v[98:101], v[192:195], v[208:211], v[98:101]
	v_mfma_f32_16x16x32_bf16 v[86:89], v[168:171], v[220:223], v[86:89]
	v_mfma_f32_16x16x32_bf16 v[82:85], v[192:195], v[220:223], v[82:85]
	v_mfma_f32_16x16x32_bf16 v[70:73], v[168:171], v[228:231], v[70:73]
	v_mfma_f32_16x16x32_bf16 v[66:69], v[192:195], v[228:231], v[66:69]
	v_mfma_f32_16x16x32_bf16 v[118:121], v[188:191], v[204:207], v[118:121]
	v_mfma_f32_16x16x32_bf16 v[114:117], v[196:199], v[204:207], v[114:117]
	v_mfma_f32_16x16x32_bf16 v[102:105], v[188:191], v[212:215], v[102:105]
	v_mfma_f32_16x16x32_bf16 v[98:101], v[196:199], v[212:215], v[98:101]
	v_mfma_f32_16x16x32_bf16 v[86:89], v[188:191], v[224:227], v[86:89]
	v_mfma_f32_16x16x32_bf16 v[82:85], v[196:199], v[224:227], v[82:85]
	v_mfma_f32_16x16x32_bf16 v[70:73], v[188:191], v[232:235], v[70:73]
	v_mfma_f32_16x16x32_bf16 v[66:69], v[196:199], v[232:235], v[66:69]
	s_setprio 0
	s_barrier
; #define PG8_STAGE(bufoff, gbase, voff) do { _Pragma("unroll") for (int _i = 0; _i < 2; ++_i) \
;         __builtin_amdgcn_global_load_lds((const unsigned*)((const char*)(gbase) + (voff)[_i]), (PG8_LAS unsigned*)(lds + (bufoff) + ldsw + _i * 8192), 16, 0, 0); } while (0)
; #define PG8_LDA(dst, b, h) do { _Pragma("unroll") for (int m = 0; m < 4; ++m) _Pragma("unroll") for (int k = 0; k < 2; ++k) dst[m][k] = *(const PG8_LAS bf16x8*)(lds + PG8_SA(b, h) + aoff + m * 2048 + k * 1024); } while (0)
; #define PG8_MMA(ai, bj, At, Bt) do { __builtin_amdgcn_s_setprio(1); _Pragma("unroll") for (int m = 0; m < 4; ++m) _Pragma("unroll") for (int n = 0; n < 2; ++n) _Pragma("unroll") for (int k = 0; k < 2; ++k) \
;         acc[ai][bj][m][n] = __builtin_amdgcn_mfma_f32_16x16x32_bf16(Bt[n][k], At[m][k], acc[ai][bj][m][n], 0, 0, 0); __builtin_amdgcn_s_setprio(0); } while (0)
; #define PG8_WAIT_V(n) asm volatile("s_waitcnt vmcnt(" #n ")" ::: "memory")
; #define PG8_WAIT_L(n) asm volatile("s_waitcnt lgkmcnt(" #n ")" ::: "memory")
; #define PG8_BAR __builtin_amdgcn_s_barrier()
; #define PG8_SCHED __builtin_amdgcn_sched_barrier(0)
; template <class Epi, class Sched, bool ALIGN_EPI = false, bool SP2 = false>
; __device__ __forceinline__ void gemm_phase(PG8_LAS unsigned char* lds, const Gemm g, const Sched& S, const Epi& E) {
;     ...
;         for (int t = 0; t < nt; t += 2) {
;     ...
;             PG8_LDA(At, 1, 1); PG8_STAGE(PG8_SB(1, 0), b3, voffB); PG8_STAGE(PG8_SB(1, 1), b3 + hstepB, voffB); PG8_STAGE(PG8_SA(1, 0), a3, voffA);
;             PG8_WAIT_V(8); PG8_WAIT_L(0); PG8_BAR; PG8_MMA(1, 0, At, B0); PG8_MMA(1, 1, At, B1); PG8_BAR; PG8_SCHED;
	s_add_i32 s46, s48, s55
	v_lshl_add_u64 v[172:173], v[172:173], 0, s[24:25]
	s_mov_b32 m0, s46
	ds_read_b128 v[200:203], v182 offset:49152
	ds_read_b128 v[204:207], v182 offset:50176
	ds_read_b128 v[208:211], v182 offset:51200
	ds_read_b128 v[212:215], v182 offset:52224
	ds_read_b128 v[220:223], v182 offset:53248
	ds_read_b128 v[224:227], v182 offset:54272
	ds_read_b128 v[228:231], v182 offset:55296
	ds_read_b128 v[232:235], v182 offset:56320
	global_load_lds_dwordx4 v[172:173], off
	s_add_i32 m0, s46, 0x2000
	s_add_u32 s8, s8, 0x40080
	v_lshl_add_u64 v[172:173], v[178:179], 0, s[24:25]
	s_addc_u32 s9, s9, 0
	s_add_i32 s46, s49, s55
	global_load_lds_dwordx4 v[172:173], off
	v_lshl_add_u64 v[172:173], s[8:9], 0, v[148:149]
	s_mov_b32 m0, s46
	s_nop 0
	global_load_lds_dwordx4 v[172:173], off
	v_lshl_add_u64 v[172:173], s[8:9], 0, v[152:153]
	s_add_i32 m0, s46, 0x2000
	s_nop 0
	global_load_lds_dwordx4 v[172:173], off
	v_lshl_add_u64 v[172:173], v[216:217], 0, s[24:25]
	s_mov_b32 m0, s66
	s_nop 0
	global_load_lds_dwordx4 v[172:173], off
	v_lshl_add_u64 v[172:173], v[236:237], 0, s[24:25]
	s_mov_b32 m0, s67
	s_nop 0
	global_load_lds_dwordx4 v[172:173], off
	s_waitcnt vmcnt(8)
	s_waitcnt lgkmcnt(0)
	s_barrier
	s_setprio 1
	s_waitcnt lgkmcnt(0)
	v_mfma_f32_16x16x32_bf16 v[62:65], v[130:133], v[200:203], v[62:65]
	v_mfma_f32_16x16x32_bf16 v[58:61], v[138:141], v[200:203], v[58:61]
	v_mfma_f32_16x16x32_bf16 v[46:49], v[130:133], v[208:211], v[46:49]
	v_mfma_f32_16x16x32_bf16 v[42:45], v[138:141], v[208:211], v[42:45]
	v_mfma_f32_16x16x32_bf16 v[30:33], v[130:133], v[220:223], v[30:33]
	v_mfma_f32_16x16x32_bf16 v[26:29], v[138:141], v[220:223], v[26:29]
	v_mfma_f32_16x16x32_bf16 v[14:17], v[130:133], v[228:231], v[14:17]
	v_mfma_f32_16x16x32_bf16 v[10:13], v[138:141], v[228:231], v[10:13]
	v_mfma_f32_16x16x32_bf16 v[62:65], v[134:137], v[204:207], v[62:65]
	v_mfma_f32_16x16x32_bf16 v[58:61], v[142:145], v[204:207], v[58:61]
	v_mfma_f32_16x16x32_bf16 v[46:49], v[134:137], v[212:215], v[46:49]
	v_mfma_f32_16x16x32_bf16 v[42:45], v[142:145], v[212:215], v[42:45]
	v_mfma_f32_16x16x32_bf16 v[30:33], v[134:137], v[224:227], v[30:33]
	v_mfma_f32_16x16x32_bf16 v[26:29], v[142:145], v[224:227], v[26:29]
	v_mfma_f32_16x16x32_bf16 v[14:17], v[134:137], v[232:235], v[14:17]
	v_mfma_f32_16x16x32_bf16 v[10:13], v[142:145], v[232:235], v[10:13]
	s_setprio 0
	s_setprio 1
	v_mfma_f32_16x16x32_bf16 v[54:57], v[168:171], v[200:203], v[54:57]
	v_mfma_f32_16x16x32_bf16 v[50:53], v[192:195], v[200:203], v[50:53]
	v_mfma_f32_16x16x32_bf16 v[38:41], v[168:171], v[208:211], v[38:41]
	v_mfma_f32_16x16x32_bf16 v[34:37], v[192:195], v[208:211], v[34:37]
	v_mfma_f32_16x16x32_bf16 v[22:25], v[168:171], v[220:223], v[22:25]
	v_mfma_f32_16x16x32_bf16 v[18:21], v[192:195], v[220:223], v[18:21]
	v_mfma_f32_16x16x32_bf16 v[6:9], v[168:171], v[228:231], v[6:9]
	v_mfma_f32_16x16x32_bf16 v[2:5], v[192:195], v[228:231], v[2:5]
	v_mfma_f32_16x16x32_bf16 v[54:57], v[188:191], v[204:207], v[54:57]
	v_mfma_f32_16x16x32_bf16 v[50:53], v[196:199], v[204:207], v[50:53]
	v_mfma_f32_16x16x32_bf16 v[38:41], v[188:191], v[212:215], v[38:41]
	v_mfma_f32_16x16x32_bf16 v[34:37], v[196:199], v[212:215], v[34:37]
	v_mfma_f32_16x16x32_bf16 v[22:25], v[188:191], v[224:227], v[22:25]
	v_mfma_f32_16x16x32_bf16 v[18:21], v[196:199], v[224:227], v[18:21]
	v_mfma_f32_16x16x32_bf16 v[6:9], v[188:191], v[232:235], v[6:9]
	v_mfma_f32_16x16x32_bf16 v[2:5], v[196:199], v[232:235], v[2:5]
	s_setprio 0
	s_barrier
	s_add_i32 s41, s41, 2
	s_add_u32 s6, s6, 0x100
	s_addc_u32 s7, s7, 0
	s_add_u32 s38, s38, 0x100
	s_addc_u32 s39, s39, 0
	s_cmp_gt_u32 s41, 13
	s_cbranch_scc1 .Lpeel_exit_0

; #define PG8_BAR __builtin_amdgcn_s_barrier()
; template <class Epi, class Sched, bool ALIGN_EPI = false, bool SP2 = false>
; __device__ __forceinline__ void gemm_phase(PG8_LAS unsigned char* lds, const Gemm g, const Sched& S, const Epi& E) {
;     ...
;         if constexpr (ALIGN_EPI) { if (wr == 0) PG8_BAR; }
.Lpeel_exit_0:
	s_and_b64 vcc, exec, s[26:27]
	s_cbranch_vccz .LBB0_200
	s_barrier

; #define PG8_STAGE(bufoff, gbase, voff) do { _Pragma("unroll") for (int _i = 0; _i < 2; ++_i) \
;         __builtin_amdgcn_global_load_lds((const unsigned*)((const char*)(gbase) + (voff)[_i]), (PG8_LAS unsigned*)(lds + (bufoff) + ldsw + _i * 8192), 16, 0, 0); } while (0)
; #define PG8_LDA(dst, b, h) do { _Pragma("unroll") for (int m = 0; m < 4; ++m) _Pragma("unroll") for (int k = 0; k < 2; ++k) dst[m][k] = *(const PG8_LAS bf16x8*)(lds + PG8_SA(b, h) + aoff + m * 2048 + k * 1024); } while (0)
; #define PG8_LDB(dst, b, h) do { _Pragma("unroll") for (int n = 0; n < 2; ++n) _Pragma("unroll") for (int k = 0; k < 2; ++k) dst[n][k] = *(const PG8_LAS bf16x8*)(lds + PG8_SB(b, h) + boff + n * 2048 + k * 1024); } while (0)
; #define PG8_MMA(ai, bj, At, Bt) do { __builtin_amdgcn_s_setprio(1); _Pragma("unroll") for (int m = 0; m < 4; ++m) _Pragma("unroll") for (int n = 0; n < 2; ++n) _Pragma("unroll") for (int k = 0; k < 2; ++k) \
;         acc[ai][bj][m][n] = __builtin_amdgcn_mfma_f32_16x16x32_bf16(Bt[n][k], At[m][k], acc[ai][bj][m][n], 0, 0, 0); __builtin_amdgcn_s_setprio(0); } while (0)
; #define PG8_BAR __builtin_amdgcn_s_barrier()
; template <class Epi, class Sched, bool ALIGN_EPI = false, bool SP2 = false>
; __device__ __forceinline__ void gemm_phase(PG8_LAS unsigned char* lds, const Gemm g, const Sched& S, const Epi& E) {
;     ...
;             const char* a1 = cA + (size_t)(t + 1) * kstep;
;             const char* a2 = last ? nA : cA + (size_t)(t + 2) * kstep; const char* b2 = last ? nB : cB + (size_t)(t + 2) * kstep;
;             const char* a3 = a2 + kstep; const char* b3 = b2 + kstep;
;             if (last && has_next) S.a_ready(nxt);
;             if constexpr (SP2) {
;             PG8_LDB(B0, 0, 0); PG8_LDB(B1, 0, 1); PG8_SCHED; PG8_LDA(At, 0, 0); PG8_STAGE(PG8_SA(1, 1), a1 + hstepA, voffA);
;             PG8_WAIT_V(8); PG8_WAIT_L(0); PG8_BAR; PG8_MMA(0, 0, At, B0); PG8_MMA(0, 1, At, B1); PG8_BAR; PG8_SCHED;
;             PG8_LDA(At, 0, 1); PG8_STAGE(PG8_SB(0, 0), b2, voffB); PG8_STAGE(PG8_SB(0, 1), b2 + hstepB, voffB); PG8_STAGE(PG8_SA(0, 0), a2, voffA);
;     ...
; #pragma unroll
;         for (int a = 0; a < 2; ++a)
; #pragma unroll
;             for (int b = 0; b < 2; ++b)
; #pragma unroll
;                 for (int m = 0; m < 4; ++m)
; #pragma unroll
;                     for (int n = 0; n < 2; ++n) acc[a][b][m][n] = (f32x4){0.f, 0.f, 0.f, 0.f};
.LBB0_416:
	s_and_b64 s[28:29], s[30:31], exec
	s_cselect_b32 s28, s74, s34
	s_ashr_i32 s29, s28, 31
	s_lshl_b64 s[28:29], s[28:29], 17
	s_add_u32 s28, s39, s28
	s_addc_u32 s29, s50, s29
	s_and_b64 s[34:35], s[30:31], exec
	s_cselect_b32 s76, s29, s13
	s_cselect_b32 s77, s28, s12
	s_mov_b64 s[40:41], 0
	s_mov_b64 s[34:35], -1
	s_mov_b64 s[36:37], 0
	s_add_u32 s44, s24, s40
	s_addc_u32 s45, s25, s41
	s_add_u32 s46, s44, 0x100
	s_addc_u32 s47, s45, 0
	s_and_b64 s[42:43], s[36:37], exec
	s_cselect_b32 s43, s27, s47
	s_cselect_b32 s42, s26, s46
	s_add_u32 s40, s12, s40
	s_addc_u32 s41, s13, s41
	ds_read_b128 v[146:149], v140
	ds_read_b128 v[150:153], v140 offset:1024
	ds_read_b128 v[154:157], v140 offset:2048
	ds_read_b128 v[158:161], v140 offset:3072
	ds_read_b128 v[162:165], v141
	ds_read_b128 v[166:169], v141 offset:1024
	ds_read_b128 v[170:173], v141 offset:2048
	ds_read_b128 v[176:179], v141 offset:3072
	s_add_u32 s40, s40, 0x100
	s_addc_u32 s41, s41, 0
	s_and_b64 s[36:37], s[36:37], exec
	s_cselect_b32 s41, s76, s41
	s_cselect_b32 s40, s77, s40
	s_add_u32 s48, s44, 0x18080
	s_addc_u32 s49, s45, 0
	s_add_u32 s44, s40, 0x10000
	s_addc_u32 s45, s41, 0
	s_add_u32 s36, s42, 0x18000
	s_addc_u32 s37, s43, 0
	s_add_u32 s46, s40, 0x10080
	s_addc_u32 s47, s41, 0
	s_mov_b32 m0, s64
	v_lshl_add_u64 v[212:213], s[48:49], 0, v[136:137]
	ds_read_b128 v[180:183], v142
	ds_read_b128 v[184:187], v142 offset:1024
	ds_read_b128 v[188:191], v142 offset:2048
	ds_read_b128 v[192:195], v142 offset:3072
	ds_read_b128 v[196:199], v142 offset:4096
	ds_read_b128 v[200:203], v142 offset:5120
	ds_read_b128 v[204:207], v142 offset:6144
	ds_read_b128 v[208:211], v142 offset:7168
	global_load_lds_dwordx4 v[212:213], off
	v_lshl_add_u64 v[212:213], s[48:49], 0, v[132:133]
	s_mov_b32 m0, s65
	s_nop 0
	global_load_lds_dwordx4 v[212:213], off
	s_waitcnt vmcnt(8)
	s_waitcnt lgkmcnt(0)
	s_barrier
	s_setprio 1
	s_waitcnt lgkmcnt(0)
	v_mfma_f32_16x16x32_bf16 v[126:129], v[146:149], v[180:183], 0
	v_mfma_f32_16x16x32_bf16 v[122:125], v[154:157], v[180:183], 0
	v_mfma_f32_16x16x32_bf16 v[118:121], v[146:149], v[188:191], 0
	v_mfma_f32_16x16x32_bf16 v[114:117], v[154:157], v[188:191], 0
	v_mfma_f32_16x16x32_bf16 v[106:109], v[146:149], v[196:199], 0
	v_mfma_f32_16x16x32_bf16 v[98:101], v[154:157], v[196:199], 0
	v_mfma_f32_16x16x32_bf16 v[90:93], v[146:149], v[204:207], 0
	v_mfma_f32_16x16x32_bf16 v[82:85], v[154:157], v[204:207], 0
	v_mfma_f32_16x16x32_bf16 v[126:129], v[150:153], v[184:187], v[126:129]
	v_mfma_f32_16x16x32_bf16 v[122:125], v[158:161], v[184:187], v[122:125]
	v_mfma_f32_16x16x32_bf16 v[118:121], v[150:153], v[192:195], v[118:121]
	v_mfma_f32_16x16x32_bf16 v[114:117], v[158:161], v[192:195], v[114:117]
	v_mfma_f32_16x16x32_bf16 v[106:109], v[150:153], v[200:203], v[106:109]
	v_mfma_f32_16x16x32_bf16 v[98:101], v[158:161], v[200:203], v[98:101]
	v_mfma_f32_16x16x32_bf16 v[90:93], v[150:153], v[208:211], v[90:93]
	v_mfma_f32_16x16x32_bf16 v[82:85], v[158:161], v[208:211], v[82:85]
	s_setprio 0
	s_setprio 1
	v_mfma_f32_16x16x32_bf16 v[110:113], v[162:165], v[180:183], 0
	v_mfma_f32_16x16x32_bf16 v[102:105], v[170:173], v[180:183], 0
	v_mfma_f32_16x16x32_bf16 v[94:97], v[162:165], v[188:191], 0
	v_mfma_f32_16x16x32_bf16 v[86:89], v[170:173], v[188:191], 0
	v_mfma_f32_16x16x32_bf16 v[78:81], v[162:165], v[196:199], 0
	v_mfma_f32_16x16x32_bf16 v[74:77], v[170:173], v[196:199], 0
	v_mfma_f32_16x16x32_bf16 v[70:73], v[162:165], v[204:207], 0
	v_mfma_f32_16x16x32_bf16 v[66:69], v[170:173], v[204:207], 0
	v_mfma_f32_16x16x32_bf16 v[110:113], v[166:169], v[184:187], v[110:113]
	v_mfma_f32_16x16x32_bf16 v[102:105], v[176:179], v[184:187], v[102:105]
	v_mfma_f32_16x16x32_bf16 v[94:97], v[166:169], v[192:195], v[94:97]
	v_mfma_f32_16x16x32_bf16 v[86:89], v[176:179], v[192:195], v[86:89]
	v_mfma_f32_16x16x32_bf16 v[78:81], v[166:169], v[200:203], v[78:81]
	v_mfma_f32_16x16x32_bf16 v[74:77], v[176:179], v[200:203], v[74:77]
	v_mfma_f32_16x16x32_bf16 v[70:73], v[166:169], v[208:211], v[70:73]
	v_mfma_f32_16x16x32_bf16 v[66:69], v[176:179], v[208:211], v[66:69]
	s_setprio 0
	s_barrier
	s_mov_b32 m0, s66
	v_lshl_add_u64 v[212:213], s[40:41], 0, v[134:135]
	ds_read_b128 v[180:183], v142 offset:16384
	ds_read_b128 v[184:187], v142 offset:17408
	ds_read_b128 v[188:191], v142 offset:18432
	ds_read_b128 v[192:195], v142 offset:19456
	ds_read_b128 v[196:199], v142 offset:20480
	ds_read_b128 v[200:203], v142 offset:21504
	ds_read_b128 v[204:207], v142 offset:22528
	ds_read_b128 v[208:211], v142 offset:23552
	global_load_lds_dwordx4 v[212:213], off
	v_lshl_add_u64 v[214:215], s[40:41], 0, v[130:131]
	s_mov_b32 m0, s67
	v_lshl_add_u64 v[216:217], s[44:45], 0, v[134:135]
	global_load_lds_dwordx4 v[214:215], off
	s_mov_b32 m0, s68
	v_lshl_add_u64 v[220:221], s[42:43], 0, v[132:133]
	global_load_lds_dwordx4 v[216:217], off
	v_lshl_add_u64 v[216:217], s[44:45], 0, v[130:131]
	s_mov_b32 m0, s69
	s_nop 0
	global_load_lds_dwordx4 v[216:217], off
	v_lshl_add_u64 v[216:217], s[42:43], 0, v[136:137]
	s_mov_b32 m0, s51
	s_nop 0
	global_load_lds_dwordx4 v[216:217], off
	s_mov_b32 m0, s53
	s_nop 0
	global_load_lds_dwordx4 v[220:221], off
	s_waitcnt vmcnt(8)
	s_waitcnt lgkmcnt(0)
	s_barrier
; #define PG8_STAGE(bufoff, gbase, voff) do { _Pragma("unroll") for (int _i = 0; _i < 2; ++_i) \
;         __builtin_amdgcn_global_load_lds((const unsigned*)((const char*)(gbase) + (voff)[_i]), (PG8_LAS unsigned*)(lds + (bufoff) + ldsw + _i * 8192), 16, 0, 0); } while (0)
; #define PG8_LDA(dst, b, h) do { _Pragma("unroll") for (int m = 0; m < 4; ++m) _Pragma("unroll") for (int k = 0; k < 2; ++k) dst[m][k] = *(const PG8_LAS bf16x8*)(lds + PG8_SA(b, h) + aoff + m * 2048 + k * 1024); } while (0)
; #define PG8_LDB(dst, b, h) do { _Pragma("unroll") for (int n = 0; n < 2; ++n) _Pragma("unroll") for (int k = 0; k < 2; ++k) dst[n][k] = *(const PG8_LAS bf16x8*)(lds + PG8_SB(b, h) + boff + n * 2048 + k * 1024); } while (0)
; #define PG8_MMA(ai, bj, At, Bt) do { __builtin_amdgcn_s_setprio(1); _Pragma("unroll") for (int m = 0; m < 4; ++m) _Pragma("unroll") for (int n = 0; n < 2; ++n) _Pragma("unroll") for (int k = 0; k < 2; ++k) \
;         acc[ai][bj][m][n] = __builtin_amdgcn_mfma_f32_16x16x32_bf16(Bt[n][k], At[m][k], acc[ai][bj][m][n], 0, 0, 0); __builtin_amdgcn_s_setprio(0); } while (0)
; #define PG8_WAIT_V(n) asm volatile("s_waitcnt vmcnt(" #n ")" ::: "memory")
; #define PG8_WAIT_L(n) asm volatile("s_waitcnt lgkmcnt(" #n ")" ::: "memory")
; #define PG8_BAR __builtin_amdgcn_s_barrier()
; #define PG8_SCHED __builtin_amdgcn_sched_barrier(0)
; template <class Epi, class Sched, bool ALIGN_EPI = false, bool SP2 = false>
; __device__ __forceinline__ void gemm_phase(PG8_LAS unsigned char* lds, const Gemm g, const Sched& S, const Epi& E) {
;     ...
;             PG8_WAIT_V(8); PG8_WAIT_L(0); PG8_BAR; PG8_MMA(1, 0, At, B0); PG8_MMA(1, 1, At, B1); PG8_BAR; PG8_SCHED;
;             PG8_LDB(B0, 1, 0); PG8_LDB(B1, 1, 1); PG8_SCHED; PG8_LDA(At, 1, 0); PG8_STAGE(PG8_SA(0, 1), a2 + hstepA, voffA);
;             PG8_WAIT_V(8); PG8_WAIT_L(0); PG8_BAR; PG8_MMA(0, 0, At, B0); PG8_MMA(0, 1, At, B1); PG8_BAR; PG8_SCHED;
	s_setprio 1
	s_waitcnt lgkmcnt(0)
	v_mfma_f32_16x16x32_bf16 v[62:65], v[146:149], v[180:183], 0
	v_mfma_f32_16x16x32_bf16 v[58:61], v[154:157], v[180:183], 0
	v_mfma_f32_16x16x32_bf16 v[54:57], v[146:149], v[188:191], 0
	v_mfma_f32_16x16x32_bf16 v[50:53], v[154:157], v[188:191], 0
	v_mfma_f32_16x16x32_bf16 v[42:45], v[146:149], v[196:199], 0
	v_mfma_f32_16x16x32_bf16 v[34:37], v[154:157], v[196:199], 0
	v_mfma_f32_16x16x32_bf16 v[26:29], v[146:149], v[204:207], 0
	v_mfma_f32_16x16x32_bf16 v[18:21], v[154:157], v[204:207], 0
	v_mfma_f32_16x16x32_bf16 v[62:65], v[150:153], v[184:187], v[62:65]
	v_mfma_f32_16x16x32_bf16 v[58:61], v[158:161], v[184:187], v[58:61]
	v_mfma_f32_16x16x32_bf16 v[54:57], v[150:153], v[192:195], v[54:57]
	v_mfma_f32_16x16x32_bf16 v[50:53], v[158:161], v[192:195], v[50:53]
	v_mfma_f32_16x16x32_bf16 v[42:45], v[150:153], v[200:203], v[42:45]
	v_mfma_f32_16x16x32_bf16 v[34:37], v[158:161], v[200:203], v[34:37]
	v_mfma_f32_16x16x32_bf16 v[26:29], v[150:153], v[208:211], v[26:29]
	v_mfma_f32_16x16x32_bf16 v[18:21], v[158:161], v[208:211], v[18:21]
	s_setprio 0
	s_setprio 1
	v_mfma_f32_16x16x32_bf16 v[46:49], v[162:165], v[180:183], 0
	v_mfma_f32_16x16x32_bf16 v[38:41], v[170:173], v[180:183], 0
	v_mfma_f32_16x16x32_bf16 v[30:33], v[162:165], v[188:191], 0
	v_mfma_f32_16x16x32_bf16 v[22:25], v[170:173], v[188:191], 0
	v_mfma_f32_16x16x32_bf16 v[14:17], v[162:165], v[196:199], 0
	v_mfma_f32_16x16x32_bf16 v[10:13], v[170:173], v[196:199], 0
	v_mfma_f32_16x16x32_bf16 v[6:9], v[162:165], v[204:207], 0
	v_mfma_f32_16x16x32_bf16 v[2:5], v[170:173], v[204:207], 0
	v_mfma_f32_16x16x32_bf16 v[46:49], v[166:169], v[184:187], v[46:49]
	v_mfma_f32_16x16x32_bf16 v[38:41], v[176:179], v[184:187], v[38:41]
	v_mfma_f32_16x16x32_bf16 v[30:33], v[166:169], v[192:195], v[30:33]
	v_mfma_f32_16x16x32_bf16 v[22:25], v[176:179], v[192:195], v[22:25]
	v_mfma_f32_16x16x32_bf16 v[14:17], v[166:169], v[200:203], v[14:17]
	v_mfma_f32_16x16x32_bf16 v[10:13], v[176:179], v[200:203], v[10:13]
	v_mfma_f32_16x16x32_bf16 v[6:9], v[166:169], v[208:211], v[6:9]
	v_mfma_f32_16x16x32_bf16 v[2:5], v[176:179], v[208:211], v[2:5]
	s_setprio 0
	s_barrier
	ds_read_b128 v[146:149], v143
	ds_read_b128 v[150:153], v143 offset:1024
	ds_read_b128 v[154:157], v143 offset:2048
	ds_read_b128 v[158:161], v143 offset:3072
	ds_read_b128 v[162:165], v144
	ds_read_b128 v[166:169], v144 offset:1024
	ds_read_b128 v[170:173], v144 offset:2048
	ds_read_b128 v[176:179], v144 offset:3072
	s_mov_b32 m0, s54
	v_lshl_add_u64 v[222:223], s[36:37], 0, v[136:137]
	ds_read_b128 v[180:183], v142 offset:32768
	ds_read_b128 v[184:187], v142 offset:33792
	ds_read_b128 v[188:191], v142 offset:34816
	ds_read_b128 v[192:195], v142 offset:35840
	ds_read_b128 v[196:199], v142 offset:36864
	ds_read_b128 v[200:203], v142 offset:37888
	ds_read_b128 v[204:207], v142 offset:38912
	ds_read_b128 v[208:211], v142 offset:39936
	global_load_lds_dwordx4 v[222:223], off
	v_lshl_add_u64 v[222:223], s[36:37], 0, v[132:133]
	s_mov_b32 m0, s55
	s_nop 0
	global_load_lds_dwordx4 v[222:223], off
	s_waitcnt vmcnt(8)
	s_waitcnt lgkmcnt(0)
	s_barrier
	s_setprio 1
	s_waitcnt lgkmcnt(0)
	v_mfma_f32_16x16x32_bf16 v[126:129], v[146:149], v[180:183], v[126:129]
	v_mfma_f32_16x16x32_bf16 v[122:125], v[154:157], v[180:183], v[122:125]
	v_mfma_f32_16x16x32_bf16 v[118:121], v[146:149], v[188:191], v[118:121]
	v_mfma_f32_16x16x32_bf16 v[114:117], v[154:157], v[188:191], v[114:117]
	v_mfma_f32_16x16x32_bf16 v[106:109], v[146:149], v[196:199], v[106:109]
	v_mfma_f32_16x16x32_bf16 v[98:101], v[154:157], v[196:199], v[98:101]
	v_mfma_f32_16x16x32_bf16 v[90:93], v[146:149], v[204:207], v[90:93]
	v_mfma_f32_16x16x32_bf16 v[82:85], v[154:157], v[204:207], v[82:85]
	v_mfma_f32_16x16x32_bf16 v[126:129], v[150:153], v[184:187], v[126:129]
	v_mfma_f32_16x16x32_bf16 v[122:125], v[158:161], v[184:187], v[122:125]
	v_mfma_f32_16x16x32_bf16 v[118:121], v[150:153], v[192:195], v[118:121]
	v_mfma_f32_16x16x32_bf16 v[114:117], v[158:161], v[192:195], v[114:117]
	v_mfma_f32_16x16x32_bf16 v[106:109], v[150:153], v[200:203], v[106:109]
	v_mfma_f32_16x16x32_bf16 v[98:101], v[158:161], v[200:203], v[98:101]
	v_mfma_f32_16x16x32_bf16 v[90:93], v[150:153], v[208:211], v[90:93]
	v_mfma_f32_16x16x32_bf16 v[82:85], v[158:161], v[208:211], v[82:85]
	s_setprio 0
	s_setprio 1
	v_mfma_f32_16x16x32_bf16 v[110:113], v[162:165], v[180:183], v[110:113]
	v_mfma_f32_16x16x32_bf16 v[102:105], v[170:173], v[180:183], v[102:105]
	v_mfma_f32_16x16x32_bf16 v[94:97], v[162:165], v[188:191], v[94:97]
	v_mfma_f32_16x16x32_bf16 v[86:89], v[170:173], v[188:191], v[86:89]
	v_mfma_f32_16x16x32_bf16 v[78:81], v[162:165], v[196:199], v[78:81]
	v_mfma_f32_16x16x32_bf16 v[74:77], v[170:173], v[196:199], v[74:77]
	v_mfma_f32_16x16x32_bf16 v[70:73], v[162:165], v[204:207], v[70:73]
	v_mfma_f32_16x16x32_bf16 v[66:69], v[170:173], v[204:207], v[66:69]
	v_mfma_f32_16x16x32_bf16 v[110:113], v[166:169], v[184:187], v[110:113]
	v_mfma_f32_16x16x32_bf16 v[102:105], v[176:179], v[184:187], v[102:105]
	v_mfma_f32_16x16x32_bf16 v[94:97], v[166:169], v[192:195], v[94:97]
	v_mfma_f32_16x16x32_bf16 v[86:89], v[176:179], v[192:195], v[86:89]
	v_mfma_f32_16x16x32_bf16 v[78:81], v[166:169], v[200:203], v[78:81]
	v_mfma_f32_16x16x32_bf16 v[74:77], v[176:179], v[200:203], v[74:77]
	v_mfma_f32_16x16x32_bf16 v[70:73], v[166:169], v[208:211], v[70:73]
	v_mfma_f32_16x16x32_bf16 v[66:69], v[176:179], v[208:211], v[66:69]
	s_setprio 0
	s_barrier
; #define PG8_STAGE(bufoff, gbase, voff) do { _Pragma("unroll") for (int _i = 0; _i < 2; ++_i) \
;         __builtin_amdgcn_global_load_lds((const unsigned*)((const char*)(gbase) + (voff)[_i]), (PG8_LAS unsigned*)(lds + (bufoff) + ldsw + _i * 8192), 16, 0, 0); } while (0)
; #define PG8_LDA(dst, b, h) do { _Pragma("unroll") for (int m = 0; m < 4; ++m) _Pragma("unroll") for (int k = 0; k < 2; ++k) dst[m][k] = *(const PG8_LAS bf16x8*)(lds + PG8_SA(b, h) + aoff + m * 2048 + k * 1024); } while (0)
; #define PG8_MMA(ai, bj, At, Bt) do { __builtin_amdgcn_s_setprio(1); _Pragma("unroll") for (int m = 0; m < 4; ++m) _Pragma("unroll") for (int n = 0; n < 2; ++n) _Pragma("unroll") for (int k = 0; k < 2; ++k) \
;         acc[ai][bj][m][n] = __builtin_amdgcn_mfma_f32_16x16x32_bf16(Bt[n][k], At[m][k], acc[ai][bj][m][n], 0, 0, 0); __builtin_amdgcn_s_setprio(0); } while (0)
; #define PG8_WAIT_V(n) asm volatile("s_waitcnt vmcnt(" #n ")" ::: "memory")
; #define PG8_WAIT_L(n) asm volatile("s_waitcnt lgkmcnt(" #n ")" ::: "memory")
; #define PG8_BAR __builtin_amdgcn_s_barrier()
; #define PG8_SCHED __builtin_amdgcn_sched_barrier(0)
; template <class Epi, class Sched, bool ALIGN_EPI = false, bool SP2 = false>
; __device__ __forceinline__ void gemm_phase(PG8_LAS unsigned char* lds, const Gemm g, const Sched& S, const Epi& E) {
;     ...
;         for (int t = 0; t < nt; t += 2) {
;     ...
;             PG8_LDA(At, 1, 1); PG8_STAGE(PG8_SB(1, 0), b3, voffB); PG8_STAGE(PG8_SB(1, 1), b3 + hstepB, voffB); PG8_STAGE(PG8_SA(1, 0), a3, voffA);
;             PG8_WAIT_V(8); PG8_WAIT_L(0); PG8_BAR; PG8_MMA(1, 0, At, B0); PG8_MMA(1, 1, At, B1); PG8_BAR; PG8_SCHED;
	s_mov_b32 m0, s70
	v_lshl_add_u64 v[212:213], v[212:213], 0, s[10:11]
	ds_read_b128 v[180:183], v142 offset:49152
	ds_read_b128 v[184:187], v142 offset:50176
	ds_read_b128 v[188:191], v142 offset:51200
	ds_read_b128 v[192:195], v142 offset:52224
	ds_read_b128 v[196:199], v142 offset:53248
	ds_read_b128 v[200:203], v142 offset:54272
	ds_read_b128 v[204:207], v142 offset:55296
	ds_read_b128 v[208:211], v142 offset:56320
	global_load_lds_dwordx4 v[212:213], off
	v_lshl_add_u64 v[212:213], v[214:215], 0, s[10:11]
	s_mov_b32 m0, s71
	s_nop 0
	global_load_lds_dwordx4 v[212:213], off
	v_lshl_add_u64 v[212:213], s[46:47], 0, v[134:135]
	s_mov_b32 m0, s72
	s_nop 0
	global_load_lds_dwordx4 v[212:213], off
	v_lshl_add_u64 v[212:213], s[46:47], 0, v[130:131]
	s_mov_b32 m0, s73
	s_nop 0
	global_load_lds_dwordx4 v[212:213], off
	v_lshl_add_u64 v[212:213], v[216:217], 0, s[10:11]
	s_mov_b32 m0, s62
	s_nop 0
	global_load_lds_dwordx4 v[212:213], off
	v_lshl_add_u64 v[212:213], v[220:221], 0, s[10:11]
	s_mov_b32 m0, s63
	s_nop 0
	global_load_lds_dwordx4 v[212:213], off
	s_waitcnt vmcnt(8)
	s_waitcnt lgkmcnt(0)
	s_barrier
	s_setprio 1
	s_waitcnt lgkmcnt(0)
	v_mfma_f32_16x16x32_bf16 v[62:65], v[146:149], v[180:183], v[62:65]
	v_mfma_f32_16x16x32_bf16 v[58:61], v[154:157], v[180:183], v[58:61]
	v_mfma_f32_16x16x32_bf16 v[54:57], v[146:149], v[188:191], v[54:57]
	v_mfma_f32_16x16x32_bf16 v[50:53], v[154:157], v[188:191], v[50:53]
	v_mfma_f32_16x16x32_bf16 v[42:45], v[146:149], v[196:199], v[42:45]
	v_mfma_f32_16x16x32_bf16 v[34:37], v[154:157], v[196:199], v[34:37]
	v_mfma_f32_16x16x32_bf16 v[26:29], v[146:149], v[204:207], v[26:29]
	v_mfma_f32_16x16x32_bf16 v[18:21], v[154:157], v[204:207], v[18:21]
	v_mfma_f32_16x16x32_bf16 v[62:65], v[150:153], v[184:187], v[62:65]
	v_mfma_f32_16x16x32_bf16 v[58:61], v[158:161], v[184:187], v[58:61]
	v_mfma_f32_16x16x32_bf16 v[54:57], v[150:153], v[192:195], v[54:57]
	v_mfma_f32_16x16x32_bf16 v[50:53], v[158:161], v[192:195], v[50:53]
	v_mfma_f32_16x16x32_bf16 v[42:45], v[150:153], v[200:203], v[42:45]
	v_mfma_f32_16x16x32_bf16 v[34:37], v[158:161], v[200:203], v[34:37]
	v_mfma_f32_16x16x32_bf16 v[26:29], v[150:153], v[208:211], v[26:29]
	v_mfma_f32_16x16x32_bf16 v[18:21], v[158:161], v[208:211], v[18:21]
	s_setprio 0
	s_setprio 1
	v_mfma_f32_16x16x32_bf16 v[46:49], v[162:165], v[180:183], v[46:49]
	v_mfma_f32_16x16x32_bf16 v[38:41], v[170:173], v[180:183], v[38:41]
	v_mfma_f32_16x16x32_bf16 v[30:33], v[162:165], v[188:191], v[30:33]
	v_mfma_f32_16x16x32_bf16 v[22:25], v[170:173], v[188:191], v[22:25]
	v_mfma_f32_16x16x32_bf16 v[14:17], v[162:165], v[196:199], v[14:17]
	v_mfma_f32_16x16x32_bf16 v[10:13], v[170:173], v[196:199], v[10:13]
	v_mfma_f32_16x16x32_bf16 v[6:9], v[162:165], v[204:207], v[6:9]
	v_mfma_f32_16x16x32_bf16 v[2:5], v[170:173], v[204:207], v[2:5]
	v_mfma_f32_16x16x32_bf16 v[46:49], v[166:169], v[184:187], v[46:49]
	v_mfma_f32_16x16x32_bf16 v[38:41], v[176:179], v[184:187], v[38:41]
	v_mfma_f32_16x16x32_bf16 v[30:33], v[166:169], v[192:195], v[30:33]
	v_mfma_f32_16x16x32_bf16 v[22:25], v[176:179], v[192:195], v[22:25]
	v_mfma_f32_16x16x32_bf16 v[14:17], v[166:169], v[200:203], v[14:17]
	v_mfma_f32_16x16x32_bf16 v[10:13], v[176:179], v[200:203], v[10:13]
	v_mfma_f32_16x16x32_bf16 v[6:9], v[166:169], v[208:211], v[6:9]
	v_mfma_f32_16x16x32_bf16 v[2:5], v[176:179], v[208:211], v[2:5]
	s_setprio 0
	s_barrier
	s_andn2_b64 vcc, exec, s[34:35]
	s_mov_b64 s[36:37], -1
	s_mov_b64 s[34:35], 0
	s_mov_b64 s[40:41], 0x100
	s_cbranch_vccnz .Lpeel_exit_1

; #define PG8_BAR __builtin_amdgcn_s_barrier()
; template <class Epi, class Sched, bool ALIGN_EPI = false, bool SP2 = false>
; __device__ __forceinline__ void gemm_phase(PG8_LAS unsigned char* lds, const Gemm g, const Sched& S, const Epi& E) {
;     ...
;         if constexpr (ALIGN_EPI) { if (wr == 0) PG8_BAR; }
.Lpeel_exit_1:
	s_and_b64 vcc, exec, s[14:15]
	s_cbranch_vccnz .LBB0_421
	s_andn2_b64 vcc, exec, s[16:17]
	s_cbranch_vccz .LBB0_422

; #define PG8_STAGE(bufoff, gbase, voff) do { _Pragma("unroll") for (int _i = 0; _i < 2; ++_i) \
;         __builtin_amdgcn_global_load_lds((const unsigned*)((const char*)(gbase) + (voff)[_i]), (PG8_LAS unsigned*)(lds + (bufoff) + ldsw + _i * 8192), 16, 0, 0); } while (0)
; #define PG8_LDA(dst, b, h) do { _Pragma("unroll") for (int m = 0; m < 4; ++m) _Pragma("unroll") for (int k = 0; k < 2; ++k) dst[m][k] = *(const PG8_LAS bf16x8*)(lds + PG8_SA(b, h) + aoff + m * 2048 + k * 1024); } while (0)
; #define PG8_LDB(dst, b, h) do { _Pragma("unroll") for (int n = 0; n < 2; ++n) _Pragma("unroll") for (int k = 0; k < 2; ++k) dst[n][k] = *(const PG8_LAS bf16x8*)(lds + PG8_SB(b, h) + boff + n * 2048 + k * 1024); } while (0)
; #define PG8_MMA(ai, bj, At, Bt) do { __builtin_amdgcn_s_setprio(1); _Pragma("unroll") for (int m = 0; m < 4; ++m) _Pragma("unroll") for (int n = 0; n < 2; ++n) _Pragma("unroll") for (int k = 0; k < 2; ++k) \
;         acc[ai][bj][m][n] = __builtin_amdgcn_mfma_f32_16x16x32_bf16(Bt[n][k], At[m][k], acc[ai][bj][m][n], 0, 0, 0); __builtin_amdgcn_s_setprio(0); } while (0)
; #define PG8_BAR __builtin_amdgcn_s_barrier()
; template <class Epi, class Sched, bool ALIGN_EPI = false, bool SP2 = false>
; __device__ __forceinline__ void gemm_phase(PG8_LAS unsigned char* lds, const Gemm g, const Sched& S, const Epi& E) {
;     ...
;             const char* a1 = cA + (size_t)(t + 1) * kstep;
;             const char* a2 = last ? nA : cA + (size_t)(t + 2) * kstep; const char* b2 = last ? nB : cB + (size_t)(t + 2) * kstep;
;             const char* a3 = a2 + kstep; const char* b3 = b2 + kstep;
;             if (last && has_next) S.a_ready(nxt);
;             if constexpr (SP2) {
;             PG8_LDB(B0, 0, 0); PG8_LDB(B1, 0, 1); PG8_SCHED; PG8_LDA(At, 0, 0); PG8_STAGE(PG8_SA(1, 1), a1 + hstepA, voffA);
;             PG8_WAIT_V(8); PG8_WAIT_L(0); PG8_BAR; PG8_MMA(0, 0, At, B0); PG8_MMA(0, 1, At, B1); PG8_BAR; PG8_SCHED;
;             PG8_LDA(At, 0, 1); PG8_STAGE(PG8_SB(0, 0), b2, voffB); PG8_STAGE(PG8_SB(0, 1), b2 + hstepB, voffB); PG8_STAGE(PG8_SA(0, 0), a2, voffA);
;     ...
; #pragma unroll
;         for (int a = 0; a < 2; ++a)
; #pragma unroll
;             for (int b = 0; b < 2; ++b)
; #pragma unroll
;                 for (int m = 0; m < 4; ++m)
; #pragma unroll
;                     for (int n = 0; n < 2; ++n) acc[a][b][m][n] = (f32x4){0.f, 0.f, 0.f, 0.f};
.LBB0_685:
	s_add_u32 s38, s22, 0x100
	s_addc_u32 s39, s23, 0
	s_mov_b32 s61, -2
	ds_read_b128 v[146:149], v152
	ds_read_b128 v[158:161], v152 offset:1024
	ds_read_b128 v[162:165], v152 offset:2048
	ds_read_b128 v[166:169], v152 offset:3072
	ds_read_b128 v[170:173], v153
	ds_read_b128 v[176:179], v153 offset:1024
	ds_read_b128 v[180:183], v153 offset:2048
	ds_read_b128 v[184:187], v153 offset:3072
	s_add_u32 s22, s20, 0x100
	s_addc_u32 s23, s21, 0
	s_cmp_eq_u32 s61, 2
	s_cselect_b32 s27, s17, s23
	s_cselect_b32 s26, s16, s22
	s_cselect_b32 s25, s19, s39
	s_cselect_b32 s24, s18, s38
	s_mov_b32 m0, s43
	v_lshl_add_u64 v[216:217], s[20:21], 0, v[142:143]
	ds_read_b128 v[188:191], v154
	ds_read_b128 v[192:195], v154 offset:1024
	ds_read_b128 v[196:199], v154 offset:2048
	ds_read_b128 v[200:203], v154 offset:3072
	ds_read_b128 v[204:207], v154 offset:4096
	ds_read_b128 v[208:211], v154 offset:5120
	ds_read_b128 v[212:215], v154 offset:6144
	ds_read_b128 v[220:223], v154 offset:7168
	global_load_lds_dwordx4 v[216:217], off
	v_lshl_add_u64 v[216:217], s[20:21], 0, v[144:145]
	s_mov_b32 m0, s44
	s_nop 0
	global_load_lds_dwordx4 v[216:217], off
	s_waitcnt vmcnt(8)
	s_waitcnt lgkmcnt(0)
	s_barrier
	s_setprio 1
	s_waitcnt lgkmcnt(0)
	v_mfma_f32_16x16x32_bf16 v[126:129], v[146:149], v[188:191], 0
	v_mfma_f32_16x16x32_bf16 v[122:125], v[162:165], v[188:191], 0
	v_mfma_f32_16x16x32_bf16 v[110:113], v[146:149], v[196:199], 0
	v_mfma_f32_16x16x32_bf16 v[106:109], v[162:165], v[196:199], 0
	v_mfma_f32_16x16x32_bf16 v[94:97], v[146:149], v[204:207], 0
	v_mfma_f32_16x16x32_bf16 v[90:93], v[162:165], v[204:207], 0
	v_mfma_f32_16x16x32_bf16 v[78:81], v[146:149], v[212:215], 0
	v_mfma_f32_16x16x32_bf16 v[74:77], v[162:165], v[212:215], 0
	v_mfma_f32_16x16x32_bf16 v[126:129], v[158:161], v[192:195], v[126:129]
	v_mfma_f32_16x16x32_bf16 v[122:125], v[166:169], v[192:195], v[122:125]
	v_mfma_f32_16x16x32_bf16 v[110:113], v[158:161], v[200:203], v[110:113]
	v_mfma_f32_16x16x32_bf16 v[106:109], v[166:169], v[200:203], v[106:109]
	v_mfma_f32_16x16x32_bf16 v[94:97], v[158:161], v[208:211], v[94:97]
	v_mfma_f32_16x16x32_bf16 v[90:93], v[166:169], v[208:211], v[90:93]
	v_mfma_f32_16x16x32_bf16 v[78:81], v[158:161], v[220:223], v[78:81]
	v_mfma_f32_16x16x32_bf16 v[74:77], v[166:169], v[220:223], v[74:77]
	s_setprio 0
	s_setprio 1
	v_mfma_f32_16x16x32_bf16 v[118:121], v[170:173], v[188:191], 0
	v_mfma_f32_16x16x32_bf16 v[114:117], v[180:183], v[188:191], 0
	v_mfma_f32_16x16x32_bf16 v[102:105], v[170:173], v[196:199], 0
	v_mfma_f32_16x16x32_bf16 v[98:101], v[180:183], v[196:199], 0
	v_mfma_f32_16x16x32_bf16 v[86:89], v[170:173], v[204:207], 0
	v_mfma_f32_16x16x32_bf16 v[82:85], v[180:183], v[204:207], 0
	v_mfma_f32_16x16x32_bf16 v[70:73], v[170:173], v[212:215], 0
	v_mfma_f32_16x16x32_bf16 v[66:69], v[180:183], v[212:215], 0
	v_mfma_f32_16x16x32_bf16 v[118:121], v[176:179], v[192:195], v[118:121]
	v_mfma_f32_16x16x32_bf16 v[114:117], v[184:187], v[192:195], v[114:117]
	v_mfma_f32_16x16x32_bf16 v[102:105], v[176:179], v[200:203], v[102:105]
	v_mfma_f32_16x16x32_bf16 v[98:101], v[184:187], v[200:203], v[98:101]
	v_mfma_f32_16x16x32_bf16 v[86:89], v[176:179], v[208:211], v[86:89]
	v_mfma_f32_16x16x32_bf16 v[82:85], v[184:187], v[208:211], v[82:85]
	v_mfma_f32_16x16x32_bf16 v[70:73], v[176:179], v[220:223], v[70:73]
	v_mfma_f32_16x16x32_bf16 v[66:69], v[184:187], v[220:223], v[66:69]
	s_setprio 0
	s_barrier
	s_mov_b32 m0, s45
	v_lshl_add_u64 v[216:217], s[24:25], 0, v[134:135]
	s_add_u32 s20, s24, 0x18000
	ds_read_b128 v[188:191], v154 offset:16384
	ds_read_b128 v[192:195], v154 offset:17408
	ds_read_b128 v[196:199], v154 offset:18432
	ds_read_b128 v[200:203], v154 offset:19456
	ds_read_b128 v[204:207], v154 offset:20480
	ds_read_b128 v[208:211], v154 offset:21504
	ds_read_b128 v[212:215], v154 offset:22528
	ds_read_b128 v[220:223], v154 offset:23552
	global_load_lds_dwordx4 v[216:217], off
	v_lshl_add_u64 v[224:225], s[24:25], 0, v[130:131]
	s_mov_b32 m0, s46
	s_addc_u32 s21, s25, 0
	global_load_lds_dwordx4 v[224:225], off
	v_lshl_add_u64 v[226:227], s[20:21], 0, v[134:135]
	s_mov_b32 m0, s47
	v_lshl_add_u64 v[228:229], s[26:27], 0, v[132:133]
	global_load_lds_dwordx4 v[226:227], off
	v_lshl_add_u64 v[226:227], s[20:21], 0, v[130:131]
	s_mov_b32 m0, s48
	s_nop 0
	global_load_lds_dwordx4 v[226:227], off
	v_lshl_add_u64 v[226:227], s[26:27], 0, v[136:137]
	s_mov_b32 m0, s34
	s_nop 0
	global_load_lds_dwordx4 v[226:227], off
	s_mov_b32 m0, s35
	s_nop 0
	global_load_lds_dwordx4 v[228:229], off
	s_waitcnt vmcnt(8)
	s_waitcnt lgkmcnt(0)
	s_barrier
; #define PG8_STAGE(bufoff, gbase, voff) do { _Pragma("unroll") for (int _i = 0; _i < 2; ++_i) \
;         __builtin_amdgcn_global_load_lds((const unsigned*)((const char*)(gbase) + (voff)[_i]), (PG8_LAS unsigned*)(lds + (bufoff) + ldsw + _i * 8192), 16, 0, 0); } while (0)
; #define PG8_LDA(dst, b, h) do { _Pragma("unroll") for (int m = 0; m < 4; ++m) _Pragma("unroll") for (int k = 0; k < 2; ++k) dst[m][k] = *(const PG8_LAS bf16x8*)(lds + PG8_SA(b, h) + aoff + m * 2048 + k * 1024); } while (0)
; #define PG8_LDB(dst, b, h) do { _Pragma("unroll") for (int n = 0; n < 2; ++n) _Pragma("unroll") for (int k = 0; k < 2; ++k) dst[n][k] = *(const PG8_LAS bf16x8*)(lds + PG8_SB(b, h) + boff + n * 2048 + k * 1024); } while (0)
; #define PG8_MMA(ai, bj, At, Bt) do { __builtin_amdgcn_s_setprio(1); _Pragma("unroll") for (int m = 0; m < 4; ++m) _Pragma("unroll") for (int n = 0; n < 2; ++n) _Pragma("unroll") for (int k = 0; k < 2; ++k) \
;         acc[ai][bj][m][n] = __builtin_amdgcn_mfma_f32_16x16x32_bf16(Bt[n][k], At[m][k], acc[ai][bj][m][n], 0, 0, 0); __builtin_amdgcn_s_setprio(0); } while (0)
; #define PG8_WAIT_V(n) asm volatile("s_waitcnt vmcnt(" #n ")" ::: "memory")
; #define PG8_WAIT_L(n) asm volatile("s_waitcnt lgkmcnt(" #n ")" ::: "memory")
; #define PG8_BAR __builtin_amdgcn_s_barrier()
; #define PG8_SCHED __builtin_amdgcn_sched_barrier(0)
; template <class Epi, class Sched, bool ALIGN_EPI = false, bool SP2 = false>
; __device__ __forceinline__ void gemm_phase(PG8_LAS unsigned char* lds, const Gemm g, const Sched& S, const Epi& E) {
;     ...
;             PG8_WAIT_V(8); PG8_WAIT_L(0); PG8_BAR; PG8_MMA(1, 0, At, B0); PG8_MMA(1, 1, At, B1); PG8_BAR; PG8_SCHED;
;             PG8_LDB(B0, 1, 0); PG8_LDB(B1, 1, 1); PG8_SCHED; PG8_LDA(At, 1, 0); PG8_STAGE(PG8_SA(0, 1), a2 + hstepA, voffA);
;             PG8_WAIT_V(8); PG8_WAIT_L(0); PG8_BAR; PG8_MMA(0, 0, At, B0); PG8_MMA(0, 1, At, B1); PG8_BAR; PG8_SCHED;
	s_setprio 1
	s_waitcnt lgkmcnt(0)
	v_mfma_f32_16x16x32_bf16 v[62:65], v[146:149], v[188:191], 0
	v_mfma_f32_16x16x32_bf16 v[58:61], v[162:165], v[188:191], 0
	v_mfma_f32_16x16x32_bf16 v[46:49], v[146:149], v[196:199], 0
	v_mfma_f32_16x16x32_bf16 v[42:45], v[162:165], v[196:199], 0
	v_mfma_f32_16x16x32_bf16 v[30:33], v[146:149], v[204:207], 0
	v_mfma_f32_16x16x32_bf16 v[26:29], v[162:165], v[204:207], 0
	v_mfma_f32_16x16x32_bf16 v[14:17], v[146:149], v[212:215], 0
	v_mfma_f32_16x16x32_bf16 v[10:13], v[162:165], v[212:215], 0
	v_mfma_f32_16x16x32_bf16 v[62:65], v[158:161], v[192:195], v[62:65]
	v_mfma_f32_16x16x32_bf16 v[58:61], v[166:169], v[192:195], v[58:61]
	v_mfma_f32_16x16x32_bf16 v[46:49], v[158:161], v[200:203], v[46:49]
	v_mfma_f32_16x16x32_bf16 v[42:45], v[166:169], v[200:203], v[42:45]
	v_mfma_f32_16x16x32_bf16 v[30:33], v[158:161], v[208:211], v[30:33]
	v_mfma_f32_16x16x32_bf16 v[26:29], v[166:169], v[208:211], v[26:29]
	v_mfma_f32_16x16x32_bf16 v[14:17], v[158:161], v[220:223], v[14:17]
	v_mfma_f32_16x16x32_bf16 v[10:13], v[166:169], v[220:223], v[10:13]
	s_setprio 0
	s_setprio 1
	v_mfma_f32_16x16x32_bf16 v[54:57], v[170:173], v[188:191], 0
	v_mfma_f32_16x16x32_bf16 v[50:53], v[180:183], v[188:191], 0
	v_mfma_f32_16x16x32_bf16 v[38:41], v[170:173], v[196:199], 0
	v_mfma_f32_16x16x32_bf16 v[34:37], v[180:183], v[196:199], 0
	v_mfma_f32_16x16x32_bf16 v[22:25], v[170:173], v[204:207], 0
	v_mfma_f32_16x16x32_bf16 v[18:21], v[180:183], v[204:207], 0
	v_mfma_f32_16x16x32_bf16 v[6:9], v[170:173], v[212:215], 0
	v_mfma_f32_16x16x32_bf16 v[2:5], v[180:183], v[212:215], 0
	v_mfma_f32_16x16x32_bf16 v[54:57], v[176:179], v[192:195], v[54:57]
	v_mfma_f32_16x16x32_bf16 v[50:53], v[184:187], v[192:195], v[50:53]
	v_mfma_f32_16x16x32_bf16 v[38:41], v[176:179], v[200:203], v[38:41]
	v_mfma_f32_16x16x32_bf16 v[34:37], v[184:187], v[200:203], v[34:37]
	v_mfma_f32_16x16x32_bf16 v[22:25], v[176:179], v[208:211], v[22:25]
	v_mfma_f32_16x16x32_bf16 v[18:21], v[184:187], v[208:211], v[18:21]
	v_mfma_f32_16x16x32_bf16 v[6:9], v[176:179], v[220:223], v[6:9]
	v_mfma_f32_16x16x32_bf16 v[2:5], v[184:187], v[220:223], v[2:5]
	s_setprio 0
	s_barrier
	ds_read_b128 v[146:149], v155
	ds_read_b128 v[158:161], v155 offset:1024
	ds_read_b128 v[162:165], v155 offset:2048
	ds_read_b128 v[166:169], v155 offset:3072
	ds_read_b128 v[170:173], v156
	ds_read_b128 v[176:179], v156 offset:1024
	ds_read_b128 v[180:183], v156 offset:2048
	ds_read_b128 v[184:187], v156 offset:3072
	s_add_u32 s20, s26, 0x18000
	s_addc_u32 s21, s27, 0
	s_mov_b32 m0, s36
	v_lshl_add_u64 v[230:231], s[20:21], 0, v[136:137]
	ds_read_b128 v[188:191], v154 offset:32768
	ds_read_b128 v[192:195], v154 offset:33792
	ds_read_b128 v[196:199], v154 offset:34816
	ds_read_b128 v[200:203], v154 offset:35840
	ds_read_b128 v[204:207], v154 offset:36864
	ds_read_b128 v[208:211], v154 offset:37888
	ds_read_b128 v[212:215], v154 offset:38912
	ds_read_b128 v[220:223], v154 offset:39936
	global_load_lds_dwordx4 v[230:231], off
	v_lshl_add_u64 v[230:231], s[20:21], 0, v[132:133]
	s_mov_b32 m0, s37
	s_nop 0
	global_load_lds_dwordx4 v[230:231], off
	s_waitcnt vmcnt(8)
	s_waitcnt lgkmcnt(0)
	s_barrier
	s_setprio 1
	s_waitcnt lgkmcnt(0)
	v_mfma_f32_16x16x32_bf16 v[126:129], v[146:149], v[188:191], v[126:129]
	v_mfma_f32_16x16x32_bf16 v[122:125], v[162:165], v[188:191], v[122:125]
	v_mfma_f32_16x16x32_bf16 v[110:113], v[146:149], v[196:199], v[110:113]
	v_mfma_f32_16x16x32_bf16 v[106:109], v[162:165], v[196:199], v[106:109]
	v_mfma_f32_16x16x32_bf16 v[94:97], v[146:149], v[204:207], v[94:97]
	v_mfma_f32_16x16x32_bf16 v[90:93], v[162:165], v[204:207], v[90:93]
	v_mfma_f32_16x16x32_bf16 v[78:81], v[146:149], v[212:215], v[78:81]
	v_mfma_f32_16x16x32_bf16 v[74:77], v[162:165], v[212:215], v[74:77]
	v_mfma_f32_16x16x32_bf16 v[126:129], v[158:161], v[192:195], v[126:129]
	v_mfma_f32_16x16x32_bf16 v[122:125], v[166:169], v[192:195], v[122:125]
	v_mfma_f32_16x16x32_bf16 v[110:113], v[158:161], v[200:203], v[110:113]
	v_mfma_f32_16x16x32_bf16 v[106:109], v[166:169], v[200:203], v[106:109]
	v_mfma_f32_16x16x32_bf16 v[94:97], v[158:161], v[208:211], v[94:97]
	v_mfma_f32_16x16x32_bf16 v[90:93], v[166:169], v[208:211], v[90:93]
	v_mfma_f32_16x16x32_bf16 v[78:81], v[158:161], v[220:223], v[78:81]
	v_mfma_f32_16x16x32_bf16 v[74:77], v[166:169], v[220:223], v[74:77]
	s_setprio 0
	s_setprio 1
	v_mfma_f32_16x16x32_bf16 v[118:121], v[170:173], v[188:191], v[118:121]
	v_mfma_f32_16x16x32_bf16 v[114:117], v[180:183], v[188:191], v[114:117]
	v_mfma_f32_16x16x32_bf16 v[102:105], v[170:173], v[196:199], v[102:105]
	v_mfma_f32_16x16x32_bf16 v[98:101], v[180:183], v[196:199], v[98:101]
	v_mfma_f32_16x16x32_bf16 v[86:89], v[170:173], v[204:207], v[86:89]
	v_mfma_f32_16x16x32_bf16 v[82:85], v[180:183], v[204:207], v[82:85]
	v_mfma_f32_16x16x32_bf16 v[70:73], v[170:173], v[212:215], v[70:73]
	v_mfma_f32_16x16x32_bf16 v[66:69], v[180:183], v[212:215], v[66:69]
	v_mfma_f32_16x16x32_bf16 v[118:121], v[176:179], v[192:195], v[118:121]
	v_mfma_f32_16x16x32_bf16 v[114:117], v[184:187], v[192:195], v[114:117]
	v_mfma_f32_16x16x32_bf16 v[102:105], v[176:179], v[200:203], v[102:105]
	v_mfma_f32_16x16x32_bf16 v[98:101], v[184:187], v[200:203], v[98:101]
	v_mfma_f32_16x16x32_bf16 v[86:89], v[176:179], v[208:211], v[86:89]
	v_mfma_f32_16x16x32_bf16 v[82:85], v[184:187], v[208:211], v[82:85]
	v_mfma_f32_16x16x32_bf16 v[70:73], v[176:179], v[220:223], v[70:73]
	v_mfma_f32_16x16x32_bf16 v[66:69], v[184:187], v[220:223], v[66:69]
	s_setprio 0
	s_barrier
; #define PG8_STAGE(bufoff, gbase, voff) do { _Pragma("unroll") for (int _i = 0; _i < 2; ++_i) \
;         __builtin_amdgcn_global_load_lds((const unsigned*)((const char*)(gbase) + (voff)[_i]), (PG8_LAS unsigned*)(lds + (bufoff) + ldsw + _i * 8192), 16, 0, 0); } while (0)
; #define PG8_LDA(dst, b, h) do { _Pragma("unroll") for (int m = 0; m < 4; ++m) _Pragma("unroll") for (int k = 0; k < 2; ++k) dst[m][k] = *(const PG8_LAS bf16x8*)(lds + PG8_SA(b, h) + aoff + m * 2048 + k * 1024); } while (0)
; #define PG8_MMA(ai, bj, At, Bt) do { __builtin_amdgcn_s_setprio(1); _Pragma("unroll") for (int m = 0; m < 4; ++m) _Pragma("unroll") for (int n = 0; n < 2; ++n) _Pragma("unroll") for (int k = 0; k < 2; ++k) \
;         acc[ai][bj][m][n] = __builtin_amdgcn_mfma_f32_16x16x32_bf16(Bt[n][k], At[m][k], acc[ai][bj][m][n], 0, 0, 0); __builtin_amdgcn_s_setprio(0); } while (0)
; #define PG8_WAIT_V(n) asm volatile("s_waitcnt vmcnt(" #n ")" ::: "memory")
; #define PG8_WAIT_L(n) asm volatile("s_waitcnt lgkmcnt(" #n ")" ::: "memory")
; #define PG8_BAR __builtin_amdgcn_s_barrier()
; #define PG8_SCHED __builtin_amdgcn_sched_barrier(0)
; template <class Epi, class Sched, bool ALIGN_EPI = false, bool SP2 = false>
; __device__ __forceinline__ void gemm_phase(PG8_LAS unsigned char* lds, const Gemm g, const Sched& S, const Epi& E) {
;     ...
;         for (int t = 0; t < nt; t += 2) {
;     ...
;             PG8_LDA(At, 1, 1); PG8_STAGE(PG8_SB(1, 0), b3, voffB); PG8_STAGE(PG8_SB(1, 1), b3 + hstepB, voffB); PG8_STAGE(PG8_SA(1, 0), a3, voffA);
;             PG8_WAIT_V(8); PG8_WAIT_L(0); PG8_BAR; PG8_MMA(1, 0, At, B0); PG8_MMA(1, 1, At, B1); PG8_BAR; PG8_SCHED;
	s_mov_b32 m0, s56
	v_lshl_add_u64 v[216:217], v[216:217], 0, s[12:13]
	s_add_u32 s20, s24, 0x18080
	ds_read_b128 v[188:191], v154 offset:49152
	ds_read_b128 v[192:195], v154 offset:50176
	ds_read_b128 v[196:199], v154 offset:51200
	ds_read_b128 v[200:203], v154 offset:52224
	ds_read_b128 v[204:207], v154 offset:53248
	ds_read_b128 v[208:211], v154 offset:54272
	ds_read_b128 v[212:215], v154 offset:55296
	ds_read_b128 v[220:223], v154 offset:56320
	global_load_lds_dwordx4 v[216:217], off
	v_lshl_add_u64 v[216:217], v[224:225], 0, s[12:13]
	s_mov_b32 m0, s57
	s_addc_u32 s21, s25, 0
	global_load_lds_dwordx4 v[216:217], off
	v_lshl_add_u64 v[216:217], s[20:21], 0, v[134:135]
	s_mov_b32 m0, s58
	s_nop 0
	global_load_lds_dwordx4 v[216:217], off
	v_lshl_add_u64 v[216:217], s[20:21], 0, v[130:131]
	s_mov_b32 m0, s59
	s_nop 0
	global_load_lds_dwordx4 v[216:217], off
	v_lshl_add_u64 v[216:217], v[226:227], 0, s[12:13]
	s_mov_b32 m0, s41
	s_nop 0
	global_load_lds_dwordx4 v[216:217], off
	v_lshl_add_u64 v[216:217], v[228:229], 0, s[12:13]
	s_mov_b32 m0, s42
	s_nop 0
	global_load_lds_dwordx4 v[216:217], off
	s_waitcnt vmcnt(8)
	s_waitcnt lgkmcnt(0)
	s_barrier
	s_setprio 1
	s_waitcnt lgkmcnt(0)
	v_mfma_f32_16x16x32_bf16 v[62:65], v[146:149], v[188:191], v[62:65]
	v_mfma_f32_16x16x32_bf16 v[58:61], v[162:165], v[188:191], v[58:61]
	v_mfma_f32_16x16x32_bf16 v[46:49], v[146:149], v[196:199], v[46:49]
	v_mfma_f32_16x16x32_bf16 v[42:45], v[162:165], v[196:199], v[42:45]
	v_mfma_f32_16x16x32_bf16 v[30:33], v[146:149], v[204:207], v[30:33]
	v_mfma_f32_16x16x32_bf16 v[26:29], v[162:165], v[204:207], v[26:29]
	v_mfma_f32_16x16x32_bf16 v[14:17], v[146:149], v[212:215], v[14:17]
	v_mfma_f32_16x16x32_bf16 v[10:13], v[162:165], v[212:215], v[10:13]
	v_mfma_f32_16x16x32_bf16 v[62:65], v[158:161], v[192:195], v[62:65]
	v_mfma_f32_16x16x32_bf16 v[58:61], v[166:169], v[192:195], v[58:61]
	v_mfma_f32_16x16x32_bf16 v[46:49], v[158:161], v[200:203], v[46:49]
	v_mfma_f32_16x16x32_bf16 v[42:45], v[166:169], v[200:203], v[42:45]
	v_mfma_f32_16x16x32_bf16 v[30:33], v[158:161], v[208:211], v[30:33]
	v_mfma_f32_16x16x32_bf16 v[26:29], v[166:169], v[208:211], v[26:29]
	v_mfma_f32_16x16x32_bf16 v[14:17], v[158:161], v[220:223], v[14:17]
	v_mfma_f32_16x16x32_bf16 v[10:13], v[166:169], v[220:223], v[10:13]
	s_setprio 0
	s_setprio 1
	v_mfma_f32_16x16x32_bf16 v[54:57], v[170:173], v[188:191], v[54:57]
	v_mfma_f32_16x16x32_bf16 v[50:53], v[180:183], v[188:191], v[50:53]
	v_mfma_f32_16x16x32_bf16 v[38:41], v[170:173], v[196:199], v[38:41]
	v_mfma_f32_16x16x32_bf16 v[34:37], v[180:183], v[196:199], v[34:37]
	v_mfma_f32_16x16x32_bf16 v[22:25], v[170:173], v[204:207], v[22:25]
	v_mfma_f32_16x16x32_bf16 v[18:21], v[180:183], v[204:207], v[18:21]
	v_mfma_f32_16x16x32_bf16 v[6:9], v[170:173], v[212:215], v[6:9]
	v_mfma_f32_16x16x32_bf16 v[2:5], v[180:183], v[212:215], v[2:5]
	v_mfma_f32_16x16x32_bf16 v[54:57], v[176:179], v[192:195], v[54:57]
	v_mfma_f32_16x16x32_bf16 v[50:53], v[184:187], v[192:195], v[50:53]
	v_mfma_f32_16x16x32_bf16 v[38:41], v[176:179], v[200:203], v[38:41]
	v_mfma_f32_16x16x32_bf16 v[34:37], v[184:187], v[200:203], v[34:37]
	v_mfma_f32_16x16x32_bf16 v[22:25], v[176:179], v[208:211], v[22:25]
	v_mfma_f32_16x16x32_bf16 v[18:21], v[184:187], v[208:211], v[18:21]
	v_mfma_f32_16x16x32_bf16 v[6:9], v[176:179], v[220:223], v[6:9]
	v_mfma_f32_16x16x32_bf16 v[2:5], v[184:187], v[220:223], v[2:5]
	s_setprio 0
	s_barrier
	s_add_i32 s61, s61, 2
	s_add_u32 s38, s38, 0x100
	s_addc_u32 s39, s39, 0
	s_cmp_gt_u32 s61, 3
	s_mov_b64 s[20:21], s[22:23]
	s_cbranch_scc1 .Lpeel_exit_2

; #define PG8_BAR __builtin_amdgcn_s_barrier()
; template <class Epi, class Sched, bool ALIGN_EPI = false, bool SP2 = false>
; __device__ __forceinline__ void gemm_phase(PG8_LAS unsigned char* lds, const Gemm g, const Sched& S, const Epi& E) {
;     ...
;         if constexpr (ALIGN_EPI) { if (wr == 0) PG8_BAR; }
.Lpeel_exit_2:
	s_and_b64 vcc, exec, s[14:15]
	s_cbranch_vccz .LBB0_689
	s_barrier

; #define PG8_STAGE(bufoff, gbase, voff) do { _Pragma("unroll") for (int _i = 0; _i < 2; ++_i) \
;         __builtin_amdgcn_global_load_lds((const unsigned*)((const char*)(gbase) + (voff)[_i]), (PG8_LAS unsigned*)(lds + (bufoff) + ldsw + _i * 8192), 16, 0, 0); } while (0)
; #define PG8_LDA(dst, b, h) do { _Pragma("unroll") for (int m = 0; m < 4; ++m) _Pragma("unroll") for (int k = 0; k < 2; ++k) dst[m][k] = *(const PG8_LAS bf16x8*)(lds + PG8_SA(b, h) + aoff + m * 2048 + k * 1024); } while (0)
; #define PG8_LDB(dst, b, h) do { _Pragma("unroll") for (int n = 0; n < 2; ++n) _Pragma("unroll") for (int k = 0; k < 2; ++k) dst[n][k] = *(const PG8_LAS bf16x8*)(lds + PG8_SB(b, h) + boff + n * 2048 + k * 1024); } while (0)
; #define PG8_MMA(ai, bj, At, Bt) do { __builtin_amdgcn_s_setprio(1); _Pragma("unroll") for (int m = 0; m < 4; ++m) _Pragma("unroll") for (int n = 0; n < 2; ++n) _Pragma("unroll") for (int k = 0; k < 2; ++k) \
;         acc[ai][bj][m][n] = __builtin_amdgcn_mfma_f32_16x16x32_bf16(Bt[n][k], At[m][k], acc[ai][bj][m][n], 0, 0, 0); __builtin_amdgcn_s_setprio(0); } while (0)
; #define PG8_BAR __builtin_amdgcn_s_barrier()
; template <class Epi, class Sched, bool ALIGN_EPI = false, bool SP2 = false>
; __device__ __forceinline__ void gemm_phase(PG8_LAS unsigned char* lds, const Gemm g, const Sched& S, const Epi& E) {
;     ...
;             const char* a1 = cA + (size_t)(t + 1) * kstep;
;             const char* a2 = last ? nA : cA + (size_t)(t + 2) * kstep; const char* b2 = last ? nB : cB + (size_t)(t + 2) * kstep;
;             const char* a3 = a2 + kstep; const char* b3 = b2 + kstep;
;             if (last && has_next) S.a_ready(nxt);
;             if constexpr (SP2) {
;             PG8_LDB(B0, 0, 0); PG8_LDB(B1, 0, 1); PG8_SCHED; PG8_LDA(At, 0, 0); PG8_STAGE(PG8_SA(1, 1), a1 + hstepA, voffA);
;             PG8_WAIT_V(8); PG8_WAIT_L(0); PG8_BAR; PG8_MMA(0, 0, At, B0); PG8_MMA(0, 1, At, B1); PG8_BAR; PG8_SCHED;
;             PG8_LDA(At, 0, 1); PG8_STAGE(PG8_SB(0, 0), b2, voffB); PG8_STAGE(PG8_SB(0, 1), b2 + hstepB, voffB); PG8_STAGE(PG8_SA(0, 0), a2, voffA);
;     ...
; #pragma unroll
;         for (int a = 0; a < 2; ++a)
; #pragma unroll
;             for (int b = 0; b < 2; ++b)
; #pragma unroll
;                 for (int m = 0; m < 4; ++m)
; #pragma unroll
;                     for (int n = 0; n < 2; ++n) acc[a][b][m][n] = (f32x4){0.f, 0.f, 0.f, 0.f};
.LBB0_850:
	s_ashr_i32 s29, s28, 31
	s_lshl_b64 s[30:31], s[28:29], 18
	s_add_u32 s30, s47, s30
	s_addc_u32 s31, s48, s31
	s_and_b64 s[34:35], s[4:5], exec
	s_cselect_b32 s29, s31, s41
	s_cselect_b32 s38, s30, s40
	s_ashr_i32 s27, s26, 31
	s_lshl_b64 s[34:35], s[26:27], 18
	s_add_u32 s34, s49, s34
	s_addc_u32 s35, s50, s35
	s_and_b64 s[44:45], s[4:5], exec
	s_cselect_b32 s27, s35, s43
	s_cselect_b32 s39, s34, s42
	s_add_u32 s40, s40, 0x20080
	s_addc_u32 s41, s41, 0
	s_add_u32 s61, s42, 0x100
	s_addc_u32 s62, s43, 0
	s_mov_b32 s63, -2
	ds_read_b128 v[130:133], v166
	ds_read_b128 v[134:137], v166 offset:1024
	ds_read_b128 v[154:157], v166 offset:2048
	ds_read_b128 v[158:161], v166 offset:3072
	ds_read_b128 v[170:173], v167
	ds_read_b128 v[176:179], v167 offset:1024
	ds_read_b128 v[180:183], v167 offset:2048
	ds_read_b128 v[184:187], v167 offset:3072
	s_add_u32 s42, s40, 0xfffe0080
	s_addc_u32 s43, s41, -1
	s_cmp_eq_u32 s63, 4
	s_cselect_b32 s45, s29, s43
	s_cselect_b32 s44, s38, s42
	s_cselect_b32 s43, s27, s62
	s_cselect_b32 s42, s39, s61
	v_lshl_add_u64 v[162:163], s[40:41], 0, v[146:147]
	s_add_i32 m0, s37, 0xc000
	ds_read_b128 v[188:191], v168
	ds_read_b128 v[192:195], v168 offset:1024
	ds_read_b128 v[196:199], v168 offset:2048
	ds_read_b128 v[200:203], v168 offset:3072
	ds_read_b128 v[204:207], v168 offset:4096
	ds_read_b128 v[208:211], v168 offset:5120
	ds_read_b128 v[212:215], v168 offset:6144
	ds_read_b128 v[220:223], v168 offset:7168
	global_load_lds_dwordx4 v[162:163], off
	v_lshl_add_u64 v[162:163], s[40:41], 0, v[148:149]
	s_add_i32 m0, s37, 0xe000
	s_nop 0
	global_load_lds_dwordx4 v[162:163], off
	s_waitcnt vmcnt(8)
	s_waitcnt lgkmcnt(0)
	s_barrier
	s_setprio 1
	s_waitcnt lgkmcnt(0)
	v_mfma_f32_16x16x32_bf16 v[126:129], v[130:133], v[188:191], 0
	v_mfma_f32_16x16x32_bf16 v[122:125], v[154:157], v[188:191], 0
	v_mfma_f32_16x16x32_bf16 v[110:113], v[130:133], v[196:199], 0
	v_mfma_f32_16x16x32_bf16 v[106:109], v[154:157], v[196:199], 0
	v_mfma_f32_16x16x32_bf16 v[94:97], v[130:133], v[204:207], 0
	v_mfma_f32_16x16x32_bf16 v[90:93], v[154:157], v[204:207], 0
	v_mfma_f32_16x16x32_bf16 v[78:81], v[130:133], v[212:215], 0
	v_mfma_f32_16x16x32_bf16 v[74:77], v[154:157], v[212:215], 0
	v_mfma_f32_16x16x32_bf16 v[126:129], v[134:137], v[192:195], v[126:129]
	v_mfma_f32_16x16x32_bf16 v[122:125], v[158:161], v[192:195], v[122:125]
	v_mfma_f32_16x16x32_bf16 v[110:113], v[134:137], v[200:203], v[110:113]
	v_mfma_f32_16x16x32_bf16 v[106:109], v[158:161], v[200:203], v[106:109]
	v_mfma_f32_16x16x32_bf16 v[94:97], v[134:137], v[208:211], v[94:97]
	v_mfma_f32_16x16x32_bf16 v[90:93], v[158:161], v[208:211], v[90:93]
	v_mfma_f32_16x16x32_bf16 v[78:81], v[134:137], v[220:223], v[78:81]
	v_mfma_f32_16x16x32_bf16 v[74:77], v[158:161], v[220:223], v[74:77]
	s_setprio 0
	s_setprio 1
	v_mfma_f32_16x16x32_bf16 v[118:121], v[170:173], v[188:191], 0
	v_mfma_f32_16x16x32_bf16 v[114:117], v[180:183], v[188:191], 0
	v_mfma_f32_16x16x32_bf16 v[102:105], v[170:173], v[196:199], 0
	v_mfma_f32_16x16x32_bf16 v[98:101], v[180:183], v[196:199], 0
	v_mfma_f32_16x16x32_bf16 v[86:89], v[170:173], v[204:207], 0
	v_mfma_f32_16x16x32_bf16 v[82:85], v[180:183], v[204:207], 0
	v_mfma_f32_16x16x32_bf16 v[70:73], v[170:173], v[212:215], 0
	v_mfma_f32_16x16x32_bf16 v[66:69], v[180:183], v[212:215], 0
	v_mfma_f32_16x16x32_bf16 v[118:121], v[176:179], v[192:195], v[118:121]
	v_mfma_f32_16x16x32_bf16 v[114:117], v[184:187], v[192:195], v[114:117]
	v_mfma_f32_16x16x32_bf16 v[102:105], v[176:179], v[200:203], v[102:105]
	v_mfma_f32_16x16x32_bf16 v[98:101], v[184:187], v[200:203], v[98:101]
	v_mfma_f32_16x16x32_bf16 v[86:89], v[176:179], v[208:211], v[86:89]
	v_mfma_f32_16x16x32_bf16 v[82:85], v[184:187], v[208:211], v[82:85]
	v_mfma_f32_16x16x32_bf16 v[70:73], v[176:179], v[220:223], v[70:73]
	v_mfma_f32_16x16x32_bf16 v[66:69], v[184:187], v[220:223], v[66:69]
	s_setprio 0
	s_barrier
	s_add_i32 s64, s59, s51
	v_lshl_add_u64 v[162:163], s[42:43], 0, v[140:141]
	s_mov_b32 m0, s64
	ds_read_b128 v[188:191], v168 offset:16384
	ds_read_b128 v[192:195], v168 offset:17408
	ds_read_b128 v[196:199], v168 offset:18432
	ds_read_b128 v[200:203], v168 offset:19456
	ds_read_b128 v[204:207], v168 offset:20480
	ds_read_b128 v[208:211], v168 offset:21504
	ds_read_b128 v[212:215], v168 offset:22528
	ds_read_b128 v[220:223], v168 offset:23552
	global_load_lds_dwordx4 v[162:163], off
	s_add_i32 m0, s64, 0x2000
	s_add_u32 s64, s42, 0x20000
	v_lshl_add_u64 v[216:217], s[42:43], 0, v[144:145]
	s_addc_u32 s65, s43, 0
	s_add_i32 s66, s60, s51
	global_load_lds_dwordx4 v[216:217], off
	v_lshl_add_u64 v[224:225], s[64:65], 0, v[140:141]
	s_mov_b32 m0, s66
	v_lshl_add_u64 v[226:227], s[44:45], 0, v[142:143]
	global_load_lds_dwordx4 v[224:225], off
	v_lshl_add_u64 v[224:225], s[64:65], 0, v[144:145]
	s_add_i32 m0, s66, 0x2000
	s_nop 0
	global_load_lds_dwordx4 v[224:225], off
	v_lshl_add_u64 v[224:225], s[44:45], 0, v[138:139]
	s_mov_b32 m0, s37
	s_nop 0
	global_load_lds_dwordx4 v[224:225], off
	s_mov_b32 m0, s52
	s_nop 0
	global_load_lds_dwordx4 v[226:227], off
	s_waitcnt vmcnt(8)
	s_waitcnt lgkmcnt(0)
	s_barrier
; #define PG8_STAGE(bufoff, gbase, voff) do { _Pragma("unroll") for (int _i = 0; _i < 2; ++_i) \
;         __builtin_amdgcn_global_load_lds((const unsigned*)((const char*)(gbase) + (voff)[_i]), (PG8_LAS unsigned*)(lds + (bufoff) + ldsw + _i * 8192), 16, 0, 0); } while (0)
; #define PG8_LDA(dst, b, h) do { _Pragma("unroll") for (int m = 0; m < 4; ++m) _Pragma("unroll") for (int k = 0; k < 2; ++k) dst[m][k] = *(const PG8_LAS bf16x8*)(lds + PG8_SA(b, h) + aoff + m * 2048 + k * 1024); } while (0)
; #define PG8_LDB(dst, b, h) do { _Pragma("unroll") for (int n = 0; n < 2; ++n) _Pragma("unroll") for (int k = 0; k < 2; ++k) dst[n][k] = *(const PG8_LAS bf16x8*)(lds + PG8_SB(b, h) + boff + n * 2048 + k * 1024); } while (0)
; #define PG8_MMA(ai, bj, At, Bt) do { __builtin_amdgcn_s_setprio(1); _Pragma("unroll") for (int m = 0; m < 4; ++m) _Pragma("unroll") for (int n = 0; n < 2; ++n) _Pragma("unroll") for (int k = 0; k < 2; ++k) \
;         acc[ai][bj][m][n] = __builtin_amdgcn_mfma_f32_16x16x32_bf16(Bt[n][k], At[m][k], acc[ai][bj][m][n], 0, 0, 0); __builtin_amdgcn_s_setprio(0); } while (0)
; #define PG8_WAIT_V(n) asm volatile("s_waitcnt vmcnt(" #n ")" ::: "memory")
; #define PG8_WAIT_L(n) asm volatile("s_waitcnt lgkmcnt(" #n ")" ::: "memory")
; #define PG8_BAR __builtin_amdgcn_s_barrier()
; #define PG8_SCHED __builtin_amdgcn_sched_barrier(0)
; template <class Epi, class Sched, bool ALIGN_EPI = false, bool SP2 = false>
; __device__ __forceinline__ void gemm_phase(PG8_LAS unsigned char* lds, const Gemm g, const Sched& S, const Epi& E) {
;     ...
;             PG8_WAIT_V(8); PG8_WAIT_L(0); PG8_BAR; PG8_MMA(1, 0, At, B0); PG8_MMA(1, 1, At, B1); PG8_BAR; PG8_SCHED;
;             PG8_LDB(B0, 1, 0); PG8_LDB(B1, 1, 1); PG8_SCHED; PG8_LDA(At, 1, 0); PG8_STAGE(PG8_SA(0, 1), a2 + hstepA, voffA);
;             PG8_WAIT_V(8); PG8_WAIT_L(0); PG8_BAR; PG8_MMA(0, 0, At, B0); PG8_MMA(0, 1, At, B1); PG8_BAR; PG8_SCHED;
	s_setprio 1
	s_waitcnt lgkmcnt(0)
	v_mfma_f32_16x16x32_bf16 v[62:65], v[130:133], v[188:191], 0
	v_mfma_f32_16x16x32_bf16 v[58:61], v[154:157], v[188:191], 0
	v_mfma_f32_16x16x32_bf16 v[46:49], v[130:133], v[196:199], 0
	v_mfma_f32_16x16x32_bf16 v[42:45], v[154:157], v[196:199], 0
	v_mfma_f32_16x16x32_bf16 v[30:33], v[130:133], v[204:207], 0
	v_mfma_f32_16x16x32_bf16 v[26:29], v[154:157], v[204:207], 0
	v_mfma_f32_16x16x32_bf16 v[14:17], v[130:133], v[212:215], 0
	v_mfma_f32_16x16x32_bf16 v[10:13], v[154:157], v[212:215], 0
	v_mfma_f32_16x16x32_bf16 v[62:65], v[134:137], v[192:195], v[62:65]
	v_mfma_f32_16x16x32_bf16 v[58:61], v[158:161], v[192:195], v[58:61]
	v_mfma_f32_16x16x32_bf16 v[46:49], v[134:137], v[200:203], v[46:49]
	v_mfma_f32_16x16x32_bf16 v[42:45], v[158:161], v[200:203], v[42:45]
	v_mfma_f32_16x16x32_bf16 v[30:33], v[134:137], v[208:211], v[30:33]
	v_mfma_f32_16x16x32_bf16 v[26:29], v[158:161], v[208:211], v[26:29]
	v_mfma_f32_16x16x32_bf16 v[14:17], v[134:137], v[220:223], v[14:17]
	v_mfma_f32_16x16x32_bf16 v[10:13], v[158:161], v[220:223], v[10:13]
	s_setprio 0
	s_setprio 1
	v_mfma_f32_16x16x32_bf16 v[54:57], v[170:173], v[188:191], 0
	v_mfma_f32_16x16x32_bf16 v[50:53], v[180:183], v[188:191], 0
	v_mfma_f32_16x16x32_bf16 v[38:41], v[170:173], v[196:199], 0
	v_mfma_f32_16x16x32_bf16 v[34:37], v[180:183], v[196:199], 0
	v_mfma_f32_16x16x32_bf16 v[22:25], v[170:173], v[204:207], 0
	v_mfma_f32_16x16x32_bf16 v[18:21], v[180:183], v[204:207], 0
	v_mfma_f32_16x16x32_bf16 v[6:9], v[170:173], v[212:215], 0
	v_mfma_f32_16x16x32_bf16 v[2:5], v[180:183], v[212:215], 0
	v_mfma_f32_16x16x32_bf16 v[54:57], v[176:179], v[192:195], v[54:57]
	v_mfma_f32_16x16x32_bf16 v[50:53], v[184:187], v[192:195], v[50:53]
	v_mfma_f32_16x16x32_bf16 v[38:41], v[176:179], v[200:203], v[38:41]
	v_mfma_f32_16x16x32_bf16 v[34:37], v[184:187], v[200:203], v[34:37]
	v_mfma_f32_16x16x32_bf16 v[22:25], v[176:179], v[208:211], v[22:25]
	v_mfma_f32_16x16x32_bf16 v[18:21], v[184:187], v[208:211], v[18:21]
	v_mfma_f32_16x16x32_bf16 v[6:9], v[176:179], v[220:223], v[6:9]
	v_mfma_f32_16x16x32_bf16 v[2:5], v[184:187], v[220:223], v[2:5]
	s_setprio 0
	s_barrier
	s_add_i32 s64, 0, 0x18000
	s_add_i32 s65, 0, 0x1c000
	v_add_u32_e32 v158, s64, v164
	v_add_u32_e32 v169, s65, v164
	ds_read_b128 v[130:133], v158
	ds_read_b128 v[134:137], v158 offset:1024
	ds_read_b128 v[154:157], v158 offset:2048
	ds_read_b128 v[158:161], v158 offset:3072
	ds_read_b128 v[170:173], v169
	ds_read_b128 v[176:179], v169 offset:1024
	ds_read_b128 v[180:183], v169 offset:2048
	ds_read_b128 v[184:187], v169 offset:3072
	s_add_u32 s44, s44, 0x20000
	s_addc_u32 s45, s45, 0
	s_mov_b32 m0, s53
	v_lshl_add_u64 v[228:229], s[44:45], 0, v[138:139]
	ds_read_b128 v[188:191], v168 offset:32768
	ds_read_b128 v[192:195], v168 offset:33792
	ds_read_b128 v[196:199], v168 offset:34816
	ds_read_b128 v[200:203], v168 offset:35840
	ds_read_b128 v[204:207], v168 offset:36864
	ds_read_b128 v[208:211], v168 offset:37888
	ds_read_b128 v[212:215], v168 offset:38912
	ds_read_b128 v[220:223], v168 offset:39936
	global_load_lds_dwordx4 v[228:229], off
	v_lshl_add_u64 v[228:229], s[44:45], 0, v[142:143]
	s_mov_b32 m0, s54
	s_nop 0
	global_load_lds_dwordx4 v[228:229], off
	s_waitcnt vmcnt(8)
	s_waitcnt lgkmcnt(0)
	s_barrier
	s_setprio 1
	s_waitcnt lgkmcnt(0)
	v_mfma_f32_16x16x32_bf16 v[126:129], v[130:133], v[188:191], v[126:129]
	v_mfma_f32_16x16x32_bf16 v[122:125], v[154:157], v[188:191], v[122:125]
	v_mfma_f32_16x16x32_bf16 v[110:113], v[130:133], v[196:199], v[110:113]
	v_mfma_f32_16x16x32_bf16 v[106:109], v[154:157], v[196:199], v[106:109]
	v_mfma_f32_16x16x32_bf16 v[94:97], v[130:133], v[204:207], v[94:97]
	v_mfma_f32_16x16x32_bf16 v[90:93], v[154:157], v[204:207], v[90:93]
	v_mfma_f32_16x16x32_bf16 v[78:81], v[130:133], v[212:215], v[78:81]
	v_mfma_f32_16x16x32_bf16 v[74:77], v[154:157], v[212:215], v[74:77]
	v_mfma_f32_16x16x32_bf16 v[126:129], v[134:137], v[192:195], v[126:129]
	v_mfma_f32_16x16x32_bf16 v[122:125], v[158:161], v[192:195], v[122:125]
	v_mfma_f32_16x16x32_bf16 v[110:113], v[134:137], v[200:203], v[110:113]
	v_mfma_f32_16x16x32_bf16 v[106:109], v[158:161], v[200:203], v[106:109]
	v_mfma_f32_16x16x32_bf16 v[94:97], v[134:137], v[208:211], v[94:97]
	v_mfma_f32_16x16x32_bf16 v[90:93], v[158:161], v[208:211], v[90:93]
	v_mfma_f32_16x16x32_bf16 v[78:81], v[134:137], v[220:223], v[78:81]
	v_mfma_f32_16x16x32_bf16 v[74:77], v[158:161], v[220:223], v[74:77]
	s_setprio 0
	s_setprio 1
	v_mfma_f32_16x16x32_bf16 v[118:121], v[170:173], v[188:191], v[118:121]
	v_mfma_f32_16x16x32_bf16 v[114:117], v[180:183], v[188:191], v[114:117]
	v_mfma_f32_16x16x32_bf16 v[102:105], v[170:173], v[196:199], v[102:105]
	v_mfma_f32_16x16x32_bf16 v[98:101], v[180:183], v[196:199], v[98:101]
	v_mfma_f32_16x16x32_bf16 v[86:89], v[170:173], v[204:207], v[86:89]
	v_mfma_f32_16x16x32_bf16 v[82:85], v[180:183], v[204:207], v[82:85]
	v_mfma_f32_16x16x32_bf16 v[70:73], v[170:173], v[212:215], v[70:73]
	v_mfma_f32_16x16x32_bf16 v[66:69], v[180:183], v[212:215], v[66:69]
	v_mfma_f32_16x16x32_bf16 v[118:121], v[176:179], v[192:195], v[118:121]
	v_mfma_f32_16x16x32_bf16 v[114:117], v[184:187], v[192:195], v[114:117]
	v_mfma_f32_16x16x32_bf16 v[102:105], v[176:179], v[200:203], v[102:105]
	v_mfma_f32_16x16x32_bf16 v[98:101], v[184:187], v[200:203], v[98:101]
	v_mfma_f32_16x16x32_bf16 v[86:89], v[176:179], v[208:211], v[86:89]
	v_mfma_f32_16x16x32_bf16 v[82:85], v[184:187], v[208:211], v[82:85]
	v_mfma_f32_16x16x32_bf16 v[70:73], v[176:179], v[220:223], v[70:73]
	v_mfma_f32_16x16x32_bf16 v[66:69], v[184:187], v[220:223], v[66:69]
	s_setprio 0
	s_barrier
; #define PG8_STAGE(bufoff, gbase, voff) do { _Pragma("unroll") for (int _i = 0; _i < 2; ++_i) \
;         __builtin_amdgcn_global_load_lds((const unsigned*)((const char*)(gbase) + (voff)[_i]), (PG8_LAS unsigned*)(lds + (bufoff) + ldsw + _i * 8192), 16, 0, 0); } while (0)
; #define PG8_LDA(dst, b, h) do { _Pragma("unroll") for (int m = 0; m < 4; ++m) _Pragma("unroll") for (int k = 0; k < 2; ++k) dst[m][k] = *(const PG8_LAS bf16x8*)(lds + PG8_SA(b, h) + aoff + m * 2048 + k * 1024); } while (0)
; #define PG8_MMA(ai, bj, At, Bt) do { __builtin_amdgcn_s_setprio(1); _Pragma("unroll") for (int m = 0; m < 4; ++m) _Pragma("unroll") for (int n = 0; n < 2; ++n) _Pragma("unroll") for (int k = 0; k < 2; ++k) \
;         acc[ai][bj][m][n] = __builtin_amdgcn_mfma_f32_16x16x32_bf16(Bt[n][k], At[m][k], acc[ai][bj][m][n], 0, 0, 0); __builtin_amdgcn_s_setprio(0); } while (0)
; #define PG8_WAIT_V(n) asm volatile("s_waitcnt vmcnt(" #n ")" ::: "memory")
; #define PG8_WAIT_L(n) asm volatile("s_waitcnt lgkmcnt(" #n ")" ::: "memory")
; #define PG8_BAR __builtin_amdgcn_s_barrier()
; #define PG8_SCHED __builtin_amdgcn_sched_barrier(0)
; template <class Epi, class Sched, bool ALIGN_EPI = false, bool SP2 = false>
; __device__ __forceinline__ void gemm_phase(PG8_LAS unsigned char* lds, const Gemm g, const Sched& S, const Epi& E) {
;     ...
;         for (int t = 0; t < nt; t += 2) {
;     ...
;             PG8_LDA(At, 1, 1); PG8_STAGE(PG8_SB(1, 0), b3, voffB); PG8_STAGE(PG8_SB(1, 1), b3 + hstepB, voffB); PG8_STAGE(PG8_SA(1, 0), a3, voffA);
;             PG8_WAIT_V(8); PG8_WAIT_L(0); PG8_BAR; PG8_MMA(1, 0, At, B0); PG8_MMA(1, 1, At, B1); PG8_BAR; PG8_SCHED;
	s_add_i32 s44, s64, s51
	v_lshl_add_u64 v[162:163], v[162:163], 0, s[22:23]
	s_mov_b32 m0, s44
	ds_read_b128 v[188:191], v168 offset:49152
	ds_read_b128 v[192:195], v168 offset:50176
	ds_read_b128 v[196:199], v168 offset:51200
	ds_read_b128 v[200:203], v168 offset:52224
	ds_read_b128 v[204:207], v168 offset:53248
	ds_read_b128 v[208:211], v168 offset:54272
	ds_read_b128 v[212:215], v168 offset:55296
	ds_read_b128 v[220:223], v168 offset:56320
	global_load_lds_dwordx4 v[162:163], off
	s_add_i32 m0, s44, 0x2000
	s_add_u32 s42, s42, 0x20080
	v_lshl_add_u64 v[162:163], v[216:217], 0, s[22:23]
	s_addc_u32 s43, s43, 0
	s_add_i32 s44, s65, s51
	global_load_lds_dwordx4 v[162:163], off
	v_lshl_add_u64 v[162:163], s[42:43], 0, v[140:141]
	s_mov_b32 m0, s44
	s_nop 0
	global_load_lds_dwordx4 v[162:163], off
	v_lshl_add_u64 v[162:163], s[42:43], 0, v[144:145]
	s_add_i32 m0, s44, 0x2000
	s_nop 0
	global_load_lds_dwordx4 v[162:163], off
	v_lshl_add_u64 v[162:163], v[224:225], 0, s[22:23]
	s_mov_b32 m0, s56
	s_nop 0
	global_load_lds_dwordx4 v[162:163], off
	v_lshl_add_u64 v[162:163], v[226:227], 0, s[22:23]
	s_mov_b32 m0, s57
	s_nop 0
	global_load_lds_dwordx4 v[162:163], off
	s_waitcnt vmcnt(8)
	s_waitcnt lgkmcnt(0)
	s_barrier
	s_setprio 1
	s_waitcnt lgkmcnt(0)
	v_mfma_f32_16x16x32_bf16 v[62:65], v[130:133], v[188:191], v[62:65]
	v_mfma_f32_16x16x32_bf16 v[58:61], v[154:157], v[188:191], v[58:61]
	v_mfma_f32_16x16x32_bf16 v[46:49], v[130:133], v[196:199], v[46:49]
	v_mfma_f32_16x16x32_bf16 v[42:45], v[154:157], v[196:199], v[42:45]
	v_mfma_f32_16x16x32_bf16 v[30:33], v[130:133], v[204:207], v[30:33]
	v_mfma_f32_16x16x32_bf16 v[26:29], v[154:157], v[204:207], v[26:29]
	v_mfma_f32_16x16x32_bf16 v[14:17], v[130:133], v[212:215], v[14:17]
	v_mfma_f32_16x16x32_bf16 v[10:13], v[154:157], v[212:215], v[10:13]
	v_mfma_f32_16x16x32_bf16 v[62:65], v[134:137], v[192:195], v[62:65]
	v_mfma_f32_16x16x32_bf16 v[58:61], v[158:161], v[192:195], v[58:61]
	v_mfma_f32_16x16x32_bf16 v[46:49], v[134:137], v[200:203], v[46:49]
	v_mfma_f32_16x16x32_bf16 v[42:45], v[158:161], v[200:203], v[42:45]
	v_mfma_f32_16x16x32_bf16 v[30:33], v[134:137], v[208:211], v[30:33]
	v_mfma_f32_16x16x32_bf16 v[26:29], v[158:161], v[208:211], v[26:29]
	v_mfma_f32_16x16x32_bf16 v[14:17], v[134:137], v[220:223], v[14:17]
	v_mfma_f32_16x16x32_bf16 v[10:13], v[158:161], v[220:223], v[10:13]
	s_setprio 0
	s_setprio 1
	v_mfma_f32_16x16x32_bf16 v[54:57], v[170:173], v[188:191], v[54:57]
	v_mfma_f32_16x16x32_bf16 v[50:53], v[180:183], v[188:191], v[50:53]
	v_mfma_f32_16x16x32_bf16 v[38:41], v[170:173], v[196:199], v[38:41]
	v_mfma_f32_16x16x32_bf16 v[34:37], v[180:183], v[196:199], v[34:37]
	v_mfma_f32_16x16x32_bf16 v[22:25], v[170:173], v[204:207], v[22:25]
	v_mfma_f32_16x16x32_bf16 v[18:21], v[180:183], v[204:207], v[18:21]
	v_mfma_f32_16x16x32_bf16 v[6:9], v[170:173], v[212:215], v[6:9]
	v_mfma_f32_16x16x32_bf16 v[2:5], v[180:183], v[212:215], v[2:5]
	v_mfma_f32_16x16x32_bf16 v[54:57], v[176:179], v[192:195], v[54:57]
	v_mfma_f32_16x16x32_bf16 v[50:53], v[184:187], v[192:195], v[50:53]
	v_mfma_f32_16x16x32_bf16 v[38:41], v[176:179], v[200:203], v[38:41]
	v_mfma_f32_16x16x32_bf16 v[34:37], v[184:187], v[200:203], v[34:37]
	v_mfma_f32_16x16x32_bf16 v[22:25], v[176:179], v[208:211], v[22:25]
	v_mfma_f32_16x16x32_bf16 v[18:21], v[184:187], v[208:211], v[18:21]
	v_mfma_f32_16x16x32_bf16 v[6:9], v[176:179], v[220:223], v[6:9]
	v_mfma_f32_16x16x32_bf16 v[2:5], v[184:187], v[220:223], v[2:5]
	s_setprio 0
	s_barrier
	s_add_i32 s63, s63, 2
	s_add_u32 s40, s40, 0x100
	s_addc_u32 s41, s41, 0
	s_add_u32 s61, s61, 0x100
	s_addc_u32 s62, s62, 0
	s_cmp_gt_u32 s63, 5
	s_cbranch_scc1 .Lpeel_exit_3

; #define PG8_BAR __builtin_amdgcn_s_barrier()
; template <class Epi, class Sched, bool ALIGN_EPI = false, bool SP2 = false>
; __device__ __forceinline__ void gemm_phase(PG8_LAS unsigned char* lds, const Gemm g, const Sched& S, const Epi& E) {
;     ...
;         if constexpr (ALIGN_EPI) { if (wr == 0) PG8_BAR; }
.Lpeel_exit_3:
	s_and_b64 vcc, exec, s[24:25]
	s_cbranch_vccz .LBB0_854
	s_barrier

; #define PG8_STAGE(bufoff, gbase, voff) do { _Pragma("unroll") for (int _i = 0; _i < 2; ++_i) \
;         __builtin_amdgcn_global_load_lds((const unsigned*)((const char*)(gbase) + (voff)[_i]), (PG8_LAS unsigned*)(lds + (bufoff) + ldsw + _i * 8192), 16, 0, 0); } while (0)
; #define PG8_LDA(dst, b, h) do { _Pragma("unroll") for (int m = 0; m < 4; ++m) _Pragma("unroll") for (int k = 0; k < 2; ++k) dst[m][k] = *(const PG8_LAS bf16x8*)(lds + PG8_SA(b, h) + aoff + m * 2048 + k * 1024); } while (0)
; #define PG8_LDB(dst, b, h) do { _Pragma("unroll") for (int n = 0; n < 2; ++n) _Pragma("unroll") for (int k = 0; k < 2; ++k) dst[n][k] = *(const PG8_LAS bf16x8*)(lds + PG8_SB(b, h) + boff + n * 2048 + k * 1024); } while (0)
; #define PG8_MMA(ai, bj, At, Bt) do { __builtin_amdgcn_s_setprio(1); _Pragma("unroll") for (int m = 0; m < 4; ++m) _Pragma("unroll") for (int n = 0; n < 2; ++n) _Pragma("unroll") for (int k = 0; k < 2; ++k) \
;         acc[ai][bj][m][n] = __builtin_amdgcn_mfma_f32_16x16x32_bf16(Bt[n][k], At[m][k], acc[ai][bj][m][n], 0, 0, 0); __builtin_amdgcn_s_setprio(0); } while (0)
; #define PG8_BAR __builtin_amdgcn_s_barrier()
; template <class Epi, class Sched, bool ALIGN_EPI = false, bool SP2 = false>
; __device__ __forceinline__ void gemm_phase(PG8_LAS unsigned char* lds, const Gemm g, const Sched& S, const Epi& E) {
;     ...
;             const char* a1 = cA + (size_t)(t + 1) * kstep;
;             const char* a2 = last ? nA : cA + (size_t)(t + 2) * kstep; const char* b2 = last ? nB : cB + (size_t)(t + 2) * kstep;
;             const char* a3 = a2 + kstep; const char* b3 = b2 + kstep;
;             if (last && has_next) S.a_ready(nxt);
;             if constexpr (SP2) {
;             PG8_LDB(B0, 0, 0); PG8_LDB(B1, 0, 1); PG8_SCHED; PG8_LDA(At, 0, 0); PG8_STAGE(PG8_SA(1, 1), a1 + hstepA, voffA);
;             PG8_WAIT_V(8); PG8_WAIT_L(0); PG8_BAR; PG8_MMA(0, 0, At, B0); PG8_MMA(0, 1, At, B1); PG8_BAR; PG8_SCHED;
;             PG8_LDA(At, 0, 1); PG8_STAGE(PG8_SB(0, 0), b2, voffB); PG8_STAGE(PG8_SB(0, 1), b2 + hstepB, voffB); PG8_STAGE(PG8_SA(0, 0), a2, voffA);
;     ...
; #pragma unroll
;         for (int a = 0; a < 2; ++a)
; #pragma unroll
;             for (int b = 0; b < 2; ++b)
; #pragma unroll
;                 for (int m = 0; m < 4; ++m)
; #pragma unroll
;                     for (int n = 0; n < 2; ++n) acc[a][b][m][n] = (f32x4){0.f, 0.f, 0.f, 0.f};
.LBB0_874:
	s_ashr_i32 s25, s24, 31
	s_lshl_b64 s[26:27], s[24:25], 18
	s_add_u32 s26, s33, s26
	s_addc_u32 s27, s42, s27
	s_and_b64 s[28:29], s[4:5], exec
	s_cselect_b32 s25, s27, s35
	s_cselect_b32 s39, s26, s34
	s_ashr_i32 s23, s22, 31
	s_lshl_b64 s[28:29], s[22:23], 18
	s_add_u32 s28, s43, s28
	s_addc_u32 s29, s44, s29
	s_and_b64 s[40:41], s[4:5], exec
	s_cselect_b32 s23, s29, s37
	s_cselect_b32 s55, s28, s36
	s_add_u32 s34, s34, 0x20080
	s_addc_u32 s35, s35, 0
	s_add_u32 s56, s36, 0x100
	s_addc_u32 s57, s37, 0
	s_mov_b32 s58, -2
	ds_read_b128 v[146:149], v160
	ds_read_b128 v[150:153], v160 offset:1024
	ds_read_b128 v[154:157], v160 offset:2048
	ds_read_b128 v[164:167], v160 offset:3072
	ds_read_b128 v[168:171], v161
	ds_read_b128 v[176:179], v161 offset:1024
	ds_read_b128 v[180:183], v161 offset:2048
	ds_read_b128 v[184:187], v161 offset:3072
	s_add_u32 s36, s34, 0xfffe0080
	s_addc_u32 s37, s35, -1
	s_cmp_eq_u32 s58, 4
	s_cselect_b32 s41, s25, s37
	s_cselect_b32 s40, s39, s36
	s_cselect_b32 s37, s23, s57
	s_cselect_b32 s36, s55, s56
	v_lshl_add_u64 v[172:173], s[34:35], 0, v[138:139]
	s_add_i32 m0, s31, 0xc000
	ds_read_b128 v[188:191], v162
	ds_read_b128 v[192:195], v162 offset:1024
	ds_read_b128 v[196:199], v162 offset:2048
	ds_read_b128 v[200:203], v162 offset:3072
	ds_read_b128 v[204:207], v162 offset:4096
	ds_read_b128 v[208:211], v162 offset:5120
	ds_read_b128 v[212:215], v162 offset:6144
	ds_read_b128 v[220:223], v162 offset:7168
	global_load_lds_dwordx4 v[172:173], off
	v_lshl_add_u64 v[172:173], s[34:35], 0, v[140:141]
	s_add_i32 m0, s31, 0xe000
	s_nop 0
	global_load_lds_dwordx4 v[172:173], off
	s_waitcnt vmcnt(8)
	s_waitcnt lgkmcnt(0)
	s_barrier
	s_setprio 1
	s_waitcnt lgkmcnt(0)
	v_mfma_f32_16x16x32_bf16 v[126:129], v[146:149], v[188:191], 0
	v_mfma_f32_16x16x32_bf16 v[122:125], v[154:157], v[188:191], 0
	v_mfma_f32_16x16x32_bf16 v[110:113], v[146:149], v[196:199], 0
	v_mfma_f32_16x16x32_bf16 v[106:109], v[154:157], v[196:199], 0
	v_mfma_f32_16x16x32_bf16 v[94:97], v[146:149], v[204:207], 0
	v_mfma_f32_16x16x32_bf16 v[90:93], v[154:157], v[204:207], 0
	v_mfma_f32_16x16x32_bf16 v[78:81], v[146:149], v[212:215], 0
	v_mfma_f32_16x16x32_bf16 v[74:77], v[154:157], v[212:215], 0
	v_mfma_f32_16x16x32_bf16 v[126:129], v[150:153], v[192:195], v[126:129]
	v_mfma_f32_16x16x32_bf16 v[122:125], v[164:167], v[192:195], v[122:125]
	v_mfma_f32_16x16x32_bf16 v[110:113], v[150:153], v[200:203], v[110:113]
	v_mfma_f32_16x16x32_bf16 v[106:109], v[164:167], v[200:203], v[106:109]
	v_mfma_f32_16x16x32_bf16 v[94:97], v[150:153], v[208:211], v[94:97]
	v_mfma_f32_16x16x32_bf16 v[90:93], v[164:167], v[208:211], v[90:93]
	v_mfma_f32_16x16x32_bf16 v[78:81], v[150:153], v[220:223], v[78:81]
	v_mfma_f32_16x16x32_bf16 v[74:77], v[164:167], v[220:223], v[74:77]
	s_setprio 0
	s_setprio 1
	v_mfma_f32_16x16x32_bf16 v[118:121], v[168:171], v[188:191], 0
	v_mfma_f32_16x16x32_bf16 v[114:117], v[180:183], v[188:191], 0
	v_mfma_f32_16x16x32_bf16 v[102:105], v[168:171], v[196:199], 0
	v_mfma_f32_16x16x32_bf16 v[98:101], v[180:183], v[196:199], 0
	v_mfma_f32_16x16x32_bf16 v[86:89], v[168:171], v[204:207], 0
	v_mfma_f32_16x16x32_bf16 v[82:85], v[180:183], v[204:207], 0
	v_mfma_f32_16x16x32_bf16 v[70:73], v[168:171], v[212:215], 0
	v_mfma_f32_16x16x32_bf16 v[66:69], v[180:183], v[212:215], 0
	v_mfma_f32_16x16x32_bf16 v[118:121], v[176:179], v[192:195], v[118:121]
	v_mfma_f32_16x16x32_bf16 v[114:117], v[184:187], v[192:195], v[114:117]
	v_mfma_f32_16x16x32_bf16 v[102:105], v[176:179], v[200:203], v[102:105]
	v_mfma_f32_16x16x32_bf16 v[98:101], v[184:187], v[200:203], v[98:101]
	v_mfma_f32_16x16x32_bf16 v[86:89], v[176:179], v[208:211], v[86:89]
	v_mfma_f32_16x16x32_bf16 v[82:85], v[184:187], v[208:211], v[82:85]
	v_mfma_f32_16x16x32_bf16 v[70:73], v[176:179], v[220:223], v[70:73]
	v_mfma_f32_16x16x32_bf16 v[66:69], v[184:187], v[220:223], v[66:69]
	s_setprio 0
	s_barrier
	s_add_i32 s59, s53, s45
	v_lshl_add_u64 v[172:173], s[36:37], 0, v[132:133]
	s_mov_b32 m0, s59
	ds_read_b128 v[188:191], v162 offset:16384
	ds_read_b128 v[192:195], v162 offset:17408
	ds_read_b128 v[196:199], v162 offset:18432
	ds_read_b128 v[200:203], v162 offset:19456
	ds_read_b128 v[204:207], v162 offset:20480
	ds_read_b128 v[208:211], v162 offset:21504
	ds_read_b128 v[212:215], v162 offset:22528
	ds_read_b128 v[220:223], v162 offset:23552
	global_load_lds_dwordx4 v[172:173], off
	s_add_i32 m0, s59, 0x2000
	s_add_u32 s60, s36, 0x20000
	v_lshl_add_u64 v[216:217], s[36:37], 0, v[136:137]
	s_addc_u32 s61, s37, 0
	s_add_i32 s59, s54, s45
	global_load_lds_dwordx4 v[216:217], off
	v_lshl_add_u64 v[224:225], s[60:61], 0, v[132:133]
	s_mov_b32 m0, s59
	v_lshl_add_u64 v[226:227], s[40:41], 0, v[134:135]
	global_load_lds_dwordx4 v[224:225], off
	v_lshl_add_u64 v[224:225], s[60:61], 0, v[136:137]
	s_add_i32 m0, s59, 0x2000
	s_nop 0
	global_load_lds_dwordx4 v[224:225], off
	v_lshl_add_u64 v[224:225], s[40:41], 0, v[130:131]
	s_mov_b32 m0, s31
	s_nop 0
	global_load_lds_dwordx4 v[224:225], off
	s_mov_b32 m0, s46
	s_nop 0
	global_load_lds_dwordx4 v[226:227], off
	s_waitcnt vmcnt(8)
	s_waitcnt lgkmcnt(0)
	s_barrier
; #define PG8_STAGE(bufoff, gbase, voff) do { _Pragma("unroll") for (int _i = 0; _i < 2; ++_i) \
;         __builtin_amdgcn_global_load_lds((const unsigned*)((const char*)(gbase) + (voff)[_i]), (PG8_LAS unsigned*)(lds + (bufoff) + ldsw + _i * 8192), 16, 0, 0); } while (0)
; #define PG8_LDA(dst, b, h) do { _Pragma("unroll") for (int m = 0; m < 4; ++m) _Pragma("unroll") for (int k = 0; k < 2; ++k) dst[m][k] = *(const PG8_LAS bf16x8*)(lds + PG8_SA(b, h) + aoff + m * 2048 + k * 1024); } while (0)
; #define PG8_LDB(dst, b, h) do { _Pragma("unroll") for (int n = 0; n < 2; ++n) _Pragma("unroll") for (int k = 0; k < 2; ++k) dst[n][k] = *(const PG8_LAS bf16x8*)(lds + PG8_SB(b, h) + boff + n * 2048 + k * 1024); } while (0)
; #define PG8_MMA(ai, bj, At, Bt) do { __builtin_amdgcn_s_setprio(1); _Pragma("unroll") for (int m = 0; m < 4; ++m) _Pragma("unroll") for (int n = 0; n < 2; ++n) _Pragma("unroll") for (int k = 0; k < 2; ++k) \
;         acc[ai][bj][m][n] = __builtin_amdgcn_mfma_f32_16x16x32_bf16(Bt[n][k], At[m][k], acc[ai][bj][m][n], 0, 0, 0); __builtin_amdgcn_s_setprio(0); } while (0)
; #define PG8_WAIT_V(n) asm volatile("s_waitcnt vmcnt(" #n ")" ::: "memory")
; #define PG8_WAIT_L(n) asm volatile("s_waitcnt lgkmcnt(" #n ")" ::: "memory")
; #define PG8_BAR __builtin_amdgcn_s_barrier()
; #define PG8_SCHED __builtin_amdgcn_sched_barrier(0)
; template <class Epi, class Sched, bool ALIGN_EPI = false, bool SP2 = false>
; __device__ __forceinline__ void gemm_phase(PG8_LAS unsigned char* lds, const Gemm g, const Sched& S, const Epi& E) {
;     ...
;             PG8_WAIT_V(8); PG8_WAIT_L(0); PG8_BAR; PG8_MMA(1, 0, At, B0); PG8_MMA(1, 1, At, B1); PG8_BAR; PG8_SCHED;
;             PG8_LDB(B0, 1, 0); PG8_LDB(B1, 1, 1); PG8_SCHED; PG8_LDA(At, 1, 0); PG8_STAGE(PG8_SA(0, 1), a2 + hstepA, voffA);
;             PG8_WAIT_V(8); PG8_WAIT_L(0); PG8_BAR; PG8_MMA(0, 0, At, B0); PG8_MMA(0, 1, At, B1); PG8_BAR; PG8_SCHED;
	s_setprio 1
	s_waitcnt lgkmcnt(0)
	v_mfma_f32_16x16x32_bf16 v[62:65], v[146:149], v[188:191], 0
	v_mfma_f32_16x16x32_bf16 v[58:61], v[154:157], v[188:191], 0
	v_mfma_f32_16x16x32_bf16 v[46:49], v[146:149], v[196:199], 0
	v_mfma_f32_16x16x32_bf16 v[42:45], v[154:157], v[196:199], 0
	v_mfma_f32_16x16x32_bf16 v[30:33], v[146:149], v[204:207], 0
	v_mfma_f32_16x16x32_bf16 v[26:29], v[154:157], v[204:207], 0
	v_mfma_f32_16x16x32_bf16 v[14:17], v[146:149], v[212:215], 0
	v_mfma_f32_16x16x32_bf16 v[10:13], v[154:157], v[212:215], 0
	v_mfma_f32_16x16x32_bf16 v[62:65], v[150:153], v[192:195], v[62:65]
	v_mfma_f32_16x16x32_bf16 v[58:61], v[164:167], v[192:195], v[58:61]
	v_mfma_f32_16x16x32_bf16 v[46:49], v[150:153], v[200:203], v[46:49]
	v_mfma_f32_16x16x32_bf16 v[42:45], v[164:167], v[200:203], v[42:45]
	v_mfma_f32_16x16x32_bf16 v[30:33], v[150:153], v[208:211], v[30:33]
	v_mfma_f32_16x16x32_bf16 v[26:29], v[164:167], v[208:211], v[26:29]
	v_mfma_f32_16x16x32_bf16 v[14:17], v[150:153], v[220:223], v[14:17]
	v_mfma_f32_16x16x32_bf16 v[10:13], v[164:167], v[220:223], v[10:13]
	s_setprio 0
	s_setprio 1
	v_mfma_f32_16x16x32_bf16 v[54:57], v[168:171], v[188:191], 0
	v_mfma_f32_16x16x32_bf16 v[50:53], v[180:183], v[188:191], 0
	v_mfma_f32_16x16x32_bf16 v[38:41], v[168:171], v[196:199], 0
	v_mfma_f32_16x16x32_bf16 v[34:37], v[180:183], v[196:199], 0
	v_mfma_f32_16x16x32_bf16 v[22:25], v[168:171], v[204:207], 0
	v_mfma_f32_16x16x32_bf16 v[18:21], v[180:183], v[204:207], 0
	v_mfma_f32_16x16x32_bf16 v[6:9], v[168:171], v[212:215], 0
	v_mfma_f32_16x16x32_bf16 v[2:5], v[180:183], v[212:215], 0
	v_mfma_f32_16x16x32_bf16 v[54:57], v[176:179], v[192:195], v[54:57]
	v_mfma_f32_16x16x32_bf16 v[50:53], v[184:187], v[192:195], v[50:53]
	v_mfma_f32_16x16x32_bf16 v[38:41], v[176:179], v[200:203], v[38:41]
	v_mfma_f32_16x16x32_bf16 v[34:37], v[184:187], v[200:203], v[34:37]
	v_mfma_f32_16x16x32_bf16 v[22:25], v[176:179], v[208:211], v[22:25]
	v_mfma_f32_16x16x32_bf16 v[18:21], v[184:187], v[208:211], v[18:21]
	v_mfma_f32_16x16x32_bf16 v[6:9], v[176:179], v[220:223], v[6:9]
	v_mfma_f32_16x16x32_bf16 v[2:5], v[184:187], v[220:223], v[2:5]
	s_setprio 0
	s_barrier
	s_add_i32 s59, 0, 0x18000
	v_add_u32_e32 v163, s59, v158
	s_add_i32 s60, 0, 0x1c000
	ds_read_b128 v[146:149], v163
	ds_read_b128 v[150:153], v163 offset:1024
	ds_read_b128 v[154:157], v163 offset:2048
	ds_read_b128 v[164:167], v163 offset:3072
	v_add_u32_e32 v163, s60, v158
	ds_read_b128 v[168:171], v163
	ds_read_b128 v[176:179], v163 offset:1024
	ds_read_b128 v[180:183], v163 offset:2048
	ds_read_b128 v[184:187], v163 offset:3072
	s_add_u32 s40, s40, 0x20000
	s_addc_u32 s41, s41, 0
	s_mov_b32 m0, s47
	v_lshl_add_u64 v[228:229], s[40:41], 0, v[130:131]
	ds_read_b128 v[188:191], v162 offset:32768
	ds_read_b128 v[192:195], v162 offset:33792
	ds_read_b128 v[196:199], v162 offset:34816
	ds_read_b128 v[200:203], v162 offset:35840
	ds_read_b128 v[204:207], v162 offset:36864
	ds_read_b128 v[208:211], v162 offset:37888
	ds_read_b128 v[212:215], v162 offset:38912
	ds_read_b128 v[220:223], v162 offset:39936
	global_load_lds_dwordx4 v[228:229], off
	v_lshl_add_u64 v[228:229], s[40:41], 0, v[134:135]
	s_mov_b32 m0, s48
	s_nop 0
	global_load_lds_dwordx4 v[228:229], off
	s_waitcnt vmcnt(8)
	s_waitcnt lgkmcnt(0)
	s_barrier
	s_setprio 1
	s_waitcnt lgkmcnt(0)
	v_mfma_f32_16x16x32_bf16 v[126:129], v[146:149], v[188:191], v[126:129]
	v_mfma_f32_16x16x32_bf16 v[122:125], v[154:157], v[188:191], v[122:125]
	v_mfma_f32_16x16x32_bf16 v[110:113], v[146:149], v[196:199], v[110:113]
	v_mfma_f32_16x16x32_bf16 v[106:109], v[154:157], v[196:199], v[106:109]
	v_mfma_f32_16x16x32_bf16 v[94:97], v[146:149], v[204:207], v[94:97]
	v_mfma_f32_16x16x32_bf16 v[90:93], v[154:157], v[204:207], v[90:93]
	v_mfma_f32_16x16x32_bf16 v[78:81], v[146:149], v[212:215], v[78:81]
	v_mfma_f32_16x16x32_bf16 v[74:77], v[154:157], v[212:215], v[74:77]
	v_mfma_f32_16x16x32_bf16 v[126:129], v[150:153], v[192:195], v[126:129]
	v_mfma_f32_16x16x32_bf16 v[122:125], v[164:167], v[192:195], v[122:125]
	v_mfma_f32_16x16x32_bf16 v[110:113], v[150:153], v[200:203], v[110:113]
	v_mfma_f32_16x16x32_bf16 v[106:109], v[164:167], v[200:203], v[106:109]
	v_mfma_f32_16x16x32_bf16 v[94:97], v[150:153], v[208:211], v[94:97]
	v_mfma_f32_16x16x32_bf16 v[90:93], v[164:167], v[208:211], v[90:93]
	v_mfma_f32_16x16x32_bf16 v[78:81], v[150:153], v[220:223], v[78:81]
	v_mfma_f32_16x16x32_bf16 v[74:77], v[164:167], v[220:223], v[74:77]
	s_setprio 0
	s_setprio 1
	v_mfma_f32_16x16x32_bf16 v[118:121], v[168:171], v[188:191], v[118:121]
	v_mfma_f32_16x16x32_bf16 v[114:117], v[180:183], v[188:191], v[114:117]
	v_mfma_f32_16x16x32_bf16 v[102:105], v[168:171], v[196:199], v[102:105]
	v_mfma_f32_16x16x32_bf16 v[98:101], v[180:183], v[196:199], v[98:101]
	v_mfma_f32_16x16x32_bf16 v[86:89], v[168:171], v[204:207], v[86:89]
	v_mfma_f32_16x16x32_bf16 v[82:85], v[180:183], v[204:207], v[82:85]
	v_mfma_f32_16x16x32_bf16 v[70:73], v[168:171], v[212:215], v[70:73]
	v_mfma_f32_16x16x32_bf16 v[66:69], v[180:183], v[212:215], v[66:69]
	v_mfma_f32_16x16x32_bf16 v[118:121], v[176:179], v[192:195], v[118:121]
	v_mfma_f32_16x16x32_bf16 v[114:117], v[184:187], v[192:195], v[114:117]
	v_mfma_f32_16x16x32_bf16 v[102:105], v[176:179], v[200:203], v[102:105]
	v_mfma_f32_16x16x32_bf16 v[98:101], v[184:187], v[200:203], v[98:101]
	v_mfma_f32_16x16x32_bf16 v[86:89], v[176:179], v[208:211], v[86:89]
	v_mfma_f32_16x16x32_bf16 v[82:85], v[184:187], v[208:211], v[82:85]
	v_mfma_f32_16x16x32_bf16 v[70:73], v[176:179], v[220:223], v[70:73]
	v_mfma_f32_16x16x32_bf16 v[66:69], v[184:187], v[220:223], v[66:69]
	s_setprio 0
	s_barrier
; #define PG8_STAGE(bufoff, gbase, voff) do { _Pragma("unroll") for (int _i = 0; _i < 2; ++_i) \
;         __builtin_amdgcn_global_load_lds((const unsigned*)((const char*)(gbase) + (voff)[_i]), (PG8_LAS unsigned*)(lds + (bufoff) + ldsw + _i * 8192), 16, 0, 0); } while (0)
; #define PG8_LDA(dst, b, h) do { _Pragma("unroll") for (int m = 0; m < 4; ++m) _Pragma("unroll") for (int k = 0; k < 2; ++k) dst[m][k] = *(const PG8_LAS bf16x8*)(lds + PG8_SA(b, h) + aoff + m * 2048 + k * 1024); } while (0)
; #define PG8_MMA(ai, bj, At, Bt) do { __builtin_amdgcn_s_setprio(1); _Pragma("unroll") for (int m = 0; m < 4; ++m) _Pragma("unroll") for (int n = 0; n < 2; ++n) _Pragma("unroll") for (int k = 0; k < 2; ++k) \
;         acc[ai][bj][m][n] = __builtin_amdgcn_mfma_f32_16x16x32_bf16(Bt[n][k], At[m][k], acc[ai][bj][m][n], 0, 0, 0); __builtin_amdgcn_s_setprio(0); } while (0)
; #define PG8_WAIT_V(n) asm volatile("s_waitcnt vmcnt(" #n ")" ::: "memory")
; #define PG8_WAIT_L(n) asm volatile("s_waitcnt lgkmcnt(" #n ")" ::: "memory")
; #define PG8_BAR __builtin_amdgcn_s_barrier()
; #define PG8_SCHED __builtin_amdgcn_sched_barrier(0)
; template <class Epi, class Sched, bool ALIGN_EPI = false, bool SP2 = false>
; __device__ __forceinline__ void gemm_phase(PG8_LAS unsigned char* lds, const Gemm g, const Sched& S, const Epi& E) {
;     ...
;         for (int t = 0; t < nt; t += 2) {
;     ...
;             PG8_LDA(At, 1, 1); PG8_STAGE(PG8_SB(1, 0), b3, voffB); PG8_STAGE(PG8_SB(1, 1), b3 + hstepB, voffB); PG8_STAGE(PG8_SA(1, 0), a3, voffA);
;             PG8_WAIT_V(8); PG8_WAIT_L(0); PG8_BAR; PG8_MMA(1, 0, At, B0); PG8_MMA(1, 1, At, B1); PG8_BAR; PG8_SCHED;
	s_add_i32 s40, s59, s45
	v_lshl_add_u64 v[172:173], v[172:173], 0, s[14:15]
	s_mov_b32 m0, s40
	ds_read_b128 v[188:191], v162 offset:49152
	ds_read_b128 v[192:195], v162 offset:50176
	ds_read_b128 v[196:199], v162 offset:51200
	ds_read_b128 v[200:203], v162 offset:52224
	ds_read_b128 v[204:207], v162 offset:53248
	ds_read_b128 v[208:211], v162 offset:54272
	ds_read_b128 v[212:215], v162 offset:55296
	ds_read_b128 v[220:223], v162 offset:56320
	global_load_lds_dwordx4 v[172:173], off
	s_add_i32 m0, s40, 0x2000
	s_add_u32 s36, s36, 0x20080
	v_lshl_add_u64 v[172:173], v[216:217], 0, s[14:15]
	s_addc_u32 s37, s37, 0
	s_add_i32 s40, s60, s45
	global_load_lds_dwordx4 v[172:173], off
	v_lshl_add_u64 v[172:173], s[36:37], 0, v[132:133]
	s_mov_b32 m0, s40
	s_nop 0
	global_load_lds_dwordx4 v[172:173], off
	v_lshl_add_u64 v[172:173], s[36:37], 0, v[136:137]
	s_add_i32 m0, s40, 0x2000
	s_nop 0
	global_load_lds_dwordx4 v[172:173], off
	v_lshl_add_u64 v[172:173], v[224:225], 0, s[14:15]
	s_mov_b32 m0, s50
	s_nop 0
	global_load_lds_dwordx4 v[172:173], off
	v_lshl_add_u64 v[172:173], v[226:227], 0, s[14:15]
	s_mov_b32 m0, s51
	s_nop 0
	global_load_lds_dwordx4 v[172:173], off
	s_waitcnt vmcnt(8)
	s_waitcnt lgkmcnt(0)
	s_barrier
	s_setprio 1
	s_waitcnt lgkmcnt(0)
	v_mfma_f32_16x16x32_bf16 v[62:65], v[146:149], v[188:191], v[62:65]
	v_mfma_f32_16x16x32_bf16 v[58:61], v[154:157], v[188:191], v[58:61]
	v_mfma_f32_16x16x32_bf16 v[46:49], v[146:149], v[196:199], v[46:49]
	v_mfma_f32_16x16x32_bf16 v[42:45], v[154:157], v[196:199], v[42:45]
	v_mfma_f32_16x16x32_bf16 v[30:33], v[146:149], v[204:207], v[30:33]
	v_mfma_f32_16x16x32_bf16 v[26:29], v[154:157], v[204:207], v[26:29]
	v_mfma_f32_16x16x32_bf16 v[14:17], v[146:149], v[212:215], v[14:17]
	v_mfma_f32_16x16x32_bf16 v[10:13], v[154:157], v[212:215], v[10:13]
	v_mfma_f32_16x16x32_bf16 v[62:65], v[150:153], v[192:195], v[62:65]
	v_mfma_f32_16x16x32_bf16 v[58:61], v[164:167], v[192:195], v[58:61]
	v_mfma_f32_16x16x32_bf16 v[46:49], v[150:153], v[200:203], v[46:49]
	v_mfma_f32_16x16x32_bf16 v[42:45], v[164:167], v[200:203], v[42:45]
	v_mfma_f32_16x16x32_bf16 v[30:33], v[150:153], v[208:211], v[30:33]
	v_mfma_f32_16x16x32_bf16 v[26:29], v[164:167], v[208:211], v[26:29]
	v_mfma_f32_16x16x32_bf16 v[14:17], v[150:153], v[220:223], v[14:17]
	v_mfma_f32_16x16x32_bf16 v[10:13], v[164:167], v[220:223], v[10:13]
	s_setprio 0
	s_setprio 1
	v_mfma_f32_16x16x32_bf16 v[54:57], v[168:171], v[188:191], v[54:57]
	v_mfma_f32_16x16x32_bf16 v[50:53], v[180:183], v[188:191], v[50:53]
	v_mfma_f32_16x16x32_bf16 v[38:41], v[168:171], v[196:199], v[38:41]
	v_mfma_f32_16x16x32_bf16 v[34:37], v[180:183], v[196:199], v[34:37]
	v_mfma_f32_16x16x32_bf16 v[22:25], v[168:171], v[204:207], v[22:25]
	v_mfma_f32_16x16x32_bf16 v[18:21], v[180:183], v[204:207], v[18:21]
	v_mfma_f32_16x16x32_bf16 v[6:9], v[168:171], v[212:215], v[6:9]
	v_mfma_f32_16x16x32_bf16 v[2:5], v[180:183], v[212:215], v[2:5]
	v_mfma_f32_16x16x32_bf16 v[54:57], v[176:179], v[192:195], v[54:57]
	v_mfma_f32_16x16x32_bf16 v[50:53], v[184:187], v[192:195], v[50:53]
	v_mfma_f32_16x16x32_bf16 v[38:41], v[176:179], v[200:203], v[38:41]
	v_mfma_f32_16x16x32_bf16 v[34:37], v[184:187], v[200:203], v[34:37]
	v_mfma_f32_16x16x32_bf16 v[22:25], v[176:179], v[208:211], v[22:25]
	v_mfma_f32_16x16x32_bf16 v[18:21], v[184:187], v[208:211], v[18:21]
	v_mfma_f32_16x16x32_bf16 v[6:9], v[176:179], v[220:223], v[6:9]
	v_mfma_f32_16x16x32_bf16 v[2:5], v[184:187], v[220:223], v[2:5]
	s_setprio 0
	s_barrier
	s_add_i32 s58, s58, 2
	s_add_u32 s34, s34, 0x100
	s_addc_u32 s35, s35, 0
	s_add_u32 s56, s56, 0x100
	s_addc_u32 s57, s57, 0
	s_cmp_gt_u32 s58, 5
	s_cbranch_scc1 .Lpeel_exit_4

; #define PG8_BAR __builtin_amdgcn_s_barrier()
; template <class Epi, class Sched, bool ALIGN_EPI = false, bool SP2 = false>
; __device__ __forceinline__ void gemm_phase(PG8_LAS unsigned char* lds, const Gemm g, const Sched& S, const Epi& E) {
;     ...
;         if constexpr (ALIGN_EPI) { if (wr == 0) PG8_BAR; }
.Lpeel_exit_4:
	s_and_b64 vcc, exec, s[16:17]
	s_cbranch_vccz .LBB0_878
	s_barrier

; #define PG8_STAGE(bufoff, gbase, voff) do { _Pragma("unroll") for (int _i = 0; _i < 2; ++_i) \
;         __builtin_amdgcn_global_load_lds((const unsigned*)((const char*)(gbase) + (voff)[_i]), (PG8_LAS unsigned*)(lds + (bufoff) + ldsw + _i * 8192), 16, 0, 0); } while (0)
; #define PG8_LDA(dst, b, h) do { _Pragma("unroll") for (int m = 0; m < 4; ++m) _Pragma("unroll") for (int k = 0; k < 2; ++k) dst[m][k] = *(const PG8_LAS bf16x8*)(lds + PG8_SA(b, h) + aoff + m * 2048 + k * 1024); } while (0)
; #define PG8_LDB(dst, b, h) do { _Pragma("unroll") for (int n = 0; n < 2; ++n) _Pragma("unroll") for (int k = 0; k < 2; ++k) dst[n][k] = *(const PG8_LAS bf16x8*)(lds + PG8_SB(b, h) + boff + n * 2048 + k * 1024); } while (0)
; #define PG8_MMA(ai, bj, At, Bt) do { __builtin_amdgcn_s_setprio(1); _Pragma("unroll") for (int m = 0; m < 4; ++m) _Pragma("unroll") for (int n = 0; n < 2; ++n) _Pragma("unroll") for (int k = 0; k < 2; ++k) \
;         acc[ai][bj][m][n] = __builtin_amdgcn_mfma_f32_16x16x32_bf16(Bt[n][k], At[m][k], acc[ai][bj][m][n], 0, 0, 0); __builtin_amdgcn_s_setprio(0); } while (0)
; #define PG8_BAR __builtin_amdgcn_s_barrier()
; template <class Epi, class Sched, bool ALIGN_EPI = false, bool SP2 = false>
; __device__ __forceinline__ void gemm_phase(PG8_LAS unsigned char* lds, const Gemm g, const Sched& S, const Epi& E) {
;     ...
;             const char* a1 = cA + (size_t)(t + 1) * kstep;
;             const char* a2 = last ? nA : cA + (size_t)(t + 2) * kstep; const char* b2 = last ? nB : cB + (size_t)(t + 2) * kstep;
;             const char* a3 = a2 + kstep; const char* b3 = b2 + kstep;
;             if (last && has_next) S.a_ready(nxt);
;             if constexpr (SP2) {
;             PG8_LDB(B0, 0, 0); PG8_LDB(B1, 0, 1); PG8_SCHED; PG8_LDA(At, 0, 0); PG8_STAGE(PG8_SA(1, 1), a1 + hstepA, voffA);
;             PG8_WAIT_V(8); PG8_WAIT_L(0); PG8_BAR; PG8_MMA(0, 0, At, B0); PG8_MMA(0, 1, At, B1); PG8_BAR; PG8_SCHED;
;             PG8_LDA(At, 0, 1); PG8_STAGE(PG8_SB(0, 0), b2, voffB); PG8_STAGE(PG8_SB(0, 1), b2 + hstepB, voffB); PG8_STAGE(PG8_SA(0, 0), a2, voffA);
;     ...
; #pragma unroll
;         for (int a = 0; a < 2; ++a)
; #pragma unroll
;             for (int b = 0; b < 2; ++b)
; #pragma unroll
;                 for (int m = 0; m < 4; ++m)
; #pragma unroll
;                     for (int n = 0; n < 2; ++n) acc[a][b][m][n] = (f32x4){0.f, 0.f, 0.f, 0.f};
.LBB0_975:
	s_ashr_i32 s27, s26, 31
	s_lshl_b64 s[28:29], s[26:27], 18
	s_add_u32 s28, s33, s28
	s_addc_u32 s29, s44, s29
	s_and_b64 s[30:31], s[4:5], exec
	s_cselect_b32 s27, s29, s37
	s_cselect_b32 s39, s28, s36
	s_ashr_i32 s25, s24, 31
	s_lshl_b64 s[30:31], s[24:25], 18
	s_add_u32 s30, s45, s30
	s_addc_u32 s31, s46, s31
	s_and_b64 s[42:43], s[4:5], exec
	s_cselect_b32 s25, s31, s41
	s_cselect_b32 s57, s30, s40
	s_add_u32 s36, s36, 0x20080
	s_addc_u32 s37, s37, 0
	s_add_u32 s58, s40, 0x100
	s_addc_u32 s59, s41, 0
	s_mov_b32 s60, -2
	ds_read_b128 v[146:149], v156
	ds_read_b128 v[150:153], v156 offset:1024
	ds_read_b128 v[160:163], v156 offset:2048
	ds_read_b128 v[164:167], v156 offset:3072
	ds_read_b128 v[168:171], v157
	ds_read_b128 v[176:179], v157 offset:1024
	ds_read_b128 v[180:183], v157 offset:2048
	ds_read_b128 v[184:187], v157 offset:3072
	s_add_u32 s40, s36, 0xfffe0080
	s_addc_u32 s41, s37, -1
	s_cmp_eq_u32 s60, 4
	s_cselect_b32 s43, s27, s41
	s_cselect_b32 s42, s39, s40
	s_cselect_b32 s41, s25, s59
	s_cselect_b32 s40, s57, s58
	v_lshl_add_u64 v[172:173], s[36:37], 0, v[138:139]
	s_add_i32 m0, s35, 0xc000
	ds_read_b128 v[188:191], v158
	ds_read_b128 v[192:195], v158 offset:1024
	ds_read_b128 v[196:199], v158 offset:2048
	ds_read_b128 v[200:203], v158 offset:3072
	ds_read_b128 v[204:207], v158 offset:4096
	ds_read_b128 v[208:211], v158 offset:5120
	ds_read_b128 v[212:215], v158 offset:6144
	ds_read_b128 v[220:223], v158 offset:7168
	global_load_lds_dwordx4 v[172:173], off
	v_lshl_add_u64 v[172:173], s[36:37], 0, v[140:141]
	s_add_i32 m0, s35, 0xe000
	s_nop 0
	global_load_lds_dwordx4 v[172:173], off
	s_waitcnt vmcnt(8)
	s_waitcnt lgkmcnt(0)
	s_barrier
	s_setprio 1
	s_waitcnt lgkmcnt(0)
	v_mfma_f32_16x16x32_bf16 v[126:129], v[146:149], v[188:191], 0
	v_mfma_f32_16x16x32_bf16 v[122:125], v[160:163], v[188:191], 0
	v_mfma_f32_16x16x32_bf16 v[110:113], v[146:149], v[196:199], 0
	v_mfma_f32_16x16x32_bf16 v[106:109], v[160:163], v[196:199], 0
	v_mfma_f32_16x16x32_bf16 v[94:97], v[146:149], v[204:207], 0
	v_mfma_f32_16x16x32_bf16 v[90:93], v[160:163], v[204:207], 0
	v_mfma_f32_16x16x32_bf16 v[78:81], v[146:149], v[212:215], 0
	v_mfma_f32_16x16x32_bf16 v[74:77], v[160:163], v[212:215], 0
	v_mfma_f32_16x16x32_bf16 v[126:129], v[150:153], v[192:195], v[126:129]
	v_mfma_f32_16x16x32_bf16 v[122:125], v[164:167], v[192:195], v[122:125]
	v_mfma_f32_16x16x32_bf16 v[110:113], v[150:153], v[200:203], v[110:113]
	v_mfma_f32_16x16x32_bf16 v[106:109], v[164:167], v[200:203], v[106:109]
	v_mfma_f32_16x16x32_bf16 v[94:97], v[150:153], v[208:211], v[94:97]
	v_mfma_f32_16x16x32_bf16 v[90:93], v[164:167], v[208:211], v[90:93]
	v_mfma_f32_16x16x32_bf16 v[78:81], v[150:153], v[220:223], v[78:81]
	v_mfma_f32_16x16x32_bf16 v[74:77], v[164:167], v[220:223], v[74:77]
	s_setprio 0
	s_setprio 1
	v_mfma_f32_16x16x32_bf16 v[118:121], v[168:171], v[188:191], 0
	v_mfma_f32_16x16x32_bf16 v[114:117], v[180:183], v[188:191], 0
	v_mfma_f32_16x16x32_bf16 v[102:105], v[168:171], v[196:199], 0
	v_mfma_f32_16x16x32_bf16 v[98:101], v[180:183], v[196:199], 0
	v_mfma_f32_16x16x32_bf16 v[86:89], v[168:171], v[204:207], 0
	v_mfma_f32_16x16x32_bf16 v[82:85], v[180:183], v[204:207], 0
	v_mfma_f32_16x16x32_bf16 v[70:73], v[168:171], v[212:215], 0
	v_mfma_f32_16x16x32_bf16 v[66:69], v[180:183], v[212:215], 0
	v_mfma_f32_16x16x32_bf16 v[118:121], v[176:179], v[192:195], v[118:121]
	v_mfma_f32_16x16x32_bf16 v[114:117], v[184:187], v[192:195], v[114:117]
	v_mfma_f32_16x16x32_bf16 v[102:105], v[176:179], v[200:203], v[102:105]
	v_mfma_f32_16x16x32_bf16 v[98:101], v[184:187], v[200:203], v[98:101]
	v_mfma_f32_16x16x32_bf16 v[86:89], v[176:179], v[208:211], v[86:89]
	v_mfma_f32_16x16x32_bf16 v[82:85], v[184:187], v[208:211], v[82:85]
	v_mfma_f32_16x16x32_bf16 v[70:73], v[176:179], v[220:223], v[70:73]
	v_mfma_f32_16x16x32_bf16 v[66:69], v[184:187], v[220:223], v[66:69]
	s_setprio 0
	s_barrier
	s_add_i32 s61, s55, s47
	v_lshl_add_u64 v[172:173], s[40:41], 0, v[132:133]
	s_mov_b32 m0, s61
	ds_read_b128 v[188:191], v158 offset:16384
	ds_read_b128 v[192:195], v158 offset:17408
	ds_read_b128 v[196:199], v158 offset:18432
	ds_read_b128 v[200:203], v158 offset:19456
	ds_read_b128 v[204:207], v158 offset:20480
	ds_read_b128 v[208:211], v158 offset:21504
	ds_read_b128 v[212:215], v158 offset:22528
	ds_read_b128 v[220:223], v158 offset:23552
	global_load_lds_dwordx4 v[172:173], off
	s_add_i32 m0, s61, 0x2000
	s_add_u32 s62, s40, 0x20000
	v_lshl_add_u64 v[216:217], s[40:41], 0, v[136:137]
	s_addc_u32 s63, s41, 0
	s_add_i32 s61, s56, s47
	global_load_lds_dwordx4 v[216:217], off
	v_lshl_add_u64 v[224:225], s[62:63], 0, v[132:133]
	s_mov_b32 m0, s61
	v_lshl_add_u64 v[226:227], s[42:43], 0, v[134:135]
	global_load_lds_dwordx4 v[224:225], off
	v_lshl_add_u64 v[224:225], s[62:63], 0, v[136:137]
	s_add_i32 m0, s61, 0x2000
	s_nop 0
	global_load_lds_dwordx4 v[224:225], off
	v_lshl_add_u64 v[224:225], s[42:43], 0, v[130:131]
	s_mov_b32 m0, s35
	s_nop 0
	global_load_lds_dwordx4 v[224:225], off
	s_mov_b32 m0, s48
	s_nop 0
	global_load_lds_dwordx4 v[226:227], off
	s_waitcnt vmcnt(8)
	s_waitcnt lgkmcnt(0)
	s_barrier
; #define PG8_STAGE(bufoff, gbase, voff) do { _Pragma("unroll") for (int _i = 0; _i < 2; ++_i) \
;         __builtin_amdgcn_global_load_lds((const unsigned*)((const char*)(gbase) + (voff)[_i]), (PG8_LAS unsigned*)(lds + (bufoff) + ldsw + _i * 8192), 16, 0, 0); } while (0)
; #define PG8_LDA(dst, b, h) do { _Pragma("unroll") for (int m = 0; m < 4; ++m) _Pragma("unroll") for (int k = 0; k < 2; ++k) dst[m][k] = *(const PG8_LAS bf16x8*)(lds + PG8_SA(b, h) + aoff + m * 2048 + k * 1024); } while (0)
; #define PG8_LDB(dst, b, h) do { _Pragma("unroll") for (int n = 0; n < 2; ++n) _Pragma("unroll") for (int k = 0; k < 2; ++k) dst[n][k] = *(const PG8_LAS bf16x8*)(lds + PG8_SB(b, h) + boff + n * 2048 + k * 1024); } while (0)
; #define PG8_MMA(ai, bj, At, Bt) do { __builtin_amdgcn_s_setprio(1); _Pragma("unroll") for (int m = 0; m < 4; ++m) _Pragma("unroll") for (int n = 0; n < 2; ++n) _Pragma("unroll") for (int k = 0; k < 2; ++k) \
;         acc[ai][bj][m][n] = __builtin_amdgcn_mfma_f32_16x16x32_bf16(Bt[n][k], At[m][k], acc[ai][bj][m][n], 0, 0, 0); __builtin_amdgcn_s_setprio(0); } while (0)
; #define PG8_WAIT_V(n) asm volatile("s_waitcnt vmcnt(" #n ")" ::: "memory")
; #define PG8_WAIT_L(n) asm volatile("s_waitcnt lgkmcnt(" #n ")" ::: "memory")
; #define PG8_BAR __builtin_amdgcn_s_barrier()
; #define PG8_SCHED __builtin_amdgcn_sched_barrier(0)
; template <class Epi, class Sched, bool ALIGN_EPI = false, bool SP2 = false>
; __device__ __forceinline__ void gemm_phase(PG8_LAS unsigned char* lds, const Gemm g, const Sched& S, const Epi& E) {
;     ...
;             PG8_WAIT_V(8); PG8_WAIT_L(0); PG8_BAR; PG8_MMA(1, 0, At, B0); PG8_MMA(1, 1, At, B1); PG8_BAR; PG8_SCHED;
;             PG8_LDB(B0, 1, 0); PG8_LDB(B1, 1, 1); PG8_SCHED; PG8_LDA(At, 1, 0); PG8_STAGE(PG8_SA(0, 1), a2 + hstepA, voffA);
;             PG8_WAIT_V(8); PG8_WAIT_L(0); PG8_BAR; PG8_MMA(0, 0, At, B0); PG8_MMA(0, 1, At, B1); PG8_BAR; PG8_SCHED;
	s_setprio 1
	s_waitcnt lgkmcnt(0)
	v_mfma_f32_16x16x32_bf16 v[62:65], v[146:149], v[188:191], 0
	v_mfma_f32_16x16x32_bf16 v[58:61], v[160:163], v[188:191], 0
	v_mfma_f32_16x16x32_bf16 v[46:49], v[146:149], v[196:199], 0
	v_mfma_f32_16x16x32_bf16 v[42:45], v[160:163], v[196:199], 0
	v_mfma_f32_16x16x32_bf16 v[30:33], v[146:149], v[204:207], 0
	v_mfma_f32_16x16x32_bf16 v[26:29], v[160:163], v[204:207], 0
	v_mfma_f32_16x16x32_bf16 v[14:17], v[146:149], v[212:215], 0
	v_mfma_f32_16x16x32_bf16 v[10:13], v[160:163], v[212:215], 0
	v_mfma_f32_16x16x32_bf16 v[62:65], v[150:153], v[192:195], v[62:65]
	v_mfma_f32_16x16x32_bf16 v[58:61], v[164:167], v[192:195], v[58:61]
	v_mfma_f32_16x16x32_bf16 v[46:49], v[150:153], v[200:203], v[46:49]
	v_mfma_f32_16x16x32_bf16 v[42:45], v[164:167], v[200:203], v[42:45]
	v_mfma_f32_16x16x32_bf16 v[30:33], v[150:153], v[208:211], v[30:33]
	v_mfma_f32_16x16x32_bf16 v[26:29], v[164:167], v[208:211], v[26:29]
	v_mfma_f32_16x16x32_bf16 v[14:17], v[150:153], v[220:223], v[14:17]
	v_mfma_f32_16x16x32_bf16 v[10:13], v[164:167], v[220:223], v[10:13]
	s_setprio 0
	s_setprio 1
	v_mfma_f32_16x16x32_bf16 v[54:57], v[168:171], v[188:191], 0
	v_mfma_f32_16x16x32_bf16 v[50:53], v[180:183], v[188:191], 0
	v_mfma_f32_16x16x32_bf16 v[38:41], v[168:171], v[196:199], 0
	v_mfma_f32_16x16x32_bf16 v[34:37], v[180:183], v[196:199], 0
	v_mfma_f32_16x16x32_bf16 v[22:25], v[168:171], v[204:207], 0
	v_mfma_f32_16x16x32_bf16 v[18:21], v[180:183], v[204:207], 0
	v_mfma_f32_16x16x32_bf16 v[6:9], v[168:171], v[212:215], 0
	v_mfma_f32_16x16x32_bf16 v[2:5], v[180:183], v[212:215], 0
	v_mfma_f32_16x16x32_bf16 v[54:57], v[176:179], v[192:195], v[54:57]
	v_mfma_f32_16x16x32_bf16 v[50:53], v[184:187], v[192:195], v[50:53]
	v_mfma_f32_16x16x32_bf16 v[38:41], v[176:179], v[200:203], v[38:41]
	v_mfma_f32_16x16x32_bf16 v[34:37], v[184:187], v[200:203], v[34:37]
	v_mfma_f32_16x16x32_bf16 v[22:25], v[176:179], v[208:211], v[22:25]
	v_mfma_f32_16x16x32_bf16 v[18:21], v[184:187], v[208:211], v[18:21]
	v_mfma_f32_16x16x32_bf16 v[6:9], v[176:179], v[220:223], v[6:9]
	v_mfma_f32_16x16x32_bf16 v[2:5], v[184:187], v[220:223], v[2:5]
	s_setprio 0
	s_barrier
	s_add_i32 s61, 0, 0x18000
	v_add_u32_e32 v159, s61, v154
	s_add_i32 s62, 0, 0x1c000
	ds_read_b128 v[146:149], v159
	ds_read_b128 v[150:153], v159 offset:1024
	ds_read_b128 v[160:163], v159 offset:2048
	ds_read_b128 v[164:167], v159 offset:3072
	v_add_u32_e32 v159, s62, v154
	ds_read_b128 v[168:171], v159
	ds_read_b128 v[176:179], v159 offset:1024
	ds_read_b128 v[180:183], v159 offset:2048
	ds_read_b128 v[184:187], v159 offset:3072
	s_add_u32 s42, s42, 0x20000
	s_addc_u32 s43, s43, 0
	s_mov_b32 m0, s49
	v_lshl_add_u64 v[228:229], s[42:43], 0, v[130:131]
	ds_read_b128 v[188:191], v158 offset:32768
	ds_read_b128 v[192:195], v158 offset:33792
	ds_read_b128 v[196:199], v158 offset:34816
	ds_read_b128 v[200:203], v158 offset:35840
	ds_read_b128 v[204:207], v158 offset:36864
	ds_read_b128 v[208:211], v158 offset:37888
	ds_read_b128 v[212:215], v158 offset:38912
	ds_read_b128 v[220:223], v158 offset:39936
	global_load_lds_dwordx4 v[228:229], off
	v_lshl_add_u64 v[228:229], s[42:43], 0, v[134:135]
	s_mov_b32 m0, s50
	s_nop 0
	global_load_lds_dwordx4 v[228:229], off
	s_waitcnt vmcnt(8)
	s_waitcnt lgkmcnt(0)
	s_barrier
	s_setprio 1
	s_waitcnt lgkmcnt(0)
	v_mfma_f32_16x16x32_bf16 v[126:129], v[146:149], v[188:191], v[126:129]
	v_mfma_f32_16x16x32_bf16 v[122:125], v[160:163], v[188:191], v[122:125]
	v_mfma_f32_16x16x32_bf16 v[110:113], v[146:149], v[196:199], v[110:113]
	v_mfma_f32_16x16x32_bf16 v[106:109], v[160:163], v[196:199], v[106:109]
	v_mfma_f32_16x16x32_bf16 v[94:97], v[146:149], v[204:207], v[94:97]
	v_mfma_f32_16x16x32_bf16 v[90:93], v[160:163], v[204:207], v[90:93]
	v_mfma_f32_16x16x32_bf16 v[78:81], v[146:149], v[212:215], v[78:81]
	v_mfma_f32_16x16x32_bf16 v[74:77], v[160:163], v[212:215], v[74:77]
	v_mfma_f32_16x16x32_bf16 v[126:129], v[150:153], v[192:195], v[126:129]
	v_mfma_f32_16x16x32_bf16 v[122:125], v[164:167], v[192:195], v[122:125]
	v_mfma_f32_16x16x32_bf16 v[110:113], v[150:153], v[200:203], v[110:113]
	v_mfma_f32_16x16x32_bf16 v[106:109], v[164:167], v[200:203], v[106:109]
	v_mfma_f32_16x16x32_bf16 v[94:97], v[150:153], v[208:211], v[94:97]
	v_mfma_f32_16x16x32_bf16 v[90:93], v[164:167], v[208:211], v[90:93]
	v_mfma_f32_16x16x32_bf16 v[78:81], v[150:153], v[220:223], v[78:81]
	v_mfma_f32_16x16x32_bf16 v[74:77], v[164:167], v[220:223], v[74:77]
	s_setprio 0
	s_setprio 1
	v_mfma_f32_16x16x32_bf16 v[118:121], v[168:171], v[188:191], v[118:121]
	v_mfma_f32_16x16x32_bf16 v[114:117], v[180:183], v[188:191], v[114:117]
	v_mfma_f32_16x16x32_bf16 v[102:105], v[168:171], v[196:199], v[102:105]
	v_mfma_f32_16x16x32_bf16 v[98:101], v[180:183], v[196:199], v[98:101]
	v_mfma_f32_16x16x32_bf16 v[86:89], v[168:171], v[204:207], v[86:89]
	v_mfma_f32_16x16x32_bf16 v[82:85], v[180:183], v[204:207], v[82:85]
	v_mfma_f32_16x16x32_bf16 v[70:73], v[168:171], v[212:215], v[70:73]
	v_mfma_f32_16x16x32_bf16 v[66:69], v[180:183], v[212:215], v[66:69]
	v_mfma_f32_16x16x32_bf16 v[118:121], v[176:179], v[192:195], v[118:121]
	v_mfma_f32_16x16x32_bf16 v[114:117], v[184:187], v[192:195], v[114:117]
	v_mfma_f32_16x16x32_bf16 v[102:105], v[176:179], v[200:203], v[102:105]
	v_mfma_f32_16x16x32_bf16 v[98:101], v[184:187], v[200:203], v[98:101]
	v_mfma_f32_16x16x32_bf16 v[86:89], v[176:179], v[208:211], v[86:89]
	v_mfma_f32_16x16x32_bf16 v[82:85], v[184:187], v[208:211], v[82:85]
	v_mfma_f32_16x16x32_bf16 v[70:73], v[176:179], v[220:223], v[70:73]
	v_mfma_f32_16x16x32_bf16 v[66:69], v[184:187], v[220:223], v[66:69]
	s_setprio 0
	s_barrier
; #define PG8_STAGE(bufoff, gbase, voff) do { _Pragma("unroll") for (int _i = 0; _i < 2; ++_i) \
;         __builtin_amdgcn_global_load_lds((const unsigned*)((const char*)(gbase) + (voff)[_i]), (PG8_LAS unsigned*)(lds + (bufoff) + ldsw + _i * 8192), 16, 0, 0); } while (0)
; #define PG8_LDA(dst, b, h) do { _Pragma("unroll") for (int m = 0; m < 4; ++m) _Pragma("unroll") for (int k = 0; k < 2; ++k) dst[m][k] = *(const PG8_LAS bf16x8*)(lds + PG8_SA(b, h) + aoff + m * 2048 + k * 1024); } while (0)
; #define PG8_MMA(ai, bj, At, Bt) do { __builtin_amdgcn_s_setprio(1); _Pragma("unroll") for (int m = 0; m < 4; ++m) _Pragma("unroll") for (int n = 0; n < 2; ++n) _Pragma("unroll") for (int k = 0; k < 2; ++k) \
;         acc[ai][bj][m][n] = __builtin_amdgcn_mfma_f32_16x16x32_bf16(Bt[n][k], At[m][k], acc[ai][bj][m][n], 0, 0, 0); __builtin_amdgcn_s_setprio(0); } while (0)
; #define PG8_WAIT_V(n) asm volatile("s_waitcnt vmcnt(" #n ")" ::: "memory")
; #define PG8_WAIT_L(n) asm volatile("s_waitcnt lgkmcnt(" #n ")" ::: "memory")
; #define PG8_BAR __builtin_amdgcn_s_barrier()
; #define PG8_SCHED __builtin_amdgcn_sched_barrier(0)
; template <class Epi, class Sched, bool ALIGN_EPI = false, bool SP2 = false>
; __device__ __forceinline__ void gemm_phase(PG8_LAS unsigned char* lds, const Gemm g, const Sched& S, const Epi& E) {
;     ...
;         for (int t = 0; t < nt; t += 2) {
;     ...
;             PG8_LDA(At, 1, 1); PG8_STAGE(PG8_SB(1, 0), b3, voffB); PG8_STAGE(PG8_SB(1, 1), b3 + hstepB, voffB); PG8_STAGE(PG8_SA(1, 0), a3, voffA);
;             PG8_WAIT_V(8); PG8_WAIT_L(0); PG8_BAR; PG8_MMA(1, 0, At, B0); PG8_MMA(1, 1, At, B1); PG8_BAR; PG8_SCHED;
	s_add_i32 s42, s61, s47
	v_lshl_add_u64 v[172:173], v[172:173], 0, s[16:17]
	s_mov_b32 m0, s42
	ds_read_b128 v[188:191], v158 offset:49152
	ds_read_b128 v[192:195], v158 offset:50176
	ds_read_b128 v[196:199], v158 offset:51200
	ds_read_b128 v[200:203], v158 offset:52224
	ds_read_b128 v[204:207], v158 offset:53248
	ds_read_b128 v[208:211], v158 offset:54272
	ds_read_b128 v[212:215], v158 offset:55296
	ds_read_b128 v[220:223], v158 offset:56320
	global_load_lds_dwordx4 v[172:173], off
	s_add_i32 m0, s42, 0x2000
	s_add_u32 s40, s40, 0x20080
	v_lshl_add_u64 v[172:173], v[216:217], 0, s[16:17]
	s_addc_u32 s41, s41, 0
	s_add_i32 s42, s62, s47
	global_load_lds_dwordx4 v[172:173], off
	v_lshl_add_u64 v[172:173], s[40:41], 0, v[132:133]
	s_mov_b32 m0, s42
	s_nop 0
	global_load_lds_dwordx4 v[172:173], off
	v_lshl_add_u64 v[172:173], s[40:41], 0, v[136:137]
	s_add_i32 m0, s42, 0x2000
	s_nop 0
	global_load_lds_dwordx4 v[172:173], off
	v_lshl_add_u64 v[172:173], v[224:225], 0, s[16:17]
	s_mov_b32 m0, s52
	s_nop 0
	global_load_lds_dwordx4 v[172:173], off
	v_lshl_add_u64 v[172:173], v[226:227], 0, s[16:17]
	s_mov_b32 m0, s53
	s_nop 0
	global_load_lds_dwordx4 v[172:173], off
	s_waitcnt vmcnt(8)
	s_waitcnt lgkmcnt(0)
	s_barrier
	s_setprio 1
	s_waitcnt lgkmcnt(0)
	v_mfma_f32_16x16x32_bf16 v[62:65], v[146:149], v[188:191], v[62:65]
	v_mfma_f32_16x16x32_bf16 v[58:61], v[160:163], v[188:191], v[58:61]
	v_mfma_f32_16x16x32_bf16 v[46:49], v[146:149], v[196:199], v[46:49]
	v_mfma_f32_16x16x32_bf16 v[42:45], v[160:163], v[196:199], v[42:45]
	v_mfma_f32_16x16x32_bf16 v[30:33], v[146:149], v[204:207], v[30:33]
	v_mfma_f32_16x16x32_bf16 v[26:29], v[160:163], v[204:207], v[26:29]
	v_mfma_f32_16x16x32_bf16 v[14:17], v[146:149], v[212:215], v[14:17]
	v_mfma_f32_16x16x32_bf16 v[10:13], v[160:163], v[212:215], v[10:13]
	v_mfma_f32_16x16x32_bf16 v[62:65], v[150:153], v[192:195], v[62:65]
	v_mfma_f32_16x16x32_bf16 v[58:61], v[164:167], v[192:195], v[58:61]
	v_mfma_f32_16x16x32_bf16 v[46:49], v[150:153], v[200:203], v[46:49]
	v_mfma_f32_16x16x32_bf16 v[42:45], v[164:167], v[200:203], v[42:45]
	v_mfma_f32_16x16x32_bf16 v[30:33], v[150:153], v[208:211], v[30:33]
	v_mfma_f32_16x16x32_bf16 v[26:29], v[164:167], v[208:211], v[26:29]
	v_mfma_f32_16x16x32_bf16 v[14:17], v[150:153], v[220:223], v[14:17]
	v_mfma_f32_16x16x32_bf16 v[10:13], v[164:167], v[220:223], v[10:13]
	s_setprio 0
	s_setprio 1
	v_mfma_f32_16x16x32_bf16 v[54:57], v[168:171], v[188:191], v[54:57]
	v_mfma_f32_16x16x32_bf16 v[50:53], v[180:183], v[188:191], v[50:53]
	v_mfma_f32_16x16x32_bf16 v[38:41], v[168:171], v[196:199], v[38:41]
	v_mfma_f32_16x16x32_bf16 v[34:37], v[180:183], v[196:199], v[34:37]
	v_mfma_f32_16x16x32_bf16 v[22:25], v[168:171], v[204:207], v[22:25]
	v_mfma_f32_16x16x32_bf16 v[18:21], v[180:183], v[204:207], v[18:21]
	v_mfma_f32_16x16x32_bf16 v[6:9], v[168:171], v[212:215], v[6:9]
	v_mfma_f32_16x16x32_bf16 v[2:5], v[180:183], v[212:215], v[2:5]
	v_mfma_f32_16x16x32_bf16 v[54:57], v[176:179], v[192:195], v[54:57]
	v_mfma_f32_16x16x32_bf16 v[50:53], v[184:187], v[192:195], v[50:53]
	v_mfma_f32_16x16x32_bf16 v[38:41], v[176:179], v[200:203], v[38:41]
	v_mfma_f32_16x16x32_bf16 v[34:37], v[184:187], v[200:203], v[34:37]
	v_mfma_f32_16x16x32_bf16 v[22:25], v[176:179], v[208:211], v[22:25]
	v_mfma_f32_16x16x32_bf16 v[18:21], v[184:187], v[208:211], v[18:21]
	v_mfma_f32_16x16x32_bf16 v[6:9], v[176:179], v[220:223], v[6:9]
	v_mfma_f32_16x16x32_bf16 v[2:5], v[184:187], v[220:223], v[2:5]
	s_setprio 0
	s_barrier
	s_add_i32 s60, s60, 2
	s_add_u32 s36, s36, 0x100
	s_addc_u32 s37, s37, 0
	s_add_u32 s58, s58, 0x100
	s_addc_u32 s59, s59, 0
	s_cmp_gt_u32 s60, 5
	s_cbranch_scc1 .Lpeel_exit_5

; #define PG8_BAR __builtin_amdgcn_s_barrier()
; template <class Epi, class Sched, bool ALIGN_EPI = false, bool SP2 = false>
; __device__ __forceinline__ void gemm_phase(PG8_LAS unsigned char* lds, const Gemm g, const Sched& S, const Epi& E) {
;     ...
;         if constexpr (ALIGN_EPI) { if (wr == 0) PG8_BAR; }
.Lpeel_exit_5:
	s_and_b64 vcc, exec, s[18:19]
	s_cbranch_vccz .LBB0_979
	s_barrier

; #define PG8_STAGE(bufoff, gbase, voff) do { _Pragma("unroll") for (int _i = 0; _i < 2; ++_i) \
;         __builtin_amdgcn_global_load_lds((const unsigned*)((const char*)(gbase) + (voff)[_i]), (PG8_LAS unsigned*)(lds + (bufoff) + ldsw + _i * 8192), 16, 0, 0); } while (0)
; #define PG8_LDA(dst, b, h) do { _Pragma("unroll") for (int m = 0; m < 4; ++m) _Pragma("unroll") for (int k = 0; k < 2; ++k) dst[m][k] = *(const PG8_LAS bf16x8*)(lds + PG8_SA(b, h) + aoff + m * 2048 + k * 1024); } while (0)
; #define PG8_LDB(dst, b, h) do { _Pragma("unroll") for (int n = 0; n < 2; ++n) _Pragma("unroll") for (int k = 0; k < 2; ++k) dst[n][k] = *(const PG8_LAS bf16x8*)(lds + PG8_SB(b, h) + boff + n * 2048 + k * 1024); } while (0)
; #define PG8_MMA(ai, bj, At, Bt) do { __builtin_amdgcn_s_setprio(1); _Pragma("unroll") for (int m = 0; m < 4; ++m) _Pragma("unroll") for (int n = 0; n < 2; ++n) _Pragma("unroll") for (int k = 0; k < 2; ++k) \
;         acc[ai][bj][m][n] = __builtin_amdgcn_mfma_f32_16x16x32_bf16(Bt[n][k], At[m][k], acc[ai][bj][m][n], 0, 0, 0); __builtin_amdgcn_s_setprio(0); } while (0)
; #define PG8_BAR __builtin_amdgcn_s_barrier()
; template <class Epi, class Sched, bool ALIGN_EPI = false, bool SP2 = false>
; __device__ __forceinline__ void gemm_phase(PG8_LAS unsigned char* lds, const Gemm g, const Sched& S, const Epi& E) {
;     ...
;             const char* a1 = cA + (size_t)(t + 1) * kstep;
;             const char* a2 = last ? nA : cA + (size_t)(t + 2) * kstep; const char* b2 = last ? nB : cB + (size_t)(t + 2) * kstep;
;             const char* a3 = a2 + kstep; const char* b3 = b2 + kstep;
;             if (last && has_next) S.a_ready(nxt);
;             if constexpr (SP2) {
;             PG8_LDB(B0, 0, 0); PG8_LDB(B1, 0, 1); PG8_SCHED; PG8_LDA(At, 0, 0); PG8_STAGE(PG8_SA(1, 1), a1 + hstepA, voffA);
;             PG8_WAIT_V(8); PG8_WAIT_L(0); PG8_BAR; PG8_MMA(0, 0, At, B0); PG8_MMA(0, 1, At, B1); PG8_BAR; PG8_SCHED;
;             PG8_LDA(At, 0, 1); PG8_STAGE(PG8_SB(0, 0), b2, voffB); PG8_STAGE(PG8_SB(0, 1), b2 + hstepB, voffB); PG8_STAGE(PG8_SA(0, 0), a2, voffA);
;     ...
; #pragma unroll
;         for (int a = 0; a < 2; ++a)
; #pragma unroll
;             for (int b = 0; b < 2; ++b)
; #pragma unroll
;                 for (int m = 0; m < 4; ++m)
; #pragma unroll
;                     for (int n = 0; n < 2; ++n) acc[a][b][m][n] = (f32x4){0.f, 0.f, 0.f, 0.f};
.LBB0_1080:
	s_ashr_i32 s25, s24, 31
	s_lshl_b64 s[26:27], s[24:25], 19
	s_add_u32 s26, s33, s26
	s_addc_u32 s27, s44, s27
	s_and_b64 s[28:29], s[6:7], exec
	s_cselect_b32 s25, s27, s37
	s_cselect_b32 s31, s26, s36
	s_ashr_i32 s23, s22, 31
	s_lshl_b64 s[28:29], s[22:23], 19
	s_add_u32 s28, s45, s28
	s_addc_u32 s29, s46, s29
	s_and_b64 s[38:39], s[6:7], exec
	s_cselect_b32 s23, s29, s41
	s_cselect_b32 s38, s28, s40
	s_add_u32 s36, s36, 0x40080
	s_addc_u32 s37, s37, 0
	s_add_u32 s39, s40, 0x100
	s_addc_u32 s58, s41, 0
	s_mov_b32 s59, -2
	s_waitcnt lgkmcnt(0)
	ds_read_b128 v[130:133], v166
	ds_read_b128 v[134:137], v166 offset:1024
	ds_read_b128 v[154:157], v166 offset:2048
	ds_read_b128 v[158:161], v166 offset:3072
	ds_read_b128 v[170:173], v167
	ds_read_b128 v[176:179], v167 offset:1024
	ds_read_b128 v[180:183], v167 offset:2048
	ds_read_b128 v[184:187], v167 offset:3072
	s_add_u32 s40, s36, 0xfffc0080
	s_addc_u32 s41, s37, -1
	s_cmp_eq_u32 s59, 12
	s_cselect_b32 s43, s25, s41
	s_cselect_b32 s42, s31, s40
	s_cselect_b32 s41, s23, s58
	s_cselect_b32 s40, s38, s39
	v_lshl_add_u64 v[162:163], s[36:37], 0, v[146:147]
	s_add_i32 m0, s35, 0xc000
	ds_read_b128 v[188:191], v168
	ds_read_b128 v[192:195], v168 offset:1024
	ds_read_b128 v[196:199], v168 offset:2048
	ds_read_b128 v[200:203], v168 offset:3072
	ds_read_b128 v[204:207], v168 offset:4096
	ds_read_b128 v[208:211], v168 offset:5120
	ds_read_b128 v[212:215], v168 offset:6144
	ds_read_b128 v[220:223], v168 offset:7168
	global_load_lds_dwordx4 v[162:163], off
	v_lshl_add_u64 v[162:163], s[36:37], 0, v[148:149]
	s_add_i32 m0, s35, 0xe000
	s_nop 0
	global_load_lds_dwordx4 v[162:163], off
	s_waitcnt vmcnt(8)
	s_waitcnt lgkmcnt(0)
	s_barrier
	s_setprio 1
	s_waitcnt lgkmcnt(0)
	v_mfma_f32_16x16x32_bf16 v[126:129], v[130:133], v[188:191], 0
	v_mfma_f32_16x16x32_bf16 v[122:125], v[154:157], v[188:191], 0
	v_mfma_f32_16x16x32_bf16 v[110:113], v[130:133], v[196:199], 0
	v_mfma_f32_16x16x32_bf16 v[106:109], v[154:157], v[196:199], 0
	v_mfma_f32_16x16x32_bf16 v[94:97], v[130:133], v[204:207], 0
	v_mfma_f32_16x16x32_bf16 v[90:93], v[154:157], v[204:207], 0
	v_mfma_f32_16x16x32_bf16 v[78:81], v[130:133], v[212:215], 0
	v_mfma_f32_16x16x32_bf16 v[74:77], v[154:157], v[212:215], 0
	v_mfma_f32_16x16x32_bf16 v[126:129], v[134:137], v[192:195], v[126:129]
	v_mfma_f32_16x16x32_bf16 v[122:125], v[158:161], v[192:195], v[122:125]
	v_mfma_f32_16x16x32_bf16 v[110:113], v[134:137], v[200:203], v[110:113]
	v_mfma_f32_16x16x32_bf16 v[106:109], v[158:161], v[200:203], v[106:109]
	v_mfma_f32_16x16x32_bf16 v[94:97], v[134:137], v[208:211], v[94:97]
	v_mfma_f32_16x16x32_bf16 v[90:93], v[158:161], v[208:211], v[90:93]
	v_mfma_f32_16x16x32_bf16 v[78:81], v[134:137], v[220:223], v[78:81]
	v_mfma_f32_16x16x32_bf16 v[74:77], v[158:161], v[220:223], v[74:77]
	s_setprio 0
	s_setprio 1
	v_mfma_f32_16x16x32_bf16 v[118:121], v[170:173], v[188:191], 0
	v_mfma_f32_16x16x32_bf16 v[114:117], v[180:183], v[188:191], 0
	v_mfma_f32_16x16x32_bf16 v[102:105], v[170:173], v[196:199], 0
	v_mfma_f32_16x16x32_bf16 v[98:101], v[180:183], v[196:199], 0
	v_mfma_f32_16x16x32_bf16 v[86:89], v[170:173], v[204:207], 0
	v_mfma_f32_16x16x32_bf16 v[82:85], v[180:183], v[204:207], 0
	v_mfma_f32_16x16x32_bf16 v[70:73], v[170:173], v[212:215], 0
	v_mfma_f32_16x16x32_bf16 v[66:69], v[180:183], v[212:215], 0
	v_mfma_f32_16x16x32_bf16 v[118:121], v[176:179], v[192:195], v[118:121]
	v_mfma_f32_16x16x32_bf16 v[114:117], v[184:187], v[192:195], v[114:117]
	v_mfma_f32_16x16x32_bf16 v[102:105], v[176:179], v[200:203], v[102:105]
	v_mfma_f32_16x16x32_bf16 v[98:101], v[184:187], v[200:203], v[98:101]
	v_mfma_f32_16x16x32_bf16 v[86:89], v[176:179], v[208:211], v[86:89]
	v_mfma_f32_16x16x32_bf16 v[82:85], v[184:187], v[208:211], v[82:85]
	v_mfma_f32_16x16x32_bf16 v[70:73], v[176:179], v[220:223], v[70:73]
	v_mfma_f32_16x16x32_bf16 v[66:69], v[184:187], v[220:223], v[66:69]
	s_setprio 0
	s_barrier
	s_add_i32 s60, s56, s47
	v_lshl_add_u64 v[162:163], s[40:41], 0, v[140:141]
	s_mov_b32 m0, s60
	ds_read_b128 v[188:191], v168 offset:16384
	ds_read_b128 v[192:195], v168 offset:17408
	ds_read_b128 v[196:199], v168 offset:18432
	ds_read_b128 v[200:203], v168 offset:19456
	ds_read_b128 v[204:207], v168 offset:20480
	ds_read_b128 v[208:211], v168 offset:21504
	ds_read_b128 v[212:215], v168 offset:22528
	ds_read_b128 v[220:223], v168 offset:23552
	global_load_lds_dwordx4 v[162:163], off
	s_add_i32 m0, s60, 0x2000
	s_add_u32 s60, s40, 0x40000
	v_lshl_add_u64 v[216:217], s[40:41], 0, v[144:145]
	s_addc_u32 s61, s41, 0
	s_add_i32 s62, s57, s47
	global_load_lds_dwordx4 v[216:217], off
	v_lshl_add_u64 v[224:225], s[60:61], 0, v[140:141]
	s_mov_b32 m0, s62
	v_lshl_add_u64 v[226:227], s[42:43], 0, v[142:143]
	global_load_lds_dwordx4 v[224:225], off
	v_lshl_add_u64 v[224:225], s[60:61], 0, v[144:145]
	s_add_i32 m0, s62, 0x2000
	s_nop 0
	global_load_lds_dwordx4 v[224:225], off
	v_lshl_add_u64 v[224:225], s[42:43], 0, v[138:139]
	s_mov_b32 m0, s35
	s_nop 0
	global_load_lds_dwordx4 v[224:225], off
	s_mov_b32 m0, s48
	s_nop 0
	global_load_lds_dwordx4 v[226:227], off
	s_waitcnt vmcnt(8)
	s_waitcnt lgkmcnt(0)
	s_barrier
; #define PG8_STAGE(bufoff, gbase, voff) do { _Pragma("unroll") for (int _i = 0; _i < 2; ++_i) \
;         __builtin_amdgcn_global_load_lds((const unsigned*)((const char*)(gbase) + (voff)[_i]), (PG8_LAS unsigned*)(lds + (bufoff) + ldsw + _i * 8192), 16, 0, 0); } while (0)
; #define PG8_LDA(dst, b, h) do { _Pragma("unroll") for (int m = 0; m < 4; ++m) _Pragma("unroll") for (int k = 0; k < 2; ++k) dst[m][k] = *(const PG8_LAS bf16x8*)(lds + PG8_SA(b, h) + aoff + m * 2048 + k * 1024); } while (0)
; #define PG8_LDB(dst, b, h) do { _Pragma("unroll") for (int n = 0; n < 2; ++n) _Pragma("unroll") for (int k = 0; k < 2; ++k) dst[n][k] = *(const PG8_LAS bf16x8*)(lds + PG8_SB(b, h) + boff + n * 2048 + k * 1024); } while (0)
; #define PG8_MMA(ai, bj, At, Bt) do { __builtin_amdgcn_s_setprio(1); _Pragma("unroll") for (int m = 0; m < 4; ++m) _Pragma("unroll") for (int n = 0; n < 2; ++n) _Pragma("unroll") for (int k = 0; k < 2; ++k) \
;         acc[ai][bj][m][n] = __builtin_amdgcn_mfma_f32_16x16x32_bf16(Bt[n][k], At[m][k], acc[ai][bj][m][n], 0, 0, 0); __builtin_amdgcn_s_setprio(0); } while (0)
; #define PG8_WAIT_V(n) asm volatile("s_waitcnt vmcnt(" #n ")" ::: "memory")
; #define PG8_WAIT_L(n) asm volatile("s_waitcnt lgkmcnt(" #n ")" ::: "memory")
; #define PG8_BAR __builtin_amdgcn_s_barrier()
; #define PG8_SCHED __builtin_amdgcn_sched_barrier(0)
; template <class Epi, class Sched, bool ALIGN_EPI = false, bool SP2 = false>
; __device__ __forceinline__ void gemm_phase(PG8_LAS unsigned char* lds, const Gemm g, const Sched& S, const Epi& E) {
;     ...
;             PG8_WAIT_V(8); PG8_WAIT_L(0); PG8_BAR; PG8_MMA(1, 0, At, B0); PG8_MMA(1, 1, At, B1); PG8_BAR; PG8_SCHED;
;             PG8_LDB(B0, 1, 0); PG8_LDB(B1, 1, 1); PG8_SCHED; PG8_LDA(At, 1, 0); PG8_STAGE(PG8_SA(0, 1), a2 + hstepA, voffA);
;             PG8_WAIT_V(8); PG8_WAIT_L(0); PG8_BAR; PG8_MMA(0, 0, At, B0); PG8_MMA(0, 1, At, B1); PG8_BAR; PG8_SCHED;
	s_setprio 1
	s_waitcnt lgkmcnt(0)
	v_mfma_f32_16x16x32_bf16 v[62:65], v[130:133], v[188:191], 0
	v_mfma_f32_16x16x32_bf16 v[58:61], v[154:157], v[188:191], 0
	v_mfma_f32_16x16x32_bf16 v[46:49], v[130:133], v[196:199], 0
	v_mfma_f32_16x16x32_bf16 v[42:45], v[154:157], v[196:199], 0
	v_mfma_f32_16x16x32_bf16 v[30:33], v[130:133], v[204:207], 0
	v_mfma_f32_16x16x32_bf16 v[26:29], v[154:157], v[204:207], 0
	v_mfma_f32_16x16x32_bf16 v[14:17], v[130:133], v[212:215], 0
	v_mfma_f32_16x16x32_bf16 v[10:13], v[154:157], v[212:215], 0
	v_mfma_f32_16x16x32_bf16 v[62:65], v[134:137], v[192:195], v[62:65]
	v_mfma_f32_16x16x32_bf16 v[58:61], v[158:161], v[192:195], v[58:61]
	v_mfma_f32_16x16x32_bf16 v[46:49], v[134:137], v[200:203], v[46:49]
	v_mfma_f32_16x16x32_bf16 v[42:45], v[158:161], v[200:203], v[42:45]
	v_mfma_f32_16x16x32_bf16 v[30:33], v[134:137], v[208:211], v[30:33]
	v_mfma_f32_16x16x32_bf16 v[26:29], v[158:161], v[208:211], v[26:29]
	v_mfma_f32_16x16x32_bf16 v[14:17], v[134:137], v[220:223], v[14:17]
	v_mfma_f32_16x16x32_bf16 v[10:13], v[158:161], v[220:223], v[10:13]
	s_setprio 0
	s_setprio 1
	v_mfma_f32_16x16x32_bf16 v[54:57], v[170:173], v[188:191], 0
	v_mfma_f32_16x16x32_bf16 v[50:53], v[180:183], v[188:191], 0
	v_mfma_f32_16x16x32_bf16 v[38:41], v[170:173], v[196:199], 0
	v_mfma_f32_16x16x32_bf16 v[34:37], v[180:183], v[196:199], 0
	v_mfma_f32_16x16x32_bf16 v[22:25], v[170:173], v[204:207], 0
	v_mfma_f32_16x16x32_bf16 v[18:21], v[180:183], v[204:207], 0
	v_mfma_f32_16x16x32_bf16 v[6:9], v[170:173], v[212:215], 0
	v_mfma_f32_16x16x32_bf16 v[2:5], v[180:183], v[212:215], 0
	v_mfma_f32_16x16x32_bf16 v[54:57], v[176:179], v[192:195], v[54:57]
	v_mfma_f32_16x16x32_bf16 v[50:53], v[184:187], v[192:195], v[50:53]
	v_mfma_f32_16x16x32_bf16 v[38:41], v[176:179], v[200:203], v[38:41]
	v_mfma_f32_16x16x32_bf16 v[34:37], v[184:187], v[200:203], v[34:37]
	v_mfma_f32_16x16x32_bf16 v[22:25], v[176:179], v[208:211], v[22:25]
	v_mfma_f32_16x16x32_bf16 v[18:21], v[184:187], v[208:211], v[18:21]
	v_mfma_f32_16x16x32_bf16 v[6:9], v[176:179], v[220:223], v[6:9]
	v_mfma_f32_16x16x32_bf16 v[2:5], v[184:187], v[220:223], v[2:5]
	s_setprio 0
	s_barrier
	s_add_i32 s60, 0, 0x18000
	s_add_i32 s61, 0, 0x1c000
	v_add_u32_e32 v158, s60, v164
	v_add_u32_e32 v175, s61, v164
	ds_read_b128 v[130:133], v158
	ds_read_b128 v[134:137], v158 offset:1024
	ds_read_b128 v[154:157], v158 offset:2048
	ds_read_b128 v[158:161], v158 offset:3072
	ds_read_b128 v[170:173], v175
	ds_read_b128 v[176:179], v175 offset:1024
	ds_read_b128 v[180:183], v175 offset:2048
	ds_read_b128 v[184:187], v175 offset:3072
	s_add_u32 s42, s42, 0x40000
	s_addc_u32 s43, s43, 0
	s_mov_b32 m0, s49
	v_lshl_add_u64 v[228:229], s[42:43], 0, v[138:139]
	ds_read_b128 v[188:191], v168 offset:32768
	ds_read_b128 v[192:195], v168 offset:33792
	ds_read_b128 v[196:199], v168 offset:34816
	ds_read_b128 v[200:203], v168 offset:35840
	ds_read_b128 v[204:207], v168 offset:36864
	ds_read_b128 v[208:211], v168 offset:37888
	ds_read_b128 v[212:215], v168 offset:38912
	ds_read_b128 v[220:223], v168 offset:39936
	global_load_lds_dwordx4 v[228:229], off
	v_lshl_add_u64 v[228:229], s[42:43], 0, v[142:143]
	s_mov_b32 m0, s50
	s_nop 0
	global_load_lds_dwordx4 v[228:229], off
	s_waitcnt vmcnt(8)
	s_waitcnt lgkmcnt(0)
	s_barrier
	s_setprio 1
	s_waitcnt lgkmcnt(0)
	v_mfma_f32_16x16x32_bf16 v[126:129], v[130:133], v[188:191], v[126:129]
	v_mfma_f32_16x16x32_bf16 v[122:125], v[154:157], v[188:191], v[122:125]
	v_mfma_f32_16x16x32_bf16 v[110:113], v[130:133], v[196:199], v[110:113]
	v_mfma_f32_16x16x32_bf16 v[106:109], v[154:157], v[196:199], v[106:109]
	v_mfma_f32_16x16x32_bf16 v[94:97], v[130:133], v[204:207], v[94:97]
	v_mfma_f32_16x16x32_bf16 v[90:93], v[154:157], v[204:207], v[90:93]
	v_mfma_f32_16x16x32_bf16 v[78:81], v[130:133], v[212:215], v[78:81]
	v_mfma_f32_16x16x32_bf16 v[74:77], v[154:157], v[212:215], v[74:77]
	v_mfma_f32_16x16x32_bf16 v[126:129], v[134:137], v[192:195], v[126:129]
	v_mfma_f32_16x16x32_bf16 v[122:125], v[158:161], v[192:195], v[122:125]
	v_mfma_f32_16x16x32_bf16 v[110:113], v[134:137], v[200:203], v[110:113]
	v_mfma_f32_16x16x32_bf16 v[106:109], v[158:161], v[200:203], v[106:109]
	v_mfma_f32_16x16x32_bf16 v[94:97], v[134:137], v[208:211], v[94:97]
	v_mfma_f32_16x16x32_bf16 v[90:93], v[158:161], v[208:211], v[90:93]
	v_mfma_f32_16x16x32_bf16 v[78:81], v[134:137], v[220:223], v[78:81]
	v_mfma_f32_16x16x32_bf16 v[74:77], v[158:161], v[220:223], v[74:77]
	s_setprio 0
	s_setprio 1
	v_mfma_f32_16x16x32_bf16 v[118:121], v[170:173], v[188:191], v[118:121]
	v_mfma_f32_16x16x32_bf16 v[114:117], v[180:183], v[188:191], v[114:117]
	v_mfma_f32_16x16x32_bf16 v[102:105], v[170:173], v[196:199], v[102:105]
	v_mfma_f32_16x16x32_bf16 v[98:101], v[180:183], v[196:199], v[98:101]
	v_mfma_f32_16x16x32_bf16 v[86:89], v[170:173], v[204:207], v[86:89]
	v_mfma_f32_16x16x32_bf16 v[82:85], v[180:183], v[204:207], v[82:85]
	v_mfma_f32_16x16x32_bf16 v[70:73], v[170:173], v[212:215], v[70:73]
	v_mfma_f32_16x16x32_bf16 v[66:69], v[180:183], v[212:215], v[66:69]
	v_mfma_f32_16x16x32_bf16 v[118:121], v[176:179], v[192:195], v[118:121]
	v_mfma_f32_16x16x32_bf16 v[114:117], v[184:187], v[192:195], v[114:117]
	v_mfma_f32_16x16x32_bf16 v[102:105], v[176:179], v[200:203], v[102:105]
	v_mfma_f32_16x16x32_bf16 v[98:101], v[184:187], v[200:203], v[98:101]
	v_mfma_f32_16x16x32_bf16 v[86:89], v[176:179], v[208:211], v[86:89]
	v_mfma_f32_16x16x32_bf16 v[82:85], v[184:187], v[208:211], v[82:85]
	v_mfma_f32_16x16x32_bf16 v[70:73], v[176:179], v[220:223], v[70:73]
	v_mfma_f32_16x16x32_bf16 v[66:69], v[184:187], v[220:223], v[66:69]
	s_setprio 0
	s_barrier
; #define PG8_STAGE(bufoff, gbase, voff) do { _Pragma("unroll") for (int _i = 0; _i < 2; ++_i) \
;         __builtin_amdgcn_global_load_lds((const unsigned*)((const char*)(gbase) + (voff)[_i]), (PG8_LAS unsigned*)(lds + (bufoff) + ldsw + _i * 8192), 16, 0, 0); } while (0)
; #define PG8_LDA(dst, b, h) do { _Pragma("unroll") for (int m = 0; m < 4; ++m) _Pragma("unroll") for (int k = 0; k < 2; ++k) dst[m][k] = *(const PG8_LAS bf16x8*)(lds + PG8_SA(b, h) + aoff + m * 2048 + k * 1024); } while (0)
; #define PG8_MMA(ai, bj, At, Bt) do { __builtin_amdgcn_s_setprio(1); _Pragma("unroll") for (int m = 0; m < 4; ++m) _Pragma("unroll") for (int n = 0; n < 2; ++n) _Pragma("unroll") for (int k = 0; k < 2; ++k) \
;         acc[ai][bj][m][n] = __builtin_amdgcn_mfma_f32_16x16x32_bf16(Bt[n][k], At[m][k], acc[ai][bj][m][n], 0, 0, 0); __builtin_amdgcn_s_setprio(0); } while (0)
; #define PG8_WAIT_V(n) asm volatile("s_waitcnt vmcnt(" #n ")" ::: "memory")
; #define PG8_WAIT_L(n) asm volatile("s_waitcnt lgkmcnt(" #n ")" ::: "memory")
; #define PG8_BAR __builtin_amdgcn_s_barrier()
; #define PG8_SCHED __builtin_amdgcn_sched_barrier(0)
; template <class Epi, class Sched, bool ALIGN_EPI = false, bool SP2 = false>
; __device__ __forceinline__ void gemm_phase(PG8_LAS unsigned char* lds, const Gemm g, const Sched& S, const Epi& E) {
;     ...
;         for (int t = 0; t < nt; t += 2) {
;     ...
;             PG8_LDA(At, 1, 1); PG8_STAGE(PG8_SB(1, 0), b3, voffB); PG8_STAGE(PG8_SB(1, 1), b3 + hstepB, voffB); PG8_STAGE(PG8_SA(1, 0), a3, voffA);
;             PG8_WAIT_V(8); PG8_WAIT_L(0); PG8_BAR; PG8_MMA(1, 0, At, B0); PG8_MMA(1, 1, At, B1); PG8_BAR; PG8_SCHED;
	s_add_i32 s42, s60, s47
	v_lshl_add_u64 v[162:163], v[162:163], 0, s[18:19]
	s_mov_b32 m0, s42
	ds_read_b128 v[188:191], v168 offset:49152
	ds_read_b128 v[192:195], v168 offset:50176
	ds_read_b128 v[196:199], v168 offset:51200
	ds_read_b128 v[200:203], v168 offset:52224
	ds_read_b128 v[204:207], v168 offset:53248
	ds_read_b128 v[208:211], v168 offset:54272
	ds_read_b128 v[212:215], v168 offset:55296
	ds_read_b128 v[220:223], v168 offset:56320
	global_load_lds_dwordx4 v[162:163], off
	s_add_i32 m0, s42, 0x2000
	s_add_u32 s40, s40, 0x40080
	v_lshl_add_u64 v[162:163], v[216:217], 0, s[18:19]
	s_addc_u32 s41, s41, 0
	s_add_i32 s42, s61, s47
	global_load_lds_dwordx4 v[162:163], off
	v_lshl_add_u64 v[162:163], s[40:41], 0, v[140:141]
	s_mov_b32 m0, s42
	s_nop 0
	global_load_lds_dwordx4 v[162:163], off
	v_lshl_add_u64 v[162:163], s[40:41], 0, v[144:145]
	s_add_i32 m0, s42, 0x2000
	s_nop 0
	global_load_lds_dwordx4 v[162:163], off
	v_lshl_add_u64 v[162:163], v[224:225], 0, s[18:19]
	s_mov_b32 m0, s52
	s_nop 0
	global_load_lds_dwordx4 v[162:163], off
	v_lshl_add_u64 v[162:163], v[226:227], 0, s[18:19]
	s_mov_b32 m0, s53
	s_nop 0
	global_load_lds_dwordx4 v[162:163], off
	s_waitcnt vmcnt(8)
	s_waitcnt lgkmcnt(0)
	s_barrier
	s_setprio 1
	s_waitcnt lgkmcnt(0)
	v_mfma_f32_16x16x32_bf16 v[62:65], v[130:133], v[188:191], v[62:65]
	v_mfma_f32_16x16x32_bf16 v[58:61], v[154:157], v[188:191], v[58:61]
	v_mfma_f32_16x16x32_bf16 v[46:49], v[130:133], v[196:199], v[46:49]
	v_mfma_f32_16x16x32_bf16 v[42:45], v[154:157], v[196:199], v[42:45]
	v_mfma_f32_16x16x32_bf16 v[30:33], v[130:133], v[204:207], v[30:33]
	v_mfma_f32_16x16x32_bf16 v[26:29], v[154:157], v[204:207], v[26:29]
	v_mfma_f32_16x16x32_bf16 v[14:17], v[130:133], v[212:215], v[14:17]
	v_mfma_f32_16x16x32_bf16 v[10:13], v[154:157], v[212:215], v[10:13]
	v_mfma_f32_16x16x32_bf16 v[62:65], v[134:137], v[192:195], v[62:65]
	v_mfma_f32_16x16x32_bf16 v[58:61], v[158:161], v[192:195], v[58:61]
	v_mfma_f32_16x16x32_bf16 v[46:49], v[134:137], v[200:203], v[46:49]
	v_mfma_f32_16x16x32_bf16 v[42:45], v[158:161], v[200:203], v[42:45]
	v_mfma_f32_16x16x32_bf16 v[30:33], v[134:137], v[208:211], v[30:33]
	v_mfma_f32_16x16x32_bf16 v[26:29], v[158:161], v[208:211], v[26:29]
	v_mfma_f32_16x16x32_bf16 v[14:17], v[134:137], v[220:223], v[14:17]
	v_mfma_f32_16x16x32_bf16 v[10:13], v[158:161], v[220:223], v[10:13]
	s_setprio 0
	s_setprio 1
	v_mfma_f32_16x16x32_bf16 v[54:57], v[170:173], v[188:191], v[54:57]
	v_mfma_f32_16x16x32_bf16 v[50:53], v[180:183], v[188:191], v[50:53]
	v_mfma_f32_16x16x32_bf16 v[38:41], v[170:173], v[196:199], v[38:41]
	v_mfma_f32_16x16x32_bf16 v[34:37], v[180:183], v[196:199], v[34:37]
	v_mfma_f32_16x16x32_bf16 v[22:25], v[170:173], v[204:207], v[22:25]
	v_mfma_f32_16x16x32_bf16 v[18:21], v[180:183], v[204:207], v[18:21]
	v_mfma_f32_16x16x32_bf16 v[6:9], v[170:173], v[212:215], v[6:9]
	v_mfma_f32_16x16x32_bf16 v[2:5], v[180:183], v[212:215], v[2:5]
	v_mfma_f32_16x16x32_bf16 v[54:57], v[176:179], v[192:195], v[54:57]
	v_mfma_f32_16x16x32_bf16 v[50:53], v[184:187], v[192:195], v[50:53]
	v_mfma_f32_16x16x32_bf16 v[38:41], v[176:179], v[200:203], v[38:41]
	v_mfma_f32_16x16x32_bf16 v[34:37], v[184:187], v[200:203], v[34:37]
	v_mfma_f32_16x16x32_bf16 v[22:25], v[176:179], v[208:211], v[22:25]
	v_mfma_f32_16x16x32_bf16 v[18:21], v[184:187], v[208:211], v[18:21]
	v_mfma_f32_16x16x32_bf16 v[6:9], v[176:179], v[220:223], v[6:9]
	v_mfma_f32_16x16x32_bf16 v[2:5], v[184:187], v[220:223], v[2:5]
	s_setprio 0
	s_barrier
	s_add_i32 s59, s59, 2
	s_add_u32 s36, s36, 0x100
	s_addc_u32 s37, s37, 0
	s_add_u32 s39, s39, 0x100
	s_addc_u32 s58, s58, 0
	s_cmp_gt_u32 s59, 13
	s_cbranch_scc1 .Lpeel_exit_6

; #define PG8_BAR __builtin_amdgcn_s_barrier()
; template <class Epi, class Sched, bool ALIGN_EPI = false, bool SP2 = false>
; __device__ __forceinline__ void gemm_phase(PG8_LAS unsigned char* lds, const Gemm g, const Sched& S, const Epi& E) {
;     ...
;         if constexpr (ALIGN_EPI) { if (wr == 0) PG8_BAR; }
.Lpeel_exit_6:
	s_and_b64 vcc, exec, s[20:21]
	s_cbranch_vccz .LBB0_1084
	s_barrier

; #define PG8_STAGE(bufoff, gbase, voff) do { _Pragma("unroll") for (int _i = 0; _i < 2; ++_i) \
;         __builtin_amdgcn_global_load_lds((const unsigned*)((const char*)(gbase) + (voff)[_i]), (PG8_LAS unsigned*)(lds + (bufoff) + ldsw + _i * 8192), 16, 0, 0); } while (0)
; #define PG8_LDA(dst, b, h) do { _Pragma("unroll") for (int m = 0; m < 4; ++m) _Pragma("unroll") for (int k = 0; k < 2; ++k) dst[m][k] = *(const PG8_LAS bf16x8*)(lds + PG8_SA(b, h) + aoff + m * 2048 + k * 1024); } while (0)
; #define PG8_LDB(dst, b, h) do { _Pragma("unroll") for (int n = 0; n < 2; ++n) _Pragma("unroll") for (int k = 0; k < 2; ++k) dst[n][k] = *(const PG8_LAS bf16x8*)(lds + PG8_SB(b, h) + boff + n * 2048 + k * 1024); } while (0)
; #define PG8_MMA(ai, bj, At, Bt) do { __builtin_amdgcn_s_setprio(1); _Pragma("unroll") for (int m = 0; m < 4; ++m) _Pragma("unroll") for (int n = 0; n < 2; ++n) _Pragma("unroll") for (int k = 0; k < 2; ++k) \
;         acc[ai][bj][m][n] = __builtin_amdgcn_mfma_f32_16x16x32_bf16(Bt[n][k], At[m][k], acc[ai][bj][m][n], 0, 0, 0); __builtin_amdgcn_s_setprio(0); } while (0)
; #define PG8_BAR __builtin_amdgcn_s_barrier()
; template <class Epi, class Sched, bool ALIGN_EPI = false, bool SP2 = false>
; __device__ __forceinline__ void gemm_phase(PG8_LAS unsigned char* lds, const Gemm g, const Sched& S, const Epi& E) {
;     ...
;             const char* a1 = cA + (size_t)(t + 1) * kstep;
;             const char* a2 = last ? nA : cA + (size_t)(t + 2) * kstep; const char* b2 = last ? nB : cB + (size_t)(t + 2) * kstep;
;             const char* a3 = a2 + kstep; const char* b3 = b2 + kstep;
;             if (last && has_next) S.a_ready(nxt);
;             if constexpr (SP2) {
;             PG8_LDB(B0, 0, 0); PG8_LDB(B1, 0, 1); PG8_SCHED; PG8_LDA(At, 0, 0); PG8_STAGE(PG8_SA(1, 1), a1 + hstepA, voffA);
;             PG8_WAIT_V(8); PG8_WAIT_L(0); PG8_BAR; PG8_MMA(0, 0, At, B0); PG8_MMA(0, 1, At, B1); PG8_BAR; PG8_SCHED;
;             PG8_LDA(At, 0, 1); PG8_STAGE(PG8_SB(0, 0), b2, voffB); PG8_STAGE(PG8_SB(0, 1), b2 + hstepB, voffB); PG8_STAGE(PG8_SA(0, 0), a2, voffA);
;     ...
; #pragma unroll
;         for (int a = 0; a < 2; ++a)
; #pragma unroll
;             for (int b = 0; b < 2; ++b)
; #pragma unroll
;                 for (int m = 0; m < 4; ++m)
; #pragma unroll
;                     for (int n = 0; n < 2; ++n) acc[a][b][m][n] = (f32x4){0.f, 0.f, 0.f, 0.f};
.LBB0_1191:
	s_ashr_i32 s49, s48, 31
	s_lshl_b64 s[38:39], s[48:49], 19
	s_add_u32 s50, s66, s38
	s_addc_u32 s51, s67, s39
	s_and_b64 s[38:39], s[12:13], exec
	s_cselect_b32 s33, s51, s59
	s_cselect_b32 s38, s50, s58
	s_ashr_i32 s47, s46, 31
	s_lshl_b64 s[52:53], s[46:47], 19
	s_add_u32 s52, s68, s52
	s_addc_u32 s53, s69, s53
	s_and_b64 s[62:63], s[12:13], exec
	s_cselect_b32 s39, s53, s61
	s_cselect_b32 s47, s52, s60
	s_add_u32 s49, s60, 0x100
	s_addc_u32 s55, s61, 0
	s_mov_b32 s57, -2
	ds_read_b128 v[60:63], v224
	ds_read_b128 v[64:67], v224 offset:1024
	ds_read_b128 v[72:75], v224 offset:2048
	ds_read_b128 v[76:79], v224 offset:3072
	ds_read_b128 v[80:83], v225
	ds_read_b128 v[84:87], v225 offset:1024
	ds_read_b128 v[88:91], v225 offset:2048
	ds_read_b128 v[92:95], v225 offset:3072
	s_add_u32 s60, s58, 0x100
	s_addc_u32 s61, s59, 0
	s_cmp_eq_u32 s57, 12
	s_cselect_b32 s65, s33, s61
	s_cselect_b32 s64, s38, s60
	s_cselect_b32 s63, s39, s55
	s_cselect_b32 s62, s47, s49
	v_lshl_add_u64 v[148:149], s[58:59], 0, v[190:191]
	s_add_i32 m0, s71, 0xc000
	ds_read_b128 v[112:115], v226
	ds_read_b128 v[140:143], v226 offset:1024
	ds_read_b128 v[170:173], v226 offset:2048
	ds_read_b128 v[174:177], v226 offset:3072
	ds_read_b128 v[178:181], v226 offset:4096
	ds_read_b128 v[198:201], v226 offset:5120
	ds_read_b128 v[202:205], v226 offset:6144
	ds_read_b128 v[206:209], v226 offset:7168
	global_load_lds_dwordx4 v[148:149], off
	v_lshl_add_u64 v[148:149], s[58:59], 0, v[192:193]
	s_add_i32 m0, s71, 0xe000
	s_nop 0
	global_load_lds_dwordx4 v[148:149], off
	s_waitcnt vmcnt(8)
	s_waitcnt lgkmcnt(0)
	s_barrier
	s_setprio 1
	s_waitcnt lgkmcnt(0)
	v_mfma_f32_16x16x32_bf16 v[154:157], v[60:63], v[112:115], 0
	v_mfma_f32_16x16x32_bf16 v[158:161], v[72:75], v[112:115], 0
	v_mfma_f32_16x16x32_bf16 v[128:131], v[60:63], v[170:173], 0
	v_mfma_f32_16x16x32_bf16 v[124:127], v[72:75], v[170:173], 0
	v_mfma_f32_16x16x32_bf16 v[162:165], v[60:63], v[178:181], 0
	v_mfma_f32_16x16x32_bf16 v[148:151], v[72:75], v[178:181], 0
	v_mfma_f32_16x16x32_bf16 v[166:169], v[60:63], v[202:205], 0
	v_mfma_f32_16x16x32_bf16 v[144:147], v[72:75], v[202:205], 0
	v_mfma_f32_16x16x32_bf16 v[154:157], v[64:67], v[140:143], v[154:157]
	v_mfma_f32_16x16x32_bf16 v[158:161], v[76:79], v[140:143], v[158:161]
	v_mfma_f32_16x16x32_bf16 v[128:131], v[64:67], v[174:177], v[128:131]
	v_mfma_f32_16x16x32_bf16 v[124:127], v[76:79], v[174:177], v[124:127]
	v_mfma_f32_16x16x32_bf16 v[162:165], v[64:67], v[198:201], v[162:165]
	v_mfma_f32_16x16x32_bf16 v[148:151], v[76:79], v[198:201], v[148:151]
	v_mfma_f32_16x16x32_bf16 v[166:169], v[64:67], v[206:209], v[166:169]
	v_mfma_f32_16x16x32_bf16 v[144:147], v[76:79], v[206:209], v[144:147]
	s_setprio 0
	s_setprio 1
	v_mfma_f32_16x16x32_bf16 v[136:139], v[80:83], v[112:115], 0
	v_mfma_f32_16x16x32_bf16 v[120:123], v[80:83], v[170:173], 0
	v_mfma_f32_16x16x32_bf16 v[116:119], v[88:91], v[170:173], 0
	v_mfma_f32_16x16x32_bf16 v[104:107], v[80:83], v[178:181], 0
	v_mfma_f32_16x16x32_bf16 v[108:111], v[88:91], v[178:181], 0
	v_mfma_f32_16x16x32_bf16 v[96:99], v[80:83], v[202:205], 0
	v_mfma_f32_16x16x32_bf16 v[100:103], v[88:91], v[202:205], 0
	v_mfma_f32_16x16x32_bf16 v[136:139], v[84:87], v[140:143], v[136:139]
	v_mfma_f32_16x16x32_bf16 v[112:115], v[88:91], v[112:115], 0
	v_mfma_f32_16x16x32_bf16 v[120:123], v[84:87], v[174:177], v[120:123]
	v_mfma_f32_16x16x32_bf16 v[116:119], v[92:95], v[174:177], v[116:119]
	v_mfma_f32_16x16x32_bf16 v[104:107], v[84:87], v[198:201], v[104:107]
	v_mfma_f32_16x16x32_bf16 v[108:111], v[92:95], v[198:201], v[108:111]
	v_mfma_f32_16x16x32_bf16 v[96:99], v[84:87], v[206:209], v[96:99]
	v_mfma_f32_16x16x32_bf16 v[100:103], v[92:95], v[206:209], v[100:103]
	v_mfma_f32_16x16x32_bf16 v[112:115], v[92:95], v[140:143], v[112:115]
	s_setprio 0
	s_barrier
	s_add_i32 s58, s90, s70
	v_lshl_add_u64 v[210:211], s[62:63], 0, v[184:185]
	s_mov_b32 m0, s58
	ds_read_b128 v[132:135], v226 offset:16384
	ds_read_b128 v[140:143], v226 offset:17408
	ds_read_b128 v[170:173], v226 offset:18432
	ds_read_b128 v[174:177], v226 offset:19456
	ds_read_b128 v[178:181], v226 offset:20480
	ds_read_b128 v[198:201], v226 offset:21504
	ds_read_b128 v[202:205], v226 offset:22528
	ds_read_b128 v[206:209], v226 offset:23552
	global_load_lds_dwordx4 v[210:211], off
	s_add_i32 m0, s58, 0x2000
	s_add_u32 s58, s62, 0x40000
	v_lshl_add_u64 v[212:213], s[62:63], 0, v[188:189]
	s_addc_u32 s59, s63, 0
	s_add_i32 s72, s91, s70
	global_load_lds_dwordx4 v[212:213], off
	v_lshl_add_u64 v[152:153], s[58:59], 0, v[184:185]
	s_mov_b32 m0, s72
	v_lshl_add_u64 v[214:215], s[64:65], 0, v[182:183]
	global_load_lds_dwordx4 v[152:153], off
	v_lshl_add_u64 v[152:153], s[58:59], 0, v[188:189]
	s_add_i32 m0, s72, 0x2000
	v_lshl_add_u64 v[216:217], s[64:65], 0, v[186:187]
	global_load_lds_dwordx4 v[152:153], off
	s_mov_b32 m0, s71
	s_nop 0
	global_load_lds_dwordx4 v[214:215], off
	s_mov_b32 m0, s76
	s_nop 0
	global_load_lds_dwordx4 v[216:217], off
	s_waitcnt vmcnt(8)
	s_waitcnt lgkmcnt(0)
	s_barrier
; #define PG8_STAGE(bufoff, gbase, voff) do { _Pragma("unroll") for (int _i = 0; _i < 2; ++_i) \
;         __builtin_amdgcn_global_load_lds((const unsigned*)((const char*)(gbase) + (voff)[_i]), (PG8_LAS unsigned*)(lds + (bufoff) + ldsw + _i * 8192), 16, 0, 0); } while (0)
; #define PG8_LDA(dst, b, h) do { _Pragma("unroll") for (int m = 0; m < 4; ++m) _Pragma("unroll") for (int k = 0; k < 2; ++k) dst[m][k] = *(const PG8_LAS bf16x8*)(lds + PG8_SA(b, h) + aoff + m * 2048 + k * 1024); } while (0)
; #define PG8_LDB(dst, b, h) do { _Pragma("unroll") for (int n = 0; n < 2; ++n) _Pragma("unroll") for (int k = 0; k < 2; ++k) dst[n][k] = *(const PG8_LAS bf16x8*)(lds + PG8_SB(b, h) + boff + n * 2048 + k * 1024); } while (0)
; #define PG8_MMA(ai, bj, At, Bt) do { __builtin_amdgcn_s_setprio(1); _Pragma("unroll") for (int m = 0; m < 4; ++m) _Pragma("unroll") for (int n = 0; n < 2; ++n) _Pragma("unroll") for (int k = 0; k < 2; ++k) \
;         acc[ai][bj][m][n] = __builtin_amdgcn_mfma_f32_16x16x32_bf16(Bt[n][k], At[m][k], acc[ai][bj][m][n], 0, 0, 0); __builtin_amdgcn_s_setprio(0); } while (0)
; #define PG8_WAIT_V(n) asm volatile("s_waitcnt vmcnt(" #n ")" ::: "memory")
; #define PG8_WAIT_L(n) asm volatile("s_waitcnt lgkmcnt(" #n ")" ::: "memory")
; #define PG8_BAR __builtin_amdgcn_s_barrier()
; #define PG8_SCHED __builtin_amdgcn_sched_barrier(0)
; template <class Epi, class Sched, bool ALIGN_EPI = false, bool SP2 = false>
; __device__ __forceinline__ void gemm_phase(PG8_LAS unsigned char* lds, const Gemm g, const Sched& S, const Epi& E) {
;     ...
;             PG8_WAIT_V(8); PG8_WAIT_L(0); PG8_BAR; PG8_MMA(1, 0, At, B0); PG8_MMA(1, 1, At, B1); PG8_BAR; PG8_SCHED;
;             PG8_LDB(B0, 1, 0); PG8_LDB(B1, 1, 1); PG8_SCHED; PG8_LDA(At, 1, 0); PG8_STAGE(PG8_SA(0, 1), a2 + hstepA, voffA);
;             PG8_WAIT_V(8); PG8_WAIT_L(0); PG8_BAR; PG8_MMA(0, 0, At, B0); PG8_MMA(0, 1, At, B1); PG8_BAR; PG8_SCHED;
	s_setprio 1
	s_waitcnt lgkmcnt(0)
	v_mfma_f32_16x16x32_bf16 v[48:51], v[60:63], v[132:135], 0
	v_mfma_f32_16x16x32_bf16 v[52:55], v[72:75], v[132:135], 0
	v_mfma_f32_16x16x32_bf16 v[28:31], v[60:63], v[170:173], 0
	v_mfma_f32_16x16x32_bf16 v[24:27], v[72:75], v[170:173], 0
	v_mfma_f32_16x16x32_bf16 v[68:71], v[60:63], v[178:181], 0
	v_mfma_f32_16x16x32_bf16 v[44:47], v[72:75], v[178:181], 0
	v_mfma_f32_16x16x32_bf16 v[56:59], v[60:63], v[202:205], 0
	v_mfma_f32_16x16x32_bf16 v[40:43], v[72:75], v[202:205], 0
	v_mfma_f32_16x16x32_bf16 v[48:51], v[64:67], v[140:143], v[48:51]
	v_mfma_f32_16x16x32_bf16 v[52:55], v[76:79], v[140:143], v[52:55]
	v_mfma_f32_16x16x32_bf16 v[28:31], v[64:67], v[174:177], v[28:31]
	v_mfma_f32_16x16x32_bf16 v[24:27], v[76:79], v[174:177], v[24:27]
	v_mfma_f32_16x16x32_bf16 v[68:71], v[64:67], v[198:201], v[68:71]
	v_mfma_f32_16x16x32_bf16 v[44:47], v[76:79], v[198:201], v[44:47]
	v_mfma_f32_16x16x32_bf16 v[56:59], v[64:67], v[206:209], v[56:59]
	v_mfma_f32_16x16x32_bf16 v[40:43], v[76:79], v[206:209], v[40:43]
	s_setprio 0
	s_setprio 1
	v_mfma_f32_16x16x32_bf16 v[36:39], v[80:83], v[132:135], 0
	v_mfma_f32_16x16x32_bf16 v[32:35], v[88:91], v[132:135], 0
	v_mfma_f32_16x16x32_bf16 v[20:23], v[80:83], v[170:173], 0
	v_mfma_f32_16x16x32_bf16 v[16:19], v[88:91], v[170:173], 0
	v_mfma_f32_16x16x32_bf16 v[12:15], v[80:83], v[178:181], 0
	v_mfma_f32_16x16x32_bf16 v[8:11], v[88:91], v[178:181], 0
	v_mfma_f32_16x16x32_bf16 v[4:7], v[80:83], v[202:205], 0
	v_mfma_f32_16x16x32_bf16 v[0:3], v[88:91], v[202:205], 0
	v_mfma_f32_16x16x32_bf16 v[36:39], v[84:87], v[140:143], v[36:39]
	v_mfma_f32_16x16x32_bf16 v[32:35], v[92:95], v[140:143], v[32:35]
	v_mfma_f32_16x16x32_bf16 v[20:23], v[84:87], v[174:177], v[20:23]
	v_mfma_f32_16x16x32_bf16 v[16:19], v[92:95], v[174:177], v[16:19]
	v_mfma_f32_16x16x32_bf16 v[12:15], v[84:87], v[198:201], v[12:15]
	v_mfma_f32_16x16x32_bf16 v[8:11], v[92:95], v[198:201], v[8:11]
	v_mfma_f32_16x16x32_bf16 v[4:7], v[84:87], v[206:209], v[4:7]
	v_mfma_f32_16x16x32_bf16 v[0:3], v[92:95], v[206:209], v[0:3]
	s_setprio 0
	s_barrier
	s_add_i32 s72, 0, 0x18000
	s_add_i32 s73, 0, 0x1c000
	v_add_u32_e32 v76, s72, v219
	v_add_u32_e32 v92, s73, v219
	ds_read_b128 v[60:63], v76
	ds_read_b128 v[64:67], v76 offset:1024
	ds_read_b128 v[72:75], v76 offset:2048
	ds_read_b128 v[76:79], v76 offset:3072
	ds_read_b128 v[80:83], v92
	ds_read_b128 v[84:87], v92 offset:1024
	ds_read_b128 v[88:91], v92 offset:2048
	ds_read_b128 v[92:95], v92 offset:3072
	s_add_u32 s58, s64, 0x40000
	s_addc_u32 s59, s65, 0
	s_mov_b32 m0, s77
	v_lshl_add_u64 v[152:153], s[58:59], 0, v[182:183]
	ds_read_b128 v[132:135], v226 offset:32768
	ds_read_b128 v[140:143], v226 offset:33792
	ds_read_b128 v[170:173], v226 offset:34816
	ds_read_b128 v[174:177], v226 offset:35840
	ds_read_b128 v[178:181], v226 offset:36864
	ds_read_b128 v[198:201], v226 offset:37888
	ds_read_b128 v[202:205], v226 offset:38912
	ds_read_b128 v[206:209], v226 offset:39936
	global_load_lds_dwordx4 v[152:153], off
	v_lshl_add_u64 v[152:153], s[58:59], 0, v[186:187]
	s_mov_b32 m0, s78
	s_nop 0
	global_load_lds_dwordx4 v[152:153], off
	s_waitcnt vmcnt(8)
	s_waitcnt lgkmcnt(0)
	s_barrier
	s_setprio 1
	s_waitcnt lgkmcnt(0)
	v_mfma_f32_16x16x32_bf16 v[152:155], v[60:63], v[132:135], v[154:157]
	v_mfma_f32_16x16x32_bf16 v[158:161], v[72:75], v[132:135], v[158:161]
	v_mfma_f32_16x16x32_bf16 v[128:131], v[60:63], v[170:173], v[128:131]
	v_mfma_f32_16x16x32_bf16 v[124:127], v[72:75], v[170:173], v[124:127]
	v_mfma_f32_16x16x32_bf16 v[162:165], v[60:63], v[178:181], v[162:165]
	v_mfma_f32_16x16x32_bf16 v[148:151], v[72:75], v[178:181], v[148:151]
	v_mfma_f32_16x16x32_bf16 v[166:169], v[60:63], v[202:205], v[166:169]
	v_mfma_f32_16x16x32_bf16 v[144:147], v[72:75], v[202:205], v[144:147]
	v_mfma_f32_16x16x32_bf16 v[154:157], v[64:67], v[140:143], v[152:155]
	v_mfma_f32_16x16x32_bf16 v[158:161], v[76:79], v[140:143], v[158:161]
	v_mfma_f32_16x16x32_bf16 v[128:131], v[64:67], v[174:177], v[128:131]
	v_mfma_f32_16x16x32_bf16 v[124:127], v[76:79], v[174:177], v[124:127]
	v_mfma_f32_16x16x32_bf16 v[162:165], v[64:67], v[198:201], v[162:165]
	v_mfma_f32_16x16x32_bf16 v[150:153], v[76:79], v[198:201], v[148:151]
	v_mfma_f32_16x16x32_bf16 v[166:169], v[64:67], v[206:209], v[166:169]
	v_mfma_f32_16x16x32_bf16 v[144:147], v[76:79], v[206:209], v[144:147]
	s_setprio 0
	s_setprio 1
	v_mfma_f32_16x16x32_bf16 v[112:115], v[88:91], v[132:135], v[112:115]
	v_mfma_f32_16x16x32_bf16 v[136:139], v[80:83], v[132:135], v[136:139]
	v_mfma_f32_16x16x32_bf16 v[132:135], v[92:95], v[140:143], v[112:115]
	v_mfma_f32_16x16x32_bf16 v[112:115], v[80:83], v[170:173], v[120:123]
	v_mfma_f32_16x16x32_bf16 v[120:123], v[84:87], v[174:177], v[112:115]
	v_mfma_f32_16x16x32_bf16 v[112:115], v[88:91], v[170:173], v[116:119]
	v_mfma_f32_16x16x32_bf16 v[104:107], v[80:83], v[178:181], v[104:107]
	v_mfma_f32_16x16x32_bf16 v[108:111], v[88:91], v[178:181], v[108:111]
	v_mfma_f32_16x16x32_bf16 v[96:99], v[80:83], v[202:205], v[96:99]
	v_mfma_f32_16x16x32_bf16 v[100:103], v[88:91], v[202:205], v[100:103]
	v_mfma_f32_16x16x32_bf16 v[136:139], v[84:87], v[140:143], v[136:139]
	v_mfma_f32_16x16x32_bf16 v[116:119], v[92:95], v[174:177], v[112:115]
	v_mfma_f32_16x16x32_bf16 v[104:107], v[84:87], v[198:201], v[104:107]
	v_mfma_f32_16x16x32_bf16 v[108:111], v[92:95], v[198:201], v[108:111]
	v_mfma_f32_16x16x32_bf16 v[96:99], v[84:87], v[206:209], v[96:99]
	v_mfma_f32_16x16x32_bf16 v[100:103], v[92:95], v[206:209], v[100:103]
	s_setprio 0
	s_barrier
; #define PG8_STAGE(bufoff, gbase, voff) do { _Pragma("unroll") for (int _i = 0; _i < 2; ++_i) \
;         __builtin_amdgcn_global_load_lds((const unsigned*)((const char*)(gbase) + (voff)[_i]), (PG8_LAS unsigned*)(lds + (bufoff) + ldsw + _i * 8192), 16, 0, 0); } while (0)
; #define PG8_LDA(dst, b, h) do { _Pragma("unroll") for (int m = 0; m < 4; ++m) _Pragma("unroll") for (int k = 0; k < 2; ++k) dst[m][k] = *(const PG8_LAS bf16x8*)(lds + PG8_SA(b, h) + aoff + m * 2048 + k * 1024); } while (0)
; #define PG8_MMA(ai, bj, At, Bt) do { __builtin_amdgcn_s_setprio(1); _Pragma("unroll") for (int m = 0; m < 4; ++m) _Pragma("unroll") for (int n = 0; n < 2; ++n) _Pragma("unroll") for (int k = 0; k < 2; ++k) \
;         acc[ai][bj][m][n] = __builtin_amdgcn_mfma_f32_16x16x32_bf16(Bt[n][k], At[m][k], acc[ai][bj][m][n], 0, 0, 0); __builtin_amdgcn_s_setprio(0); } while (0)
; #define PG8_WAIT_V(n) asm volatile("s_waitcnt vmcnt(" #n ")" ::: "memory")
; #define PG8_WAIT_L(n) asm volatile("s_waitcnt lgkmcnt(" #n ")" ::: "memory")
; #define PG8_BAR __builtin_amdgcn_s_barrier()
; #define PG8_SCHED __builtin_amdgcn_sched_barrier(0)
; template <class Epi, class Sched, bool ALIGN_EPI = false, bool SP2 = false>
; __device__ __forceinline__ void gemm_phase(PG8_LAS unsigned char* lds, const Gemm g, const Sched& S, const Epi& E) {
;     ...
;         for (int t = 0; t < nt; t += 2) {
;     ...
;             PG8_LDA(At, 1, 1); PG8_STAGE(PG8_SB(1, 0), b3, voffB); PG8_STAGE(PG8_SB(1, 1), b3 + hstepB, voffB); PG8_STAGE(PG8_SA(1, 0), a3, voffA);
;             PG8_WAIT_V(8); PG8_WAIT_L(0); PG8_BAR; PG8_MMA(1, 0, At, B0); PG8_MMA(1, 1, At, B1); PG8_BAR; PG8_SCHED;
	s_add_i32 s58, s72, s70
	v_lshl_add_u64 v[148:149], v[210:211], 0, s[26:27]
	s_mov_b32 m0, s58
	ds_read_b128 v[112:115], v226 offset:49152
	ds_read_b128 v[140:143], v226 offset:50176
	ds_read_b128 v[170:173], v226 offset:51200
	ds_read_b128 v[174:177], v226 offset:52224
	ds_read_b128 v[178:181], v226 offset:53248
	ds_read_b128 v[198:201], v226 offset:54272
	ds_read_b128 v[202:205], v226 offset:55296
	ds_read_b128 v[206:209], v226 offset:56320
	global_load_lds_dwordx4 v[148:149], off
	s_add_i32 m0, s58, 0x2000
	s_add_u32 s58, s62, 0x40080
	v_lshl_add_u64 v[148:149], v[212:213], 0, s[26:27]
	s_addc_u32 s59, s63, 0
	s_add_i32 s62, s73, s70
	global_load_lds_dwordx4 v[148:149], off
	v_lshl_add_u64 v[148:149], s[58:59], 0, v[184:185]
	s_mov_b32 m0, s62
	s_nop 0
	global_load_lds_dwordx4 v[148:149], off
	v_lshl_add_u64 v[148:149], s[58:59], 0, v[188:189]
	s_add_i32 m0, s62, 0x2000
	s_nop 0
	global_load_lds_dwordx4 v[148:149], off
	v_lshl_add_u64 v[148:149], v[214:215], 0, s[26:27]
	s_mov_b32 m0, s86
	s_nop 0
	global_load_lds_dwordx4 v[148:149], off
	v_lshl_add_u64 v[148:149], v[216:217], 0, s[26:27]
	s_mov_b32 m0, s87
	s_nop 0
	global_load_lds_dwordx4 v[148:149], off
	s_waitcnt vmcnt(8)
	s_waitcnt lgkmcnt(0)
	s_barrier
	s_setprio 1
	s_waitcnt lgkmcnt(0)
	v_mfma_f32_16x16x32_bf16 v[48:51], v[60:63], v[112:115], v[48:51]
	v_mfma_f32_16x16x32_bf16 v[52:55], v[72:75], v[112:115], v[52:55]
	v_mfma_f32_16x16x32_bf16 v[28:31], v[60:63], v[170:173], v[28:31]
	v_mfma_f32_16x16x32_bf16 v[24:27], v[72:75], v[170:173], v[24:27]
	v_mfma_f32_16x16x32_bf16 v[68:71], v[60:63], v[178:181], v[68:71]
	v_mfma_f32_16x16x32_bf16 v[44:47], v[72:75], v[178:181], v[44:47]
	v_mfma_f32_16x16x32_bf16 v[56:59], v[60:63], v[202:205], v[56:59]
	v_mfma_f32_16x16x32_bf16 v[40:43], v[72:75], v[202:205], v[40:43]
	v_mfma_f32_16x16x32_bf16 v[48:51], v[64:67], v[140:143], v[48:51]
	v_mfma_f32_16x16x32_bf16 v[52:55], v[76:79], v[140:143], v[52:55]
	v_mfma_f32_16x16x32_bf16 v[28:31], v[64:67], v[174:177], v[28:31]
	v_mfma_f32_16x16x32_bf16 v[24:27], v[76:79], v[174:177], v[24:27]
	v_mfma_f32_16x16x32_bf16 v[68:71], v[64:67], v[198:201], v[68:71]
	v_mfma_f32_16x16x32_bf16 v[44:47], v[76:79], v[198:201], v[44:47]
	v_mfma_f32_16x16x32_bf16 v[56:59], v[64:67], v[206:209], v[56:59]
	v_mfma_f32_16x16x32_bf16 v[40:43], v[76:79], v[206:209], v[40:43]
	s_setprio 0
	s_setprio 1
	v_mfma_f32_16x16x32_bf16 v[36:39], v[80:83], v[112:115], v[36:39]
	v_mfma_f32_16x16x32_bf16 v[32:35], v[88:91], v[112:115], v[32:35]
	v_mfma_f32_16x16x32_bf16 v[20:23], v[80:83], v[170:173], v[20:23]
	v_mfma_f32_16x16x32_bf16 v[16:19], v[88:91], v[170:173], v[16:19]
	v_mfma_f32_16x16x32_bf16 v[12:15], v[80:83], v[178:181], v[12:15]
	v_mfma_f32_16x16x32_bf16 v[8:11], v[88:91], v[178:181], v[8:11]
	v_mfma_f32_16x16x32_bf16 v[4:7], v[80:83], v[202:205], v[4:7]
	v_mfma_f32_16x16x32_bf16 v[0:3], v[88:91], v[202:205], v[0:3]
	v_mfma_f32_16x16x32_bf16 v[36:39], v[84:87], v[140:143], v[36:39]
	v_mfma_f32_16x16x32_bf16 v[32:35], v[92:95], v[140:143], v[32:35]
	v_mfma_f32_16x16x32_bf16 v[20:23], v[84:87], v[174:177], v[20:23]
	v_mfma_f32_16x16x32_bf16 v[16:19], v[92:95], v[174:177], v[16:19]
	v_mfma_f32_16x16x32_bf16 v[12:15], v[84:87], v[198:201], v[12:15]
	v_mfma_f32_16x16x32_bf16 v[8:11], v[92:95], v[198:201], v[8:11]
	v_mfma_f32_16x16x32_bf16 v[4:7], v[84:87], v[206:209], v[4:7]
	v_mfma_f32_16x16x32_bf16 v[0:3], v[92:95], v[206:209], v[0:3]
	s_setprio 0
	s_barrier
	s_add_i32 s57, s57, 2
	s_add_u32 s49, s49, 0x100
	s_addc_u32 s55, s55, 0
	s_cmp_gt_u32 s57, 13
	s_mov_b64 s[58:59], s[60:61]
	s_cbranch_scc1 .Lpeel_exit_7

; #define PG8_BAR __builtin_amdgcn_s_barrier()
; template <class Epi, class Sched, bool ALIGN_EPI = false, bool SP2 = false>
; __device__ __forceinline__ void gemm_phase(PG8_LAS unsigned char* lds, const Gemm g, const Sched& S, const Epi& E) {
;     ...
;         if constexpr (ALIGN_EPI) { if (wr == 0) PG8_BAR; }
.Lpeel_exit_7:
	s_and_b64 vcc, exec, s[28:29]
	s_cbranch_vccz .LBB0_1195
	s_barrier

; #define PG8_STAGE(bufoff, gbase, voff) do { _Pragma("unroll") for (int _i = 0; _i < 2; ++_i) \
;         __builtin_amdgcn_global_load_lds((const unsigned*)((const char*)(gbase) + (voff)[_i]), (PG8_LAS unsigned*)(lds + (bufoff) + ldsw + _i * 8192), 16, 0, 0); } while (0)
; #define PG8_LDA(dst, b, h) do { _Pragma("unroll") for (int m = 0; m < 4; ++m) _Pragma("unroll") for (int k = 0; k < 2; ++k) dst[m][k] = *(const PG8_LAS bf16x8*)(lds + PG8_SA(b, h) + aoff + m * 2048 + k * 1024); } while (0)
; #define PG8_LDB(dst, b, h) do { _Pragma("unroll") for (int n = 0; n < 2; ++n) _Pragma("unroll") for (int k = 0; k < 2; ++k) dst[n][k] = *(const PG8_LAS bf16x8*)(lds + PG8_SB(b, h) + boff + n * 2048 + k * 1024); } while (0)
; #define PG8_MMA(ai, bj, At, Bt) do { __builtin_amdgcn_s_setprio(1); _Pragma("unroll") for (int m = 0; m < 4; ++m) _Pragma("unroll") for (int n = 0; n < 2; ++n) _Pragma("unroll") for (int k = 0; k < 2; ++k) \
;         acc[ai][bj][m][n] = __builtin_amdgcn_mfma_f32_16x16x32_bf16(Bt[n][k], At[m][k], acc[ai][bj][m][n], 0, 0, 0); __builtin_amdgcn_s_setprio(0); } while (0)
; #define PG8_BAR __builtin_amdgcn_s_barrier()
; template <class Epi, class Sched, bool ALIGN_EPI = false, bool SP2 = false>
; __device__ __forceinline__ void gemm_phase(PG8_LAS unsigned char* lds, const Gemm g, const Sched& S, const Epi& E) {
;     ...
;             const char* a1 = cA + (size_t)(t + 1) * kstep;
;             const char* a2 = last ? nA : cA + (size_t)(t + 2) * kstep; const char* b2 = last ? nB : cB + (size_t)(t + 2) * kstep;
;             const char* a3 = a2 + kstep; const char* b3 = b2 + kstep;
;             if (last && has_next) S.a_ready(nxt);
;             if constexpr (SP2) {
;             PG8_LDB(B0, 0, 0); PG8_LDB(B1, 0, 1); PG8_SCHED; PG8_LDA(At, 0, 0); PG8_STAGE(PG8_SA(1, 1), a1 + hstepA, voffA);
;             PG8_WAIT_V(8); PG8_WAIT_L(0); PG8_BAR; PG8_MMA(0, 0, At, B0); PG8_MMA(0, 1, At, B1); PG8_BAR; PG8_SCHED;
;             PG8_LDA(At, 0, 1); PG8_STAGE(PG8_SB(0, 0), b2, voffB); PG8_STAGE(PG8_SB(0, 1), b2 + hstepB, voffB); PG8_STAGE(PG8_SA(0, 0), a2, voffA);
;     ...
; #pragma unroll
;         for (int a = 0; a < 2; ++a)
; #pragma unroll
;             for (int b = 0; b < 2; ++b)
; #pragma unroll
;                 for (int m = 0; m < 4; ++m)
; #pragma unroll
;                     for (int n = 0; n < 2; ++n) acc[a][b][m][n] = (f32x4){0.f, 0.f, 0.f, 0.f};
.LBB0_1328:
	s_add_u32 s47, s20, 0x100
	s_addc_u32 s48, s21, 0
	s_mov_b32 s49, -2
	ds_read_b128 v[144:147], v155
	ds_read_b128 v[148:151], v155 offset:1024
	ds_read_b128 v[158:161], v155 offset:2048
	ds_read_b128 v[162:165], v155 offset:3072
	ds_read_b128 v[166:169], v156
	ds_read_b128 v[170:173], v156 offset:1024
	ds_read_b128 v[174:177], v156 offset:2048
	ds_read_b128 v[178:181], v156 offset:3072
	s_add_u32 s20, s18, 0x100
	s_addc_u32 s21, s19, 0
	s_cmp_eq_u32 s49, 40
	s_cselect_b32 s25, s5, s21
	s_cselect_b32 s24, s4, s20
	s_cselect_b32 s23, s17, s48
	s_cselect_b32 s22, s16, s47
	v_lshl_add_u64 v[214:215], s[18:19], 0, v[136:137]
	s_add_i32 m0, s34, 0xc000
	ds_read_b128 v[182:185], v157
	ds_read_b128 v[186:189], v157 offset:1024
	ds_read_b128 v[190:193], v157 offset:2048
	ds_read_b128 v[194:197], v157 offset:3072
	ds_read_b128 v[198:201], v157 offset:4096
	ds_read_b128 v[202:205], v157 offset:5120
	ds_read_b128 v[206:209], v157 offset:6144
	ds_read_b128 v[210:213], v157 offset:7168
	global_load_lds_dwordx4 v[214:215], off
	v_lshl_add_u64 v[214:215], s[18:19], 0, v[138:139]
	s_add_i32 m0, s34, 0xe000
	s_nop 0
	global_load_lds_dwordx4 v[214:215], off
	s_waitcnt vmcnt(8)
	s_waitcnt lgkmcnt(0)
	s_barrier
	s_setprio 1
	s_waitcnt lgkmcnt(0)
	v_mfma_f32_16x16x32_bf16 v[124:127], v[144:147], v[182:185], 0
	v_mfma_f32_16x16x32_bf16 v[120:123], v[158:161], v[182:185], 0
	v_mfma_f32_16x16x32_bf16 v[112:115], v[144:147], v[190:193], 0
	v_mfma_f32_16x16x32_bf16 v[104:107], v[158:161], v[190:193], 0
	v_mfma_f32_16x16x32_bf16 v[92:95], v[144:147], v[198:201], 0
	v_mfma_f32_16x16x32_bf16 v[88:91], v[158:161], v[198:201], 0
	v_mfma_f32_16x16x32_bf16 v[80:83], v[144:147], v[206:209], 0
	v_mfma_f32_16x16x32_bf16 v[72:75], v[158:161], v[206:209], 0
	v_mfma_f32_16x16x32_bf16 v[124:127], v[148:151], v[186:189], v[124:127]
	v_mfma_f32_16x16x32_bf16 v[120:123], v[162:165], v[186:189], v[120:123]
	v_mfma_f32_16x16x32_bf16 v[112:115], v[148:151], v[194:197], v[112:115]
	v_mfma_f32_16x16x32_bf16 v[104:107], v[162:165], v[194:197], v[104:107]
	v_mfma_f32_16x16x32_bf16 v[92:95], v[148:151], v[202:205], v[92:95]
	v_mfma_f32_16x16x32_bf16 v[88:91], v[162:165], v[202:205], v[88:91]
	v_mfma_f32_16x16x32_bf16 v[80:83], v[148:151], v[210:213], v[80:83]
	v_mfma_f32_16x16x32_bf16 v[72:75], v[162:165], v[210:213], v[72:75]
	s_setprio 0
	s_setprio 1
	v_mfma_f32_16x16x32_bf16 v[116:119], v[166:169], v[182:185], 0
	v_mfma_f32_16x16x32_bf16 v[108:111], v[174:177], v[182:185], 0
	v_mfma_f32_16x16x32_bf16 v[100:103], v[166:169], v[190:193], 0
	v_mfma_f32_16x16x32_bf16 v[96:99], v[174:177], v[190:193], 0
	v_mfma_f32_16x16x32_bf16 v[84:87], v[166:169], v[198:201], 0
	v_mfma_f32_16x16x32_bf16 v[76:79], v[174:177], v[198:201], 0
	v_mfma_f32_16x16x32_bf16 v[68:71], v[166:169], v[206:209], 0
	v_mfma_f32_16x16x32_bf16 v[64:67], v[174:177], v[206:209], 0
	v_mfma_f32_16x16x32_bf16 v[116:119], v[170:173], v[186:189], v[116:119]
	v_mfma_f32_16x16x32_bf16 v[108:111], v[178:181], v[186:189], v[108:111]
	v_mfma_f32_16x16x32_bf16 v[100:103], v[170:173], v[194:197], v[100:103]
	v_mfma_f32_16x16x32_bf16 v[96:99], v[178:181], v[194:197], v[96:99]
	v_mfma_f32_16x16x32_bf16 v[84:87], v[170:173], v[202:205], v[84:87]
	v_mfma_f32_16x16x32_bf16 v[76:79], v[178:181], v[202:205], v[76:79]
	v_mfma_f32_16x16x32_bf16 v[68:71], v[170:173], v[210:213], v[68:71]
	v_mfma_f32_16x16x32_bf16 v[64:67], v[178:181], v[210:213], v[64:67]
	s_setprio 0
	s_barrier
	s_add_i32 s18, s41, s33
	v_lshl_add_u64 v[214:215], s[22:23], 0, v[130:131]
	s_mov_b32 m0, s18
	ds_read_b128 v[182:185], v157 offset:16384
	ds_read_b128 v[186:189], v157 offset:17408
	ds_read_b128 v[190:193], v157 offset:18432
	ds_read_b128 v[194:197], v157 offset:19456
	ds_read_b128 v[198:201], v157 offset:20480
	ds_read_b128 v[202:205], v157 offset:21504
	ds_read_b128 v[206:209], v157 offset:22528
	ds_read_b128 v[210:213], v157 offset:23552
	global_load_lds_dwordx4 v[214:215], off
	s_add_i32 m0, s18, 0x2000
	s_add_u32 s18, s22, 0xb0000
	v_lshl_add_u64 v[216:217], s[22:23], 0, v[134:135]
	s_addc_u32 s19, s23, 0
	s_add_i32 s50, s42, s33
	global_load_lds_dwordx4 v[216:217], off
	v_lshl_add_u64 v[218:219], s[18:19], 0, v[130:131]
	s_mov_b32 m0, s50
	v_lshl_add_u64 v[220:221], s[24:25], 0, v[132:133]
	global_load_lds_dwordx4 v[218:219], off
	v_lshl_add_u64 v[218:219], s[18:19], 0, v[134:135]
	s_add_i32 m0, s50, 0x2000
	s_nop 0
	global_load_lds_dwordx4 v[218:219], off
	v_lshl_add_u64 v[218:219], s[24:25], 0, v[128:129]
	s_mov_b32 m0, s34
	s_nop 0
	global_load_lds_dwordx4 v[218:219], off
	s_mov_b32 m0, s35
	s_nop 0
	global_load_lds_dwordx4 v[220:221], off
	s_waitcnt vmcnt(8)
	s_waitcnt lgkmcnt(0)
	s_barrier
; #define PG8_STAGE(bufoff, gbase, voff) do { _Pragma("unroll") for (int _i = 0; _i < 2; ++_i) \
;         __builtin_amdgcn_global_load_lds((const unsigned*)((const char*)(gbase) + (voff)[_i]), (PG8_LAS unsigned*)(lds + (bufoff) + ldsw + _i * 8192), 16, 0, 0); } while (0)
; #define PG8_LDA(dst, b, h) do { _Pragma("unroll") for (int m = 0; m < 4; ++m) _Pragma("unroll") for (int k = 0; k < 2; ++k) dst[m][k] = *(const PG8_LAS bf16x8*)(lds + PG8_SA(b, h) + aoff + m * 2048 + k * 1024); } while (0)
; #define PG8_LDB(dst, b, h) do { _Pragma("unroll") for (int n = 0; n < 2; ++n) _Pragma("unroll") for (int k = 0; k < 2; ++k) dst[n][k] = *(const PG8_LAS bf16x8*)(lds + PG8_SB(b, h) + boff + n * 2048 + k * 1024); } while (0)
; #define PG8_MMA(ai, bj, At, Bt) do { __builtin_amdgcn_s_setprio(1); _Pragma("unroll") for (int m = 0; m < 4; ++m) _Pragma("unroll") for (int n = 0; n < 2; ++n) _Pragma("unroll") for (int k = 0; k < 2; ++k) \
;         acc[ai][bj][m][n] = __builtin_amdgcn_mfma_f32_16x16x32_bf16(Bt[n][k], At[m][k], acc[ai][bj][m][n], 0, 0, 0); __builtin_amdgcn_s_setprio(0); } while (0)
; #define PG8_WAIT_V(n) asm volatile("s_waitcnt vmcnt(" #n ")" ::: "memory")
; #define PG8_WAIT_L(n) asm volatile("s_waitcnt lgkmcnt(" #n ")" ::: "memory")
; #define PG8_BAR __builtin_amdgcn_s_barrier()
; #define PG8_SCHED __builtin_amdgcn_sched_barrier(0)
; template <class Epi, class Sched, bool ALIGN_EPI = false, bool SP2 = false>
; __device__ __forceinline__ void gemm_phase(PG8_LAS unsigned char* lds, const Gemm g, const Sched& S, const Epi& E) {
;     ...
;             PG8_WAIT_V(8); PG8_WAIT_L(0); PG8_BAR; PG8_MMA(1, 0, At, B0); PG8_MMA(1, 1, At, B1); PG8_BAR; PG8_SCHED;
;             PG8_LDB(B0, 1, 0); PG8_LDB(B1, 1, 1); PG8_SCHED; PG8_LDA(At, 1, 0); PG8_STAGE(PG8_SA(0, 1), a2 + hstepA, voffA);
;             PG8_WAIT_V(8); PG8_WAIT_L(0); PG8_BAR; PG8_MMA(0, 0, At, B0); PG8_MMA(0, 1, At, B1); PG8_BAR; PG8_SCHED;
	s_setprio 1
	s_waitcnt lgkmcnt(0)
	v_mfma_f32_16x16x32_bf16 v[60:63], v[144:147], v[182:185], 0
	v_mfma_f32_16x16x32_bf16 v[56:59], v[158:161], v[182:185], 0
	v_mfma_f32_16x16x32_bf16 v[48:51], v[144:147], v[190:193], 0
	v_mfma_f32_16x16x32_bf16 v[40:43], v[158:161], v[190:193], 0
	v_mfma_f32_16x16x32_bf16 v[28:31], v[144:147], v[198:201], 0
	v_mfma_f32_16x16x32_bf16 v[24:27], v[158:161], v[198:201], 0
	v_mfma_f32_16x16x32_bf16 v[20:23], v[144:147], v[206:209], 0
	v_mfma_f32_16x16x32_bf16 v[12:15], v[158:161], v[206:209], 0
	v_mfma_f32_16x16x32_bf16 v[60:63], v[148:151], v[186:189], v[60:63]
	v_mfma_f32_16x16x32_bf16 v[56:59], v[162:165], v[186:189], v[56:59]
	v_mfma_f32_16x16x32_bf16 v[48:51], v[148:151], v[194:197], v[48:51]
	v_mfma_f32_16x16x32_bf16 v[40:43], v[162:165], v[194:197], v[40:43]
	v_mfma_f32_16x16x32_bf16 v[28:31], v[148:151], v[202:205], v[28:31]
	v_mfma_f32_16x16x32_bf16 v[24:27], v[162:165], v[202:205], v[24:27]
	v_mfma_f32_16x16x32_bf16 v[20:23], v[148:151], v[210:213], v[20:23]
	v_mfma_f32_16x16x32_bf16 v[12:15], v[162:165], v[210:213], v[12:15]
	s_setprio 0
	s_setprio 1
	v_mfma_f32_16x16x32_bf16 v[52:55], v[166:169], v[182:185], 0
	v_mfma_f32_16x16x32_bf16 v[44:47], v[174:177], v[182:185], 0
	v_mfma_f32_16x16x32_bf16 v[36:39], v[166:169], v[190:193], 0
	v_mfma_f32_16x16x32_bf16 v[32:35], v[174:177], v[190:193], 0
	v_mfma_f32_16x16x32_bf16 v[16:19], v[166:169], v[198:201], 0
	v_mfma_f32_16x16x32_bf16 v[8:11], v[174:177], v[198:201], 0
	v_mfma_f32_16x16x32_bf16 v[4:7], v[166:169], v[206:209], 0
	v_mfma_f32_16x16x32_bf16 v[0:3], v[174:177], v[206:209], 0
	v_mfma_f32_16x16x32_bf16 v[52:55], v[170:173], v[186:189], v[52:55]
	v_mfma_f32_16x16x32_bf16 v[44:47], v[178:181], v[186:189], v[44:47]
	v_mfma_f32_16x16x32_bf16 v[36:39], v[170:173], v[194:197], v[36:39]
	v_mfma_f32_16x16x32_bf16 v[32:35], v[178:181], v[194:197], v[32:35]
	v_mfma_f32_16x16x32_bf16 v[16:19], v[170:173], v[202:205], v[16:19]
	v_mfma_f32_16x16x32_bf16 v[8:11], v[178:181], v[202:205], v[8:11]
	v_mfma_f32_16x16x32_bf16 v[4:7], v[170:173], v[210:213], v[4:7]
	v_mfma_f32_16x16x32_bf16 v[0:3], v[178:181], v[210:213], v[0:3]
	s_setprio 0
	s_barrier
	s_add_i32 s50, 0, 0x18000
	s_add_i32 s51, 0, 0x1c000
	v_add_u32_e32 v162, s50, v153
	v_add_u32_e32 v178, s51, v153
	ds_read_b128 v[144:147], v162
	ds_read_b128 v[148:151], v162 offset:1024
	ds_read_b128 v[158:161], v162 offset:2048
	ds_read_b128 v[162:165], v162 offset:3072
	ds_read_b128 v[166:169], v178
	ds_read_b128 v[170:173], v178 offset:1024
	ds_read_b128 v[174:177], v178 offset:2048
	ds_read_b128 v[178:181], v178 offset:3072
	s_add_u32 s18, s24, 0xb0000
	s_addc_u32 s19, s25, 0
	s_mov_b32 m0, s36
	v_lshl_add_u64 v[222:223], s[18:19], 0, v[128:129]
	ds_read_b128 v[182:185], v157 offset:32768
	ds_read_b128 v[186:189], v157 offset:33792
	ds_read_b128 v[190:193], v157 offset:34816
	ds_read_b128 v[194:197], v157 offset:35840
	ds_read_b128 v[198:201], v157 offset:36864
	ds_read_b128 v[202:205], v157 offset:37888
	ds_read_b128 v[206:209], v157 offset:38912
	ds_read_b128 v[210:213], v157 offset:39936
	global_load_lds_dwordx4 v[222:223], off
	v_lshl_add_u64 v[222:223], s[18:19], 0, v[132:133]
	s_mov_b32 m0, s37
	s_nop 0
	global_load_lds_dwordx4 v[222:223], off
	s_waitcnt vmcnt(8)
	s_waitcnt lgkmcnt(0)
	s_barrier
	s_setprio 1
	s_waitcnt lgkmcnt(0)
	v_mfma_f32_16x16x32_bf16 v[124:127], v[144:147], v[182:185], v[124:127]
	v_mfma_f32_16x16x32_bf16 v[120:123], v[158:161], v[182:185], v[120:123]
	v_mfma_f32_16x16x32_bf16 v[112:115], v[144:147], v[190:193], v[112:115]
	v_mfma_f32_16x16x32_bf16 v[104:107], v[158:161], v[190:193], v[104:107]
	v_mfma_f32_16x16x32_bf16 v[92:95], v[144:147], v[198:201], v[92:95]
	v_mfma_f32_16x16x32_bf16 v[88:91], v[158:161], v[198:201], v[88:91]
	v_mfma_f32_16x16x32_bf16 v[80:83], v[144:147], v[206:209], v[80:83]
	v_mfma_f32_16x16x32_bf16 v[72:75], v[158:161], v[206:209], v[72:75]
	v_mfma_f32_16x16x32_bf16 v[124:127], v[148:151], v[186:189], v[124:127]
	v_mfma_f32_16x16x32_bf16 v[120:123], v[162:165], v[186:189], v[120:123]
	v_mfma_f32_16x16x32_bf16 v[112:115], v[148:151], v[194:197], v[112:115]
	v_mfma_f32_16x16x32_bf16 v[104:107], v[162:165], v[194:197], v[104:107]
	v_mfma_f32_16x16x32_bf16 v[92:95], v[148:151], v[202:205], v[92:95]
	v_mfma_f32_16x16x32_bf16 v[88:91], v[162:165], v[202:205], v[88:91]
	v_mfma_f32_16x16x32_bf16 v[80:83], v[148:151], v[210:213], v[80:83]
	v_mfma_f32_16x16x32_bf16 v[72:75], v[162:165], v[210:213], v[72:75]
	s_setprio 0
	s_setprio 1
	v_mfma_f32_16x16x32_bf16 v[116:119], v[166:169], v[182:185], v[116:119]
	v_mfma_f32_16x16x32_bf16 v[108:111], v[174:177], v[182:185], v[108:111]
	v_mfma_f32_16x16x32_bf16 v[100:103], v[166:169], v[190:193], v[100:103]
	v_mfma_f32_16x16x32_bf16 v[96:99], v[174:177], v[190:193], v[96:99]
	v_mfma_f32_16x16x32_bf16 v[84:87], v[166:169], v[198:201], v[84:87]
	v_mfma_f32_16x16x32_bf16 v[76:79], v[174:177], v[198:201], v[76:79]
	v_mfma_f32_16x16x32_bf16 v[68:71], v[166:169], v[206:209], v[68:71]
	v_mfma_f32_16x16x32_bf16 v[64:67], v[174:177], v[206:209], v[64:67]
	v_mfma_f32_16x16x32_bf16 v[116:119], v[170:173], v[186:189], v[116:119]
	v_mfma_f32_16x16x32_bf16 v[108:111], v[178:181], v[186:189], v[108:111]
	v_mfma_f32_16x16x32_bf16 v[100:103], v[170:173], v[194:197], v[100:103]
	v_mfma_f32_16x16x32_bf16 v[96:99], v[178:181], v[194:197], v[96:99]
	v_mfma_f32_16x16x32_bf16 v[84:87], v[170:173], v[202:205], v[84:87]
	v_mfma_f32_16x16x32_bf16 v[76:79], v[178:181], v[202:205], v[76:79]
	v_mfma_f32_16x16x32_bf16 v[68:71], v[170:173], v[210:213], v[68:71]
	v_mfma_f32_16x16x32_bf16 v[64:67], v[178:181], v[210:213], v[64:67]
	s_setprio 0
	s_barrier
; #define PG8_STAGE(bufoff, gbase, voff) do { _Pragma("unroll") for (int _i = 0; _i < 2; ++_i) \
;         __builtin_amdgcn_global_load_lds((const unsigned*)((const char*)(gbase) + (voff)[_i]), (PG8_LAS unsigned*)(lds + (bufoff) + ldsw + _i * 8192), 16, 0, 0); } while (0)
; #define PG8_LDA(dst, b, h) do { _Pragma("unroll") for (int m = 0; m < 4; ++m) _Pragma("unroll") for (int k = 0; k < 2; ++k) dst[m][k] = *(const PG8_LAS bf16x8*)(lds + PG8_SA(b, h) + aoff + m * 2048 + k * 1024); } while (0)
; #define PG8_MMA(ai, bj, At, Bt) do { __builtin_amdgcn_s_setprio(1); _Pragma("unroll") for (int m = 0; m < 4; ++m) _Pragma("unroll") for (int n = 0; n < 2; ++n) _Pragma("unroll") for (int k = 0; k < 2; ++k) \
;         acc[ai][bj][m][n] = __builtin_amdgcn_mfma_f32_16x16x32_bf16(Bt[n][k], At[m][k], acc[ai][bj][m][n], 0, 0, 0); __builtin_amdgcn_s_setprio(0); } while (0)
; #define PG8_WAIT_V(n) asm volatile("s_waitcnt vmcnt(" #n ")" ::: "memory")
; #define PG8_WAIT_L(n) asm volatile("s_waitcnt lgkmcnt(" #n ")" ::: "memory")
; #define PG8_BAR __builtin_amdgcn_s_barrier()
; #define PG8_SCHED __builtin_amdgcn_sched_barrier(0)
; template <class Epi, class Sched, bool ALIGN_EPI = false, bool SP2 = false>
; __device__ __forceinline__ void gemm_phase(PG8_LAS unsigned char* lds, const Gemm g, const Sched& S, const Epi& E) {
;     ...
;         for (int t = 0; t < nt; t += 2) {
;             const bool last = (t == nt - 2);
;     ...
;             PG8_LDA(At, 1, 1); PG8_STAGE(PG8_SB(1, 0), b3, voffB); PG8_STAGE(PG8_SB(1, 1), b3 + hstepB, voffB); PG8_STAGE(PG8_SA(1, 0), a3, voffA);
;             PG8_WAIT_V(8); PG8_WAIT_L(0); PG8_BAR; PG8_MMA(1, 0, At, B0); PG8_MMA(1, 1, At, B1); PG8_BAR; PG8_SCHED;
	s_add_i32 s18, s50, s33
	v_lshl_add_u64 v[214:215], v[214:215], 0, s[12:13]
	s_mov_b32 m0, s18
	ds_read_b128 v[182:185], v157 offset:49152
	ds_read_b128 v[186:189], v157 offset:50176
	ds_read_b128 v[190:193], v157 offset:51200
	ds_read_b128 v[194:197], v157 offset:52224
	ds_read_b128 v[198:201], v157 offset:53248
	ds_read_b128 v[202:205], v157 offset:54272
	ds_read_b128 v[206:209], v157 offset:55296
	ds_read_b128 v[210:213], v157 offset:56320
	global_load_lds_dwordx4 v[214:215], off
	s_add_i32 m0, s18, 0x2000
	s_add_u32 s18, s22, 0xb0080
	v_lshl_add_u64 v[214:215], v[216:217], 0, s[12:13]
	s_addc_u32 s19, s23, 0
	s_add_i32 s22, s51, s33
	global_load_lds_dwordx4 v[214:215], off
	v_lshl_add_u64 v[214:215], s[18:19], 0, v[130:131]
	s_mov_b32 m0, s22
	s_nop 0
	global_load_lds_dwordx4 v[214:215], off
	v_lshl_add_u64 v[214:215], s[18:19], 0, v[134:135]
	s_add_i32 m0, s22, 0x2000
	s_nop 0
	global_load_lds_dwordx4 v[214:215], off
	v_lshl_add_u64 v[214:215], v[218:219], 0, s[12:13]
	s_mov_b32 m0, s39
	s_nop 0
	global_load_lds_dwordx4 v[214:215], off
	v_lshl_add_u64 v[214:215], v[220:221], 0, s[12:13]
	s_mov_b32 m0, s40
	s_nop 0
	global_load_lds_dwordx4 v[214:215], off
	s_waitcnt vmcnt(8)
	s_waitcnt lgkmcnt(0)
	s_barrier
	s_setprio 1
	s_waitcnt lgkmcnt(0)
	v_mfma_f32_16x16x32_bf16 v[60:63], v[144:147], v[182:185], v[60:63]
	v_mfma_f32_16x16x32_bf16 v[56:59], v[158:161], v[182:185], v[56:59]
	v_mfma_f32_16x16x32_bf16 v[48:51], v[144:147], v[190:193], v[48:51]
	v_mfma_f32_16x16x32_bf16 v[40:43], v[158:161], v[190:193], v[40:43]
	v_mfma_f32_16x16x32_bf16 v[28:31], v[144:147], v[198:201], v[28:31]
	v_mfma_f32_16x16x32_bf16 v[24:27], v[158:161], v[198:201], v[24:27]
	v_mfma_f32_16x16x32_bf16 v[20:23], v[144:147], v[206:209], v[20:23]
	v_mfma_f32_16x16x32_bf16 v[12:15], v[158:161], v[206:209], v[12:15]
	v_mfma_f32_16x16x32_bf16 v[60:63], v[148:151], v[186:189], v[60:63]
	v_mfma_f32_16x16x32_bf16 v[56:59], v[162:165], v[186:189], v[56:59]
	v_mfma_f32_16x16x32_bf16 v[48:51], v[148:151], v[194:197], v[48:51]
	v_mfma_f32_16x16x32_bf16 v[40:43], v[162:165], v[194:197], v[40:43]
	v_mfma_f32_16x16x32_bf16 v[28:31], v[148:151], v[202:205], v[28:31]
	v_mfma_f32_16x16x32_bf16 v[24:27], v[162:165], v[202:205], v[24:27]
	v_mfma_f32_16x16x32_bf16 v[20:23], v[148:151], v[210:213], v[20:23]
	v_mfma_f32_16x16x32_bf16 v[12:15], v[162:165], v[210:213], v[12:15]
	s_setprio 0
	s_setprio 1
	v_mfma_f32_16x16x32_bf16 v[52:55], v[166:169], v[182:185], v[52:55]
	v_mfma_f32_16x16x32_bf16 v[44:47], v[174:177], v[182:185], v[44:47]
	v_mfma_f32_16x16x32_bf16 v[36:39], v[166:169], v[190:193], v[36:39]
	v_mfma_f32_16x16x32_bf16 v[32:35], v[174:177], v[190:193], v[32:35]
	v_mfma_f32_16x16x32_bf16 v[16:19], v[166:169], v[198:201], v[16:19]
	v_mfma_f32_16x16x32_bf16 v[8:11], v[174:177], v[198:201], v[8:11]
	v_mfma_f32_16x16x32_bf16 v[4:7], v[166:169], v[206:209], v[4:7]
	v_mfma_f32_16x16x32_bf16 v[0:3], v[174:177], v[206:209], v[0:3]
	v_mfma_f32_16x16x32_bf16 v[52:55], v[170:173], v[186:189], v[52:55]
	v_mfma_f32_16x16x32_bf16 v[44:47], v[178:181], v[186:189], v[44:47]
	v_mfma_f32_16x16x32_bf16 v[36:39], v[170:173], v[194:197], v[36:39]
	v_mfma_f32_16x16x32_bf16 v[32:35], v[178:181], v[194:197], v[32:35]
	v_mfma_f32_16x16x32_bf16 v[16:19], v[170:173], v[202:205], v[16:19]
	v_mfma_f32_16x16x32_bf16 v[8:11], v[178:181], v[202:205], v[8:11]
	v_mfma_f32_16x16x32_bf16 v[4:7], v[170:173], v[210:213], v[4:7]
	v_mfma_f32_16x16x32_bf16 v[0:3], v[178:181], v[210:213], v[0:3]
	s_setprio 0
	s_barrier
	s_add_i32 s49, s49, 2
	s_add_u32 s47, s47, 0x100
	s_addc_u32 s48, s48, 0
	s_cmp_gt_u32 s49, 41
	s_mov_b64 s[18:19], s[20:21]
	s_cbranch_scc1 .Lpeel_exit_8
